# FFT unit loop: first half-pass input rows requested one unit ahead (after the middle pass frees v200-215), copied at the unit top; first unit's batch requested before the loop
# speedup vs baseline: 1.0073x; 1.0023x over previous
.LBB0_355:
	s_cmp_lt_i32 s60, 4
	s_cselect_b64 s[0:1], -1, 0
	s_cmp_gt_i32 s61, 3
	s_cselect_b64 s[2:3], -1, 0
	s_and_b64 s[0:1], s[0:1], s[2:3]
	s_andn2_b64 vcc, exec, s[0:1]
	s_cbranch_vccnz .LBB0_419
	s_cmpk_gt_i32 s72, 0x3ff
	s_cbranch_scc1 .LBB0_367
	v_readlane_b32 s2, v247, 0
	v_readlane_b32 s3, v247, 1
	s_add_u32 s54, s2, 0x1c000000
	s_addc_u32 s55, s3, 0
	s_add_u32 s56, s2, 0x14000000
	s_addc_u32 s57, s3, 0
	s_ashr_i32 s73, s72, 31
	s_lshl_b64 s[0:1], s[72:73], 17
	s_add_u32 s0, s2, s0
	s_addc_u32 s1, s3, s1
	v_lshlrev_b32_e32 v0, 3, v170
	v_mov_b32_e32 v1, 0
	v_lshl_add_u64 v[64:65], s[0:1], 0, v[0:1]
	s_mov_b64 s[0:1], 0x8000000
	v_lshl_add_u64 v[2:3], v[64:65], 0, s[0:1]
	s_mov_b64 s[0:1], 0x8001000
	v_lshl_add_u64 v[4:5], v[64:65], 0, s[0:1]
	s_mov_b64 s[0:1], 0x8002000
	v_lshl_add_u64 v[6:7], v[64:65], 0, s[0:1]
	s_mov_b64 s[0:1], 0x8003000
	v_lshl_add_u64 v[8:9], v[64:65], 0, s[0:1]
	s_mov_b64 s[0:1], 0x8004000
	v_lshl_add_u64 v[10:11], v[64:65], 0, s[0:1]
	s_mov_b64 s[0:1], 0x8005000
	v_lshl_add_u64 v[12:13], v[64:65], 0, s[0:1]
	s_mov_b64 s[0:1], 0x8006000
	v_lshl_add_u64 v[14:15], v[64:65], 0, s[0:1]
	s_mov_b64 s[0:1], 0x8007000
	v_lshl_add_u64 v[16:17], v[64:65], 0, s[0:1]
	s_mov_b64 s[0:1], 0x8008000
	v_lshl_add_u64 v[18:19], v[64:65], 0, s[0:1]
	s_mov_b64 s[0:1], 0x8009000
	v_lshl_add_u64 v[20:21], v[64:65], 0, s[0:1]
	s_mov_b64 s[0:1], 0x800a000
	v_lshl_add_u64 v[22:23], v[64:65], 0, s[0:1]
	s_mov_b64 s[0:1], 0x800b000
	v_lshl_add_u64 v[24:25], v[64:65], 0, s[0:1]
	s_mov_b64 s[0:1], 0x800c000
	v_lshl_add_u64 v[26:27], v[64:65], 0, s[0:1]
	s_mov_b64 s[0:1], 0x800d000
	v_lshl_add_u64 v[28:29], v[64:65], 0, s[0:1]
	s_mov_b64 s[0:1], 0x800e000
	v_lshl_add_u64 v[30:31], v[64:65], 0, s[0:1]
	s_mov_b64 s[0:1], 0x800f000
	v_lshl_add_u64 v[32:33], v[64:65], 0, s[0:1]
	s_mov_b64 s[0:1], 0x8010000
	v_lshl_add_u64 v[34:35], v[64:65], 0, s[0:1]
	s_mov_b64 s[0:1], 0x8011000
	v_lshl_add_u64 v[36:37], v[64:65], 0, s[0:1]
	s_mov_b64 s[0:1], 0x8012000
	v_lshl_add_u64 v[38:39], v[64:65], 0, s[0:1]
	s_mov_b64 s[0:1], 0x8013000
	v_lshl_add_u64 v[40:41], v[64:65], 0, s[0:1]
	s_mov_b64 s[0:1], 0x8014000
	v_lshl_add_u64 v[42:43], v[64:65], 0, s[0:1]
	s_mov_b64 s[0:1], 0x8015000
	v_lshl_add_u64 v[44:45], v[64:65], 0, s[0:1]
	s_mov_b64 s[0:1], 0x8016000
	v_lshl_add_u64 v[46:47], v[64:65], 0, s[0:1]
	s_mov_b64 s[0:1], 0x8017000
	v_lshl_add_u64 v[48:49], v[64:65], 0, s[0:1]
	s_mov_b64 s[0:1], 0x8018000
	v_lshl_add_u64 v[50:51], v[64:65], 0, s[0:1]
	s_mov_b64 s[0:1], 0x8019000
	v_lshl_add_u64 v[52:53], v[64:65], 0, s[0:1]
	s_mov_b64 s[0:1], 0x801a000
	v_lshl_add_u64 v[54:55], v[64:65], 0, s[0:1]
	s_mov_b64 s[0:1], 0x801b000
	v_lshl_add_u64 v[56:57], v[64:65], 0, s[0:1]
	s_mov_b64 s[0:1], 0x801c000
	v_lshl_add_u64 v[58:59], v[64:65], 0, s[0:1]
	s_mov_b64 s[0:1], 0x801d000
	v_lshl_add_u64 v[60:61], v[64:65], 0, s[0:1]
	s_mov_b64 s[0:1], 0x801e000
	v_mul_u32_u24_e32 v0, 0x108, v170
	v_lshl_add_u64 v[62:63], v[64:65], 0, s[0:1]
	s_mov_b64 s[0:1], 0x801f000
	s_mov_b32 s6, 0x3f6c835e
	s_mov_b32 s10, 0x3f3504f3
	s_mov_b32 s14, 0x3ec3ef15
	s_mov_b32 s18, 0xbe47c5c2
	s_mov_b32 s22, 0xbf0e39da
	v_lshl_add_u64 v[64:65], v[64:65], 0, s[0:1]
	s_movk_i32 s58, 0x1000
	s_mov_b32 s3, 0
	s_movk_i32 s59, 0x2000
	s_movk_i32 s60, 0x3000
	s_mov_b32 s4, 0xbec3ef15
	s_mov_b32 s8, 0xbf3504f3
	s_mov_b32 s12, 0xbf6c835e
	s_mov_b32 s16, 0xbf3504f3
	s_mov_b32 s17, s10
	s_mov_b32 s2, 0x38800000
	s_mov_b32 s19, 0x3e47c5c2
	s_mov_b32 s20, 0x3f7b14be
	s_mov_b32 s23, 0x3f0e39da
	s_mov_b32 s24, 0x3f54db31
	s_mov_b32 s26, 0xbf54db31
	s_mov_b32 s34, 0xbf7b14be
	s_mov_b32 s36, 0xbec3ef15
	s_mov_b32 s37, s14
	s_mov_b32 s38, 0xbf6c835e
	s_mov_b32 s39, s6
	v_add_u32_e32 v104, 0, v0
	s_mov_b32 s40, s72
	s_mov_b32 s66, s40
	s_ashr_i32 s67, s66, 31
	s_lshl_b64 s[64:65], s[66:67], 16
	s_add_u32 s64, s54, s64
	s_addc_u32 s65, s55, s65
	v_lshlrev_b32_e32 v198, 2, v170
	global_load_dword v200, v198, s[64:65]
	v_add_u32_e32 v199, 0x1000, v198
	global_load_dword v201, v199, s[64:65]
	v_add_u32_e32 v199, 0x2000, v198
	global_load_dword v204, v199, s[64:65]
	v_add_u32_e32 v199, 0x3000, v198
	global_load_dword v205, v199, s[64:65]
	v_add_u32_e32 v199, 0x4000, v198
	global_load_dword v206, v199, s[64:65]
	v_add_u32_e32 v199, 0x5000, v198
	global_load_dword v207, v199, s[64:65]
	v_add_u32_e32 v199, 0x6000, v198
	global_load_dword v208, v199, s[64:65]
	v_add_u32_e32 v199, 0x7000, v198
	global_load_dword v209, v199, s[64:65]
	v_add_u32_e32 v199, 0x8000, v198
	global_load_dword v210, v199, s[64:65]
	v_add_u32_e32 v199, 0x9000, v198
	global_load_dword v211, v199, s[64:65]
	v_add_u32_e32 v199, 0xa000, v198
	global_load_dword v212, v199, s[64:65]
	v_add_u32_e32 v199, 0xb000, v198
	global_load_dword v213, v199, s[64:65]
	v_add_u32_e32 v199, 0xc000, v198
	global_load_dword v214, v199, s[64:65]
	v_add_u32_e32 v199, 0xd000, v198
	global_load_dword v215, v199, s[64:65]
	v_add_u32_e32 v199, 0xe000, v198
	global_load_dword v202, v199, s[64:65]
	v_add_u32_e32 v199, 0xf000, v198
	global_load_dword v203, v199, s[64:65]
	s_waitcnt vmcnt(0)

.LBB0_359:
	s_cmp_lg_u32 s5, 0
	s_cbranch_scc1 .Lmy_fft_k1
	v_add_u32_e32 v0, s5, v170
	v_cndmask_b32_e64 v66, 0, 1, s[46:47]
	v_cmp_ne_u32_e64 s[0:1], 1, v66
	v_mov_b32_e32 v71, v1
	v_mov_b32_e32 v72, v1
	v_mov_b32_e32 v77, v1
	v_mov_b32_e32 v84, v1
	v_mov_b32_e32 v67, v1
	v_mov_b32_e32 v108, v200
	v_mov_b32_e32 v109, v201
	v_mov_b32_e32 v112, v204
	v_mov_b32_e32 v113, v205
	v_mov_b32_e32 v114, v206
	v_mov_b32_e32 v115, v207
	v_mov_b32_e32 v116, v208
	v_mov_b32_e32 v117, v209
	v_mov_b32_e32 v118, v210
	v_mov_b32_e32 v119, v211
	v_mov_b32_e32 v120, v212
	v_mov_b32_e32 v121, v213
	v_mov_b32_e32 v122, v214
	v_mov_b32_e32 v123, v215
	v_mov_b32_e32 v110, v202
	v_mov_b32_e32 v111, v203
	v_mov_b32_e32 v219, 0
	v_add_u32_e32 v218, 0x200, v170
	v_lshl_add_u64 v[198:199], v[218:219], 2, s[44:45]
	v_add_co_u32_e32 v202, vcc, 0x1000, v198
	global_load_dword v200, v[198:199], off
	s_nop 0
	v_addc_co_u32_e32 v203, vcc, 0, v199, vcc
	v_add_co_u32_e32 v204, vcc, 0x2000, v198
	global_load_dword v201, v[202:203], off
	s_nop 0
	v_addc_co_u32_e32 v205, vcc, 0, v199, vcc
	v_add_co_u32_e32 v202, vcc, 0x3000, v198
	s_nop 0
	v_addc_co_u32_e32 v203, vcc, 0, v199, vcc
	v_add_co_u32_e32 v206, vcc, 0x4000, v198
	global_load_dword v204, v[204:205], off
	s_nop 0
	global_load_dword v205, v[202:203], off
	v_addc_co_u32_e32 v207, vcc, 0, v199, vcc
	v_add_co_u32_e32 v202, vcc, 0x5000, v198
	s_nop 0
	v_addc_co_u32_e32 v203, vcc, 0, v199, vcc
	v_add_co_u32_e32 v208, vcc, 0x6000, v198
	global_load_dword v206, v[206:207], off
	s_nop 0
	global_load_dword v207, v[202:203], off
	v_addc_co_u32_e32 v209, vcc, 0, v199, vcc
	v_add_co_u32_e32 v202, vcc, 0x7000, v198
	s_nop 0
	v_addc_co_u32_e32 v203, vcc, 0, v199, vcc
	v_add_co_u32_e32 v210, vcc, 0x8000, v198
	global_load_dword v208, v[208:209], off
	s_nop 0
	global_load_dword v209, v[202:203], off
	v_addc_co_u32_e32 v211, vcc, 0, v199, vcc
	v_add_co_u32_e32 v202, vcc, 0x9000, v198
	s_nop 0
	v_addc_co_u32_e32 v203, vcc, 0, v199, vcc
	v_add_co_u32_e32 v212, vcc, 0xa000, v198
	global_load_dword v210, v[210:211], off
	s_nop 0
	global_load_dword v211, v[202:203], off
	v_addc_co_u32_e32 v213, vcc, 0, v199, vcc
	v_add_co_u32_e32 v202, vcc, 0xb000, v198
	s_nop 0
	v_addc_co_u32_e32 v203, vcc, 0, v199, vcc
	v_add_co_u32_e32 v214, vcc, 0xc000, v198
	global_load_dword v212, v[212:213], off
	s_nop 0
	global_load_dword v213, v[202:203], off
	v_addc_co_u32_e32 v215, vcc, 0, v199, vcc
	v_add_co_u32_e32 v202, vcc, 0xd000, v198
	s_nop 0
	v_addc_co_u32_e32 v203, vcc, 0, v199, vcc
	v_add_co_u32_e32 v216, vcc, 0xe000, v198
	global_load_dword v214, v[214:215], off
	s_nop 0
	global_load_dword v215, v[202:203], off
	v_addc_co_u32_e32 v217, vcc, 0, v199, vcc
	v_add_co_u32_e32 v198, vcc, 0xf000, v198
	s_nop 0
	v_addc_co_u32_e32 v199, vcc, 0, v199, vcc
	global_load_dword v202, v[216:217], off
	global_load_dword v203, v[198:199], off
	s_branch .Lmy_fft_kj

.Lmy_fft_h1:
	s_waitcnt vmcnt(0)
	v_mov_b32_e32 v105, v197
	v_mov_b32_e32 v127, v198
	v_mov_b32_e32 v128, v199
	v_mov_b32_e32 v130, v200
	v_mov_b32_e32 v131, v201
	v_mov_b32_e32 v132, v202
	v_mov_b32_e32 v133, v203
	v_mov_b32_e32 v134, v204
	v_mov_b32_e32 v136, v205
	v_mov_b32_e32 v135, v206
	v_mov_b32_e32 v137, v207
	v_mov_b32_e32 v138, v208
	v_mov_b32_e32 v139, v209
	v_mov_b32_e32 v140, v210
	v_mov_b32_e32 v141, v211
	v_mov_b32_e32 v142, v212
	s_add_i32 s66, s40, s30
	s_cmpk_gt_i32 s66, 0x3ff
	s_cbranch_scc1 .Lmy_fft_xskip
	s_ashr_i32 s67, s66, 31
	s_lshl_b64 s[64:65], s[66:67], 16
	s_add_u32 s64, s54, s64
	s_addc_u32 s65, s55, s65
	v_lshlrev_b32_e32 v198, 2, v170
	global_load_dword v200, v198, s[64:65]
	v_add_u32_e32 v199, 0x1000, v198
	global_load_dword v201, v199, s[64:65]
	v_add_u32_e32 v199, 0x2000, v198
	global_load_dword v204, v199, s[64:65]
	v_add_u32_e32 v199, 0x3000, v198
	global_load_dword v205, v199, s[64:65]
	v_add_u32_e32 v199, 0x4000, v198
	global_load_dword v206, v199, s[64:65]
	v_add_u32_e32 v199, 0x5000, v198
	global_load_dword v207, v199, s[64:65]
	v_add_u32_e32 v199, 0x6000, v198
	global_load_dword v208, v199, s[64:65]
	v_add_u32_e32 v199, 0x7000, v198
	global_load_dword v209, v199, s[64:65]
	v_add_u32_e32 v199, 0x8000, v198
	global_load_dword v210, v199, s[64:65]
	v_add_u32_e32 v199, 0x9000, v198
	global_load_dword v211, v199, s[64:65]
	v_add_u32_e32 v199, 0xa000, v198
	global_load_dword v212, v199, s[64:65]
	v_add_u32_e32 v199, 0xb000, v198
	global_load_dword v213, v199, s[64:65]
	v_add_u32_e32 v199, 0xc000, v198
	global_load_dword v214, v199, s[64:65]
	v_add_u32_e32 v199, 0xd000, v198
	global_load_dword v215, v199, s[64:65]
	v_add_u32_e32 v199, 0xe000, v198
	global_load_dword v202, v199, s[64:65]
	v_add_u32_e32 v199, 0xf000, v198
	global_load_dword v203, v199, s[64:65]
.Lmy_fft_xskip:
.Lmy_fft_hj:
	v_mov_b32 v66, 0
	s_movk_i32 s5, 0x200
	v_add_u32_e32 v0, v66, v0
	v_cvt_f32_i32_e32 v68, v0
	v_ashrrev_i32_e32 v66, 5, v0
	v_lshlrev_b32_e32 v67, 3, v0
	v_lshlrev_b32_e32 v66, 3, v66
	v_add3_u32 v171, 0, v66, v67
	v_add_u32_e32 v216, 0x10800, v171
	v_mul_f32_e32 v0, 0x38800000, v68
	v_sin_f32_e32 v67, v0
	v_cos_f32_e32 v66, v0
	v_xor_b32_e32 v68, 0x80000000, v67
	v_mov_b32_e32 v69, v67
	v_pk_mul_f32 v[70:71], v[68:69], v[66:67] op_sel:[0,1] op_sel_hi:[1,0]
	v_pk_fma_f32 v[70:71], v[66:67], v[66:67], v[70:71] op_sel_hi:[1,0,1]
	v_pk_mul_f32 v[74:75], v[68:69], v[70:71] op_sel:[0,1] op_sel_hi:[1,0]
	v_pk_fma_f32 v[74:75], v[70:71], v[66:67], v[74:75] op_sel_hi:[1,0,1]
	v_pk_mul_f32 v[78:79], v[68:69], v[74:75] op_sel:[0,1] op_sel_hi:[1,0]
	v_pk_fma_f32 v[78:79], v[74:75], v[66:67], v[78:79] op_sel_hi:[1,0,1]
	v_pk_mul_f32 v[82:83], v[68:69], v[78:79] op_sel:[0,1] op_sel_hi:[1,0]
	v_pk_fma_f32 v[82:83], v[78:79], v[66:67], v[82:83] op_sel_hi:[1,0,1]
	v_pk_mul_f32 v[86:87], v[68:69], v[82:83] op_sel:[0,1] op_sel_hi:[1,0]
	s_waitcnt vmcnt(31)
	v_lshlrev_b32_e32 v126, 16, v105
	v_pk_fma_f32 v[86:87], v[82:83], v[66:67], v[86:87] op_sel_hi:[1,0,1]
	s_waitcnt vmcnt(30)
	v_lshlrev_b32_e32 v127, 16, v127
	v_pk_mul_f32 v[90:91], v[68:69], v[86:87] op_sel:[0,1] op_sel_hi:[1,0]
	s_waitcnt vmcnt(29)
	v_lshlrev_b32_e32 v129, 16, v128
	v_pk_fma_f32 v[90:91], v[86:87], v[66:67], v[90:91] op_sel_hi:[1,0,1]
	s_waitcnt vmcnt(24)
	v_lshlrev_b32_e32 v128, 16, v134
	v_pk_mul_f32 v[94:95], v[68:69], v[90:91] op_sel:[0,1] op_sel_hi:[1,0]
	v_lshlrev_b32_e32 v130, 16, v130
	v_pk_fma_f32 v[94:95], v[90:91], v[66:67], v[94:95] op_sel_hi:[1,0,1]
	v_lshlrev_b32_e32 v131, 16, v131
	v_pk_mul_f32 v[98:99], v[68:69], v[94:95] op_sel:[0,1] op_sel_hi:[1,0]
	v_lshlrev_b32_e32 v132, 16, v132
	v_pk_fma_f32 v[98:99], v[94:95], v[66:67], v[98:99] op_sel_hi:[1,0,1]
	v_lshlrev_b32_e32 v133, 16, v133
	v_pk_mul_f32 v[102:103], v[68:69], v[98:99] op_sel:[0,1] op_sel_hi:[1,0]
	s_waitcnt vmcnt(22)
	v_lshlrev_b32_e32 v135, 16, v135
	v_pk_fma_f32 v[102:103], v[98:99], v[66:67], v[102:103] op_sel_hi:[1,0,1]
	v_lshlrev_b32_e32 v134, 16, v136
	v_pk_mul_f32 v[108:109], v[68:69], v[102:103] op_sel:[0,1] op_sel_hi:[1,0]
	s_waitcnt vmcnt(21)
	v_lshlrev_b32_e32 v136, 16, v137
	v_pk_fma_f32 v[108:109], v[102:103], v[66:67], v[108:109] op_sel_hi:[1,0,1]
	s_waitcnt vmcnt(20)
	v_lshlrev_b32_e32 v137, 16, v138
	v_pk_mul_f32 v[112:113], v[68:69], v[108:109] op_sel:[0,1] op_sel_hi:[1,0]
	s_waitcnt vmcnt(19)
	v_lshlrev_b32_e32 v138, 16, v139
	s_waitcnt vmcnt(18)
	v_lshlrev_b32_e32 v139, 16, v140
	s_waitcnt vmcnt(17)
	v_lshlrev_b32_e32 v140, 16, v141
	s_waitcnt vmcnt(16)
	v_lshlrev_b32_e32 v141, 16, v142
	v_pk_fma_f32 v[112:113], v[108:109], v[66:67], v[112:113] op_sel_hi:[1,0,1]
	v_pk_add_f32 v[142:143], v[126:127], 0 op_sel_hi:[1,0]
	v_pk_add_f32 v[144:145], v[128:129], 0 op_sel_hi:[1,0]
	v_pk_mul_f32 v[146:147], v[128:129], s[36:37]
	v_pk_add_f32 v[148:149], v[130:131], 0 op_sel_hi:[1,0]
	v_pk_mul_f32 v[150:151], v[130:131], s[16:17]
	v_pk_add_f32 v[152:153], v[132:133], 0 op_sel_hi:[1,0]
	v_pk_mul_f32 v[154:155], v[132:133], s[38:39]
	v_pk_add_f32 v[156:157], v[134:135], 0 op_sel_hi:[1,0]
	v_xor_b32_e32 v159, 0x80000000, v134
	v_mov_b32_e32 v158, v135
	v_pk_add_f32 v[134:135], v[136:137], 0 op_sel_hi:[1,0]
	v_pk_mul_f32 v[160:161], v[136:137], s[38:39]
	v_pk_add_f32 v[162:163], v[138:139], 0 op_sel_hi:[1,0]
	v_pk_mul_f32 v[164:165], v[138:139], s[16:17]
	v_pk_add_f32 v[166:167], v[140:141], 0 op_sel_hi:[1,0]
	v_pk_mul_f32 v[168:169], v[140:141], s[36:37]
	v_pk_mul_f32 v[116:117], v[68:69], v[112:113] op_sel:[0,1] op_sel_hi:[1,0]
	v_pk_fma_f32 v[128:129], v[128:129], s[6:7], v[146:147] op_sel:[0,0,1] op_sel_hi:[1,0,0]
	v_pk_fma_f32 v[130:131], v[130:131], s[10:11], v[150:151] op_sel:[0,0,1] op_sel_hi:[1,0,0]
	v_pk_fma_f32 v[132:133], v[132:133], s[14:15], v[154:155] op_sel:[0,0,1] op_sel_hi:[1,0,0]
	v_pk_fma_f32 v[136:137], v[136:137], s[4:5], v[160:161] op_sel:[0,0,1] op_sel_hi:[1,0,0]
	v_pk_fma_f32 v[138:139], v[138:139], s[8:9], v[164:165] op_sel:[0,0,1] op_sel_hi:[1,0,0]
	v_pk_fma_f32 v[140:141], v[140:141], s[12:13], v[168:169] op_sel:[0,0,1] op_sel_hi:[1,0,0]
	v_pk_add_f32 v[146:147], v[142:143], v[156:157]
	v_pk_add_f32 v[150:151], v[144:145], v[134:135]
	v_pk_add_f32 v[134:135], v[144:145], v[134:135] neg_lo:[0,1] neg_hi:[0,1]
	v_pk_add_f32 v[144:145], v[148:149], v[162:163]
	v_pk_add_f32 v[160:161], v[148:149], v[162:163] op_sel:[1,1] op_sel_hi:[0,0] neg_lo:[0,1] neg_hi:[1,0]
	v_pk_add_f32 v[154:155], v[152:153], v[166:167]
	v_pk_add_f32 v[152:153], v[152:153], v[166:167] neg_lo:[0,1] neg_hi:[0,1]
	v_pk_fma_f32 v[116:117], v[112:113], v[66:67], v[116:117] op_sel_hi:[1,0,1]
	v_pk_add_f32 v[142:143], v[142:143], v[156:157] neg_lo:[0,1] neg_hi:[0,1]
	v_pk_add_f32 v[156:157], v[158:159], v[126:127]
	v_pk_add_f32 v[126:127], v[126:127], v[158:159] neg_lo:[0,1] neg_hi:[0,1]
	v_pk_mul_f32 v[158:159], v[134:135], s[16:17]
	v_pk_mul_f32 v[148:149], v[152:153], s[16:17]
	v_pk_add_f32 v[162:163], v[128:129], v[136:137]
	v_pk_add_f32 v[128:129], v[128:129], v[136:137] neg_lo:[0,1] neg_hi:[0,1]
	v_pk_add_f32 v[136:137], v[130:131], v[138:139]
	v_pk_add_f32 v[130:131], v[130:131], v[138:139] neg_lo:[0,1] neg_hi:[0,1]
	v_pk_add_f32 v[138:139], v[132:133], v[140:141]
	v_pk_add_f32 v[132:133], v[132:133], v[140:141] neg_lo:[0,1] neg_hi:[0,1]
	v_pk_add_f32 v[140:141], v[146:147], v[144:145]
	v_pk_add_f32 v[144:145], v[146:147], v[144:145] neg_lo:[0,1] neg_hi:[0,1]
	v_pk_add_f32 v[146:147], v[150:151], v[154:155]
	v_pk_add_f32 v[150:151], v[150:151], v[154:155] neg_lo:[0,1] neg_hi:[0,1]
	v_pk_mul_f32 v[120:121], v[68:69], v[116:117] op_sel:[0,1] op_sel_hi:[1,0]
	v_pk_fma_f32 v[134:135], v[134:135], s[10:11], v[158:159] op_sel:[0,0,1] op_sel_hi:[1,0,0]
	v_pk_fma_f32 v[148:149], v[152:153], s[8:9], v[148:149] op_sel:[0,0,1] op_sel_hi:[1,0,0]
	v_pk_mul_f32 v[152:153], v[128:129], s[16:17]
	v_xor_b32_e32 v155, 0x80000000, v130
	v_mov_b32_e32 v154, v131
	v_pk_mul_f32 v[130:131], v[132:133], s[16:17]
	v_xor_b32_e32 v159, 0x80000000, v150
	v_mov_b32_e32 v158, v151
	v_pk_add_f32 v[150:151], v[142:143], v[160:161]
	v_pk_add_f32 v[142:143], v[142:143], v[160:161] neg_lo:[0,1] neg_hi:[0,1]
	v_pk_add_f32 v[160:161], v[156:157], v[136:137]
	v_pk_add_f32 v[136:137], v[156:157], v[136:137] neg_lo:[0,1] neg_hi:[0,1]
	v_pk_add_f32 v[156:157], v[162:163], v[138:139]
	v_pk_add_f32 v[138:139], v[162:163], v[138:139] neg_lo:[0,1] neg_hi:[0,1]
	v_mov_b32_e32 v0, v67
	v_pk_fma_f32 v[120:121], v[116:117], v[66:67], v[120:121] op_sel_hi:[1,0,1]
	v_pk_add_f32 v[162:163], v[140:141], v[146:147]
	v_pk_add_f32 v[140:141], v[140:141], v[146:147] neg_lo:[0,1] neg_hi:[0,1]
	v_pk_fma_f32 v[128:129], v[128:129], s[10:11], v[152:153] op_sel:[0,0,1] op_sel_hi:[1,0,0]
	v_pk_fma_f32 v[130:131], v[132:133], s[8:9], v[130:131] op_sel:[0,0,1] op_sel_hi:[1,0,0]
	v_pk_add_f32 v[132:133], v[134:135], v[148:149]
	v_pk_add_f32 v[134:135], v[134:135], v[148:149] neg_lo:[0,1] neg_hi:[0,1]
	v_xor_b32_e32 v147, 0x80000000, v138
	v_mov_b32_e32 v146, v139
	v_pk_add_f32 v[152:153], v[160:161], v[156:157]
	v_pk_mul_f32 v[68:69], v[68:69], v[120:121] op_sel:[0,1] op_sel_hi:[1,0]
	v_pk_add_f32 v[138:139], v[126:127], v[154:155]
	v_pk_add_f32 v[126:127], v[126:127], v[154:155] neg_lo:[0,1] neg_hi:[0,1]
	v_pk_add_f32 v[148:149], v[144:145], v[158:159]
	v_pk_add_f32 v[144:145], v[144:145], v[158:159] neg_lo:[0,1] neg_hi:[0,1]
	v_pk_add_f32 v[154:155], v[160:161], v[156:157] neg_lo:[0,1] neg_hi:[0,1]
	v_pk_mul_f32 v[96:97], v[140:141], v[94:95] op_sel:[1,1] op_sel_hi:[0,1] neg_hi:[0,1]
	v_xor_b32_e32 v157, 0x80000000, v134
	v_mov_b32_e32 v156, v135
	v_pk_add_f32 v[134:135], v[128:129], v[130:131]
	v_pk_add_f32 v[128:129], v[128:129], v[130:131] neg_lo:[0,1] neg_hi:[0,1]
	v_pk_add_f32 v[130:131], v[150:151], v[132:133]
	v_pk_add_f32 v[132:133], v[150:151], v[132:133] neg_lo:[0,1] neg_hi:[0,1]
	v_pk_add_f32 v[150:151], v[136:137], v[146:147]
	v_pk_add_f32 v[136:137], v[136:137], v[146:147] neg_lo:[0,1] neg_hi:[0,1]
	v_pk_mul_f32 v[146:147], v[0:1], v[152:153] op_sel:[0,1] op_sel_hi:[0,0] neg_hi:[1,0]
	v_pk_add_f32 v[92:93], v[90:91], 0 neg_lo:[1,1] neg_hi:[1,1]
	v_pk_fma_f32 v[68:69], v[120:121], v[66:67], v[68:69] op_sel_hi:[1,0,1]
	v_pk_mul_f32 v[80:81], v[148:149], v[78:79] op_sel:[1,1] op_sel_hi:[0,1] neg_hi:[0,1]
	v_pk_fma_f32 v[94:95], v[140:141], v[94:95], v[96:97] op_sel_hi:[1,0,1]
	v_pk_mul_f32 v[96:97], v[154:155], v[98:99] op_sel:[1,1] op_sel_hi:[0,1] neg_hi:[0,1]
	v_pk_mul_f32 v[100:101], v[144:145], v[112:113] op_sel:[1,1] op_sel_hi:[0,1] neg_hi:[0,1]
	v_xor_b32_e32 v115, 0x80000000, v128
	v_mov_b32_e32 v114, v129
	v_pk_add_f32 v[128:129], v[142:143], v[156:157]
	v_pk_add_f32 v[140:141], v[142:143], v[156:157] neg_lo:[0,1] neg_hi:[0,1]
	v_pk_add_f32 v[142:143], v[138:139], v[134:135]
	v_pk_fma_f32 v[66:67], v[152:153], v[66:67], v[146:147] op_sel_hi:[1,0,1]
	v_pk_mul_f32 v[72:73], v[130:131], v[70:71] op_sel:[1,1] op_sel_hi:[0,1] neg_hi:[0,1]
	v_mov_b32_e32 v92, v91
	v_pk_add_f32 v[110:111], v[108:109], 0 neg_lo:[1,1] neg_hi:[1,1]
	v_pk_add_f32 v[118:119], v[116:117], 0 neg_lo:[1,1] neg_hi:[1,1]
	v_pk_add_f32 v[122:123], v[120:121], 0 neg_lo:[1,1] neg_hi:[1,1]
	v_pk_add_f32 v[124:125], v[68:69], 0 neg_lo:[1,1] neg_hi:[1,1]
	ds_write_b64 v171, v[162:163]
	v_pk_fma_f32 v[78:79], v[148:149], v[78:79], v[80:81] op_sel_hi:[1,0,1]
	v_pk_mul_f32 v[80:81], v[150:151], v[82:83] op_sel:[1,1] op_sel_hi:[0,1] neg_hi:[0,1]
	v_pk_fma_f32 v[84:85], v[154:155], v[98:99], v[96:97] op_sel_hi:[1,0,1]
	v_pk_mul_f32 v[96:97], v[132:133], v[102:103] op_sel:[1,1] op_sel_hi:[0,1] neg_hi:[0,1]
	v_pk_add_f32 v[106:107], v[126:127], v[114:115]
	ds_write_b64 v171, v[66:67] offset:8448
	v_pk_fma_f32 v[66:67], v[130:131], v[70:71], v[72:73] op_sel_hi:[1,0,1]
	v_pk_mul_f32 v[70:71], v[142:143], v[74:75] op_sel:[1,1] op_sel_hi:[0,1] neg_hi:[0,1]
	v_mov_b32_e32 v110, v109
	v_mov_b32_e32 v118, v117
	v_mov_b32_e32 v122, v121
	v_mov_b32_e32 v124, v69
	v_pk_add_f32 v[134:135], v[138:139], v[134:135] neg_lo:[0,1] neg_hi:[0,1]
	v_pk_fma_f32 v[98:99], v[144:145], v[112:113], v[100:101] op_sel_hi:[1,0,1]
	v_pk_add_f32 v[112:113], v[126:127], v[114:115] neg_lo:[0,1] neg_hi:[0,1]
	v_pk_mul_f32 v[76:77], v[128:129], v[86:87] op_sel:[1,1] op_sel_hi:[0,1] neg_hi:[0,1]
	ds_write_b64 v171, v[66:67] offset:16896
	v_pk_fma_f32 v[66:67], v[142:143], v[74:75], v[70:71] op_sel_hi:[1,0,1]
	v_pk_mul_f32 v[74:75], v[106:107], v[92:93] op_sel:[1,0] op_sel_hi:[0,1]
	s_mov_b64 s[48:49], 0
	s_and_b64 vcc, exec, vcc
	v_pk_mul_f32 v[100:101], v[136:137], v[118:119] op_sel:[1,0] op_sel_hi:[0,1]
	v_pk_fma_f32 v[72:73], v[150:151], v[82:83], v[80:81] op_sel_hi:[1,0,1]
	v_pk_fma_f32 v[80:81], v[132:133], v[102:103], v[96:97] op_sel_hi:[1,0,1]
	v_pk_mul_f32 v[82:83], v[134:135], v[110:111] op_sel:[1,0] op_sel_hi:[0,1]
	v_pk_mul_f32 v[96:97], v[140:141], v[122:123] op_sel:[1,0] op_sel_hi:[0,1]
	v_pk_fma_f32 v[70:71], v[128:129], v[86:87], v[76:77] op_sel_hi:[1,0,1]
	v_pk_mul_f32 v[86:87], v[112:113], v[124:125] op_sel:[1,0] op_sel_hi:[0,1]
	ds_write_b64 v171, v[66:67] offset:25344
	ds_write_b64 v171, v[78:79] offset:33792
	ds_write_b64 v171, v[72:73] offset:42240
	ds_write_b64 v171, v[70:71] offset:50688
	v_pk_fma_f32 v[66:67], v[106:107], v[90:91], v[74:75] op_sel_hi:[1,0,1]
	v_pk_fma_f32 v[88:89], v[136:137], v[116:117], v[100:101] op_sel_hi:[1,0,1]
	v_pk_fma_f32 v[76:77], v[134:135], v[108:109], v[82:83] op_sel_hi:[1,0,1]
	v_pk_fma_f32 v[82:83], v[140:141], v[120:121], v[96:97] op_sel_hi:[1,0,1]
	v_pk_fma_f32 v[68:69], v[112:113], v[68:69], v[86:87] op_sel_hi:[1,0,1]
	ds_write_b64 v171, v[66:67] offset:59136
	ds_write_b64 v216, v[94:95]
	ds_write_b64 v216, v[84:85] offset:8448
	ds_write_b64 v216, v[80:81] offset:16896
	ds_write_b64 v216, v[76:77] offset:25344
	ds_write_b64 v216, v[98:99] offset:33792
	ds_write_b64 v216, v[88:89] offset:42240
	ds_write_b64 v216, v[82:83] offset:50688
	ds_write_b64 v216, v[68:69] offset:59136
	s_cbranch_vccz .LBB0_362
	s_waitcnt lgkmcnt(0)
	s_barrier
	v_mov_b32 v0, 0
	s_mov_b32 s5, s14
	v_add_u32_e32 v74, v0, v170
	v_lshlrev_b32_e32 v0, 5, v74
	v_and_b32_e32 v71, 0xfffffc00, v0
	v_and_b32_e32 v70, 31, v74
	v_lshlrev_b32_e32 v78, 3, v71
	v_lshlrev_b32_e32 v79, 3, v70
	v_or_b32_e32 v67, 32, v71
	v_ashrrev_i32_e32 v67, 2, v67
	v_add_u32_e32 v67, 0, v67
	v_add3_u32 v114, v67, v78, v79
	v_ashrrev_i32_e32 v66, 2, v71
	v_add_u32_e32 v66, 0, v66
	v_add3_u32 v66, v66, v78, v79
	v_mov_b32_e32 v222, v114
	ds_read_b64 v[66:67], v66
	ds_read_b64 v[68:69], v222 offset:256
	ds_read_b64 v[72:73], v222 offset:520
	ds_read_b64 v[76:77], v222 offset:784
	ds_read_b64 v[80:81], v222 offset:1048
	ds_read_b64 v[82:83], v222 offset:1312
	ds_read_b64 v[116:117], v222 offset:1576
	ds_read_b64 v[118:119], v222 offset:1840
	ds_read_b64 v[120:121], v222 offset:2104
	ds_read_b64 v[122:123], v222 offset:2368
	ds_read_b64 v[124:125], v222 offset:2632
	ds_read_b64 v[126:127], v222 offset:2896
	ds_read_b64 v[128:129], v222 offset:3160
	ds_read_b64 v[130:131], v222 offset:3424
	ds_read_b64 v[132:133], v222 offset:3688
	ds_read_b64 v[134:135], v222 offset:3952
	ds_read_b64 v[136:137], v222 offset:4216
	ds_read_b64 v[138:139], v222 offset:4480
	ds_read_b64 v[140:141], v222 offset:4744
	ds_read_b64 v[142:143], v222 offset:5008
	s_waitcnt lgkmcnt(3)
	v_pk_add_f32 v[168:169], v[66:67], v[136:137]
	v_pk_add_f32 v[66:67], v[66:67], v[136:137] neg_lo:[0,1] neg_hi:[0,1]
	s_waitcnt lgkmcnt(2)
	v_pk_add_f32 v[136:137], v[68:69], v[138:139]
	v_pk_add_f32 v[68:69], v[68:69], v[138:139] neg_lo:[0,1] neg_hi:[0,1]
	v_pk_mul_f32 v[138:139], v[68:69], s[18:19]
	v_pk_fma_f32 v[68:69], v[68:69], s[20:21], v[138:139] op_sel:[0,0,1] op_sel_hi:[1,0,0]
	s_waitcnt lgkmcnt(1)
	v_pk_add_f32 v[138:139], v[72:73], v[140:141]
	v_pk_add_f32 v[72:73], v[72:73], v[140:141] neg_lo:[0,1] neg_hi:[0,1]
	v_pk_mul_f32 v[140:141], v[72:73], s[4:5]
	ds_read_b64 v[144:145], v222 offset:5272
	ds_read_b64 v[146:147], v222 offset:5536
	ds_read_b64 v[148:149], v222 offset:5800
	ds_read_b64 v[150:151], v222 offset:6064
	v_pk_fma_f32 v[72:73], v[72:73], s[6:7], v[140:141] op_sel:[0,0,1] op_sel_hi:[1,0,0]
	s_waitcnt lgkmcnt(4)
	v_pk_add_f32 v[140:141], v[76:77], v[142:143]
	v_pk_add_f32 v[76:77], v[76:77], v[142:143] neg_lo:[0,1] neg_hi:[0,1]
	v_pk_mul_f32 v[142:143], v[76:77], s[22:23]
	v_pk_fma_f32 v[76:77], v[76:77], s[24:25], v[142:143] op_sel:[0,0,1] op_sel_hi:[1,0,0]
	s_waitcnt lgkmcnt(3)
	v_pk_add_f32 v[142:143], v[80:81], v[144:145]
	v_pk_add_f32 v[80:81], v[80:81], v[144:145] neg_lo:[0,1] neg_hi:[0,1]
	s_mov_b32 s9, s10
	v_pk_mul_f32 v[144:145], v[80:81], s[8:9]
	v_pk_fma_f32 v[80:81], v[80:81], s[10:11], v[144:145] op_sel:[0,0,1] op_sel_hi:[1,0,0]
	s_waitcnt lgkmcnt(2)
	v_pk_add_f32 v[144:145], v[82:83], v[146:147]
	v_pk_add_f32 v[82:83], v[82:83], v[146:147] neg_lo:[0,1] neg_hi:[0,1]
	s_mov_b32 s27, s24
	v_pk_mul_f32 v[146:147], v[82:83], s[26:27]
	s_mov_b32 s0, s23
	v_pk_fma_f32 v[82:83], v[82:83], s[0:1], v[146:147] op_sel:[0,0,1] op_sel_hi:[1,0,0]
	s_waitcnt lgkmcnt(1)
	v_pk_add_f32 v[146:147], v[116:117], v[148:149]
	v_pk_add_f32 v[116:117], v[116:117], v[148:149] neg_lo:[0,1] neg_hi:[0,1]
	s_mov_b32 s13, s6
	v_pk_mul_f32 v[148:149], v[116:117], s[12:13]
	ds_read_b64 v[152:153], v222 offset:6328
	ds_read_b64 v[154:155], v222 offset:6592
	ds_read_b64 v[156:157], v222 offset:6856
	ds_read_b64 v[158:159], v222 offset:7120
	v_pk_fma_f32 v[116:117], v[116:117], s[14:15], v[148:149] op_sel:[0,0,1] op_sel_hi:[1,0,0]
	s_waitcnt lgkmcnt(4)
	v_pk_add_f32 v[148:149], v[118:119], v[150:151]
	v_pk_add_f32 v[118:119], v[118:119], v[150:151] neg_lo:[0,1] neg_hi:[0,1]
	s_mov_b32 s35, s20
	v_pk_mul_f32 v[150:151], v[118:119], s[34:35]
	s_mov_b32 s48, s19
	v_pk_fma_f32 v[118:119], v[118:119], s[48:49], v[150:151] op_sel:[0,0,1] op_sel_hi:[1,0,0]
	s_waitcnt lgkmcnt(3)
	v_pk_add_f32 v[150:151], v[120:121], v[152:153]
	v_pk_add_f32 v[152:153], v[120:121], v[152:153] op_sel:[1,1] op_sel_hi:[0,0] neg_lo:[0,1] neg_hi:[1,0]
	s_waitcnt lgkmcnt(2)
	v_pk_add_f32 v[120:121], v[122:123], v[154:155]
	v_pk_add_f32 v[122:123], v[122:123], v[154:155] neg_lo:[0,1] neg_hi:[0,1]
	v_pk_mul_f32 v[154:155], v[122:123], s[34:35]
	v_pk_fma_f32 v[122:123], v[122:123], s[18:19], v[154:155] op_sel:[0,0,1] op_sel_hi:[1,0,0]
	s_waitcnt lgkmcnt(1)
	v_pk_add_f32 v[154:155], v[124:125], v[156:157]
	v_pk_add_f32 v[124:125], v[124:125], v[156:157] neg_lo:[0,1] neg_hi:[0,1]
	v_pk_mul_f32 v[156:157], v[124:125], s[12:13]
	ds_read_b64 v[160:161], v222 offset:7384
	ds_read_b64 v[162:163], v222 offset:7648
	ds_read_b64 v[164:165], v222 offset:7912
	ds_read_b64 v[166:167], v222 offset:8176
	v_pk_fma_f32 v[124:125], v[124:125], s[4:5], v[156:157] op_sel:[0,0,1] op_sel_hi:[1,0,0]
	s_waitcnt lgkmcnt(4)
	v_pk_add_f32 v[156:157], v[126:127], v[158:159]
	v_pk_add_f32 v[126:127], v[126:127], v[158:159] neg_lo:[0,1] neg_hi:[0,1]
	v_lshlrev_b32_e32 v70, 4, v70
	v_pk_mul_f32 v[158:159], v[126:127], s[26:27]
	v_cvt_f32_u32_e32 v75, v70
	v_pk_fma_f32 v[126:127], v[126:127], s[22:23], v[158:159] op_sel:[0,0,1] op_sel_hi:[1,0,0]
	s_waitcnt lgkmcnt(3)
	v_pk_add_f32 v[158:159], v[128:129], v[160:161]
	v_pk_add_f32 v[128:129], v[128:129], v[160:161] neg_lo:[0,1] neg_hi:[0,1]
	v_and_b32_e32 v74, 0x1fffffe0, v74
	v_pk_mul_f32 v[160:161], v[128:129], s[8:9]
	v_mul_f32_e32 v115, 0x38800000, v75
	v_pk_fma_f32 v[128:129], v[128:129], s[8:9], v[160:161] op_sel:[0,0,1] op_sel_hi:[1,0,0]
	s_waitcnt lgkmcnt(2)
	v_pk_add_f32 v[160:161], v[130:131], v[162:163]
	v_pk_add_f32 v[130:131], v[130:131], v[162:163] neg_lo:[0,1] neg_hi:[0,1]
	v_lshl_add_u32 v74, v74, 3, 0
	v_pk_mul_f32 v[162:163], v[130:131], s[22:23]
	v_sin_f32_e32 v75, v115
	v_pk_fma_f32 v[130:131], v[130:131], s[26:27], v[162:163] op_sel:[0,0,1] op_sel_hi:[1,0,0]
	s_waitcnt lgkmcnt(1)
	v_pk_add_f32 v[162:163], v[132:133], v[164:165]
	v_pk_add_f32 v[132:133], v[132:133], v[164:165] neg_lo:[0,1] neg_hi:[0,1]
	v_add3_u32 v74, v74, v78, v79
	v_pk_mul_f32 v[164:165], v[132:133], s[4:5]
	v_xor_b32_e32 v78, 0x80000000, v75
	v_pk_fma_f32 v[132:133], v[132:133], s[12:13], v[164:165] op_sel:[0,0,1] op_sel_hi:[1,0,0]
	s_waitcnt lgkmcnt(0)
	v_pk_add_f32 v[164:165], v[134:135], v[166:167]
	v_pk_add_f32 v[134:135], v[134:135], v[166:167] neg_lo:[0,1] neg_hi:[0,1]
	v_mov_b32_e32 v79, v75
	v_pk_mul_f32 v[166:167], v[134:135], s[18:19]
	s_mov_b32 s50, s19
	v_pk_fma_f32 v[134:135], v[134:135], s[34:35], v[166:167] op_sel:[0,0,1] op_sel_hi:[1,0,0]
	v_pk_add_f32 v[166:167], v[168:169], v[150:151]
	v_pk_add_f32 v[150:151], v[168:169], v[150:151] neg_lo:[0,1] neg_hi:[0,1]
	v_pk_add_f32 v[168:169], v[136:137], v[120:121]
	v_pk_add_f32 v[120:121], v[136:137], v[120:121] neg_lo:[0,1] neg_hi:[0,1]
	s_mov_b32 s51, s18
	v_pk_mul_f32 v[136:137], v[120:121], s[4:5]
	s_mov_b32 s52, s23
	v_pk_fma_f32 v[120:121], v[120:121], s[6:7], v[136:137] op_sel:[0,0,1] op_sel_hi:[1,0,0]
	v_pk_add_f32 v[136:137], v[138:139], v[154:155]
	v_pk_add_f32 v[138:139], v[138:139], v[154:155] neg_lo:[0,1] neg_hi:[0,1]
	s_mov_b32 s53, s22
	v_pk_mul_f32 v[154:155], v[138:139], s[8:9]
	s_nop 0
	v_pk_fma_f32 v[138:139], v[138:139], s[10:11], v[154:155] op_sel:[0,0,1] op_sel_hi:[1,0,0]
	v_pk_add_f32 v[154:155], v[140:141], v[156:157]
	v_pk_add_f32 v[140:141], v[140:141], v[156:157] neg_lo:[0,1] neg_hi:[0,1]
	s_nop 0
	v_pk_mul_f32 v[156:157], v[140:141], s[12:13]
	s_nop 0
	v_pk_fma_f32 v[140:141], v[140:141], s[14:15], v[156:157] op_sel:[0,0,1] op_sel_hi:[1,0,0]
	v_pk_add_f32 v[156:157], v[142:143], v[158:159]
	v_pk_add_f32 v[158:159], v[142:143], v[158:159] op_sel:[1,1] op_sel_hi:[0,0] neg_lo:[0,1] neg_hi:[1,0]
	s_nop 0
	v_pk_add_f32 v[142:143], v[144:145], v[160:161]
	v_pk_add_f32 v[144:145], v[144:145], v[160:161] neg_lo:[0,1] neg_hi:[0,1]
	s_nop 0
	v_pk_mul_f32 v[160:161], v[144:145], s[12:13]
	s_nop 0
	v_pk_fma_f32 v[144:145], v[144:145], s[4:5], v[160:161] op_sel:[0,0,1] op_sel_hi:[1,0,0]
	v_pk_add_f32 v[160:161], v[146:147], v[162:163]
	v_pk_add_f32 v[146:147], v[146:147], v[162:163] neg_lo:[0,1] neg_hi:[0,1]
	s_nop 0
	v_pk_mul_f32 v[162:163], v[146:147], s[8:9]
	s_nop 0
	v_pk_fma_f32 v[146:147], v[146:147], s[8:9], v[162:163] op_sel:[0,0,1] op_sel_hi:[1,0,0]
	v_pk_add_f32 v[162:163], v[148:149], v[164:165]
	v_pk_add_f32 v[148:149], v[148:149], v[164:165] neg_lo:[0,1] neg_hi:[0,1]
	s_nop 0
	v_pk_mul_f32 v[164:165], v[148:149], s[4:5]
	s_nop 0
	v_pk_fma_f32 v[148:149], v[148:149], s[12:13], v[164:165] op_sel:[0,0,1] op_sel_hi:[1,0,0]
	v_pk_add_f32 v[164:165], v[66:67], v[152:153]
	v_pk_add_f32 v[66:67], v[66:67], v[152:153] neg_lo:[0,1] neg_hi:[0,1]
	v_pk_add_f32 v[152:153], v[68:69], v[122:123]
	v_pk_add_f32 v[68:69], v[68:69], v[122:123] neg_lo:[0,1] neg_hi:[0,1]
	s_nop 0
	v_pk_mul_f32 v[122:123], v[68:69], s[4:5]
	s_nop 0
	v_pk_fma_f32 v[68:69], v[68:69], s[6:7], v[122:123] op_sel:[0,0,1] op_sel_hi:[1,0,0]
	v_pk_add_f32 v[122:123], v[72:73], v[124:125]
	v_pk_add_f32 v[72:73], v[72:73], v[124:125] neg_lo:[0,1] neg_hi:[0,1]
	s_nop 0
	v_pk_mul_f32 v[124:125], v[72:73], s[8:9]
	s_nop 0
	v_pk_fma_f32 v[72:73], v[72:73], s[10:11], v[124:125] op_sel:[0,0,1] op_sel_hi:[1,0,0]
	v_pk_add_f32 v[124:125], v[76:77], v[126:127]
	v_pk_add_f32 v[76:77], v[76:77], v[126:127] neg_lo:[0,1] neg_hi:[0,1]
	s_nop 0
	v_pk_mul_f32 v[126:127], v[76:77], s[12:13]
	s_nop 0
	v_pk_fma_f32 v[76:77], v[76:77], s[14:15], v[126:127] op_sel:[0,0,1] op_sel_hi:[1,0,0]
	v_pk_add_f32 v[126:127], v[80:81], v[128:129]
	v_pk_add_f32 v[128:129], v[80:81], v[128:129] op_sel:[1,1] op_sel_hi:[0,0] neg_lo:[0,1] neg_hi:[1,0]
	s_nop 0
	v_pk_add_f32 v[80:81], v[82:83], v[130:131]
	v_pk_add_f32 v[82:83], v[82:83], v[130:131] neg_lo:[0,1] neg_hi:[0,1]
	s_nop 0
	v_pk_mul_f32 v[130:131], v[82:83], s[12:13]
	s_nop 0
	v_pk_fma_f32 v[82:83], v[82:83], s[4:5], v[130:131] op_sel:[0,0,1] op_sel_hi:[1,0,0]
	v_pk_add_f32 v[130:131], v[116:117], v[132:133]
	v_pk_add_f32 v[116:117], v[116:117], v[132:133] neg_lo:[0,1] neg_hi:[0,1]
	s_nop 0
	v_pk_mul_f32 v[132:133], v[116:117], s[8:9]
	s_nop 0
	v_pk_fma_f32 v[116:117], v[116:117], s[8:9], v[132:133] op_sel:[0,0,1] op_sel_hi:[1,0,0]
	v_pk_add_f32 v[132:133], v[118:119], v[134:135]
	v_pk_add_f32 v[118:119], v[118:119], v[134:135] neg_lo:[0,1] neg_hi:[0,1]
	s_nop 0
	v_pk_mul_f32 v[134:135], v[118:119], s[4:5]
	s_nop 0
	v_pk_fma_f32 v[118:119], v[118:119], s[12:13], v[134:135] op_sel:[0,0,1] op_sel_hi:[1,0,0]
	v_pk_add_f32 v[134:135], v[166:167], v[156:157]
	v_pk_add_f32 v[156:157], v[166:167], v[156:157] neg_lo:[0,1] neg_hi:[0,1]
	v_pk_add_f32 v[166:167], v[168:169], v[142:143]
	v_pk_add_f32 v[142:143], v[168:169], v[142:143] neg_lo:[0,1] neg_hi:[0,1]
	s_nop 0
	v_pk_mul_f32 v[168:169], v[142:143], s[8:9]
	s_nop 0
	v_pk_fma_f32 v[142:143], v[142:143], s[10:11], v[168:169] op_sel:[0,0,1] op_sel_hi:[1,0,0]
	v_pk_add_f32 v[168:169], v[136:137], v[160:161]
	v_pk_add_f32 v[160:161], v[136:137], v[160:161] op_sel:[1,1] op_sel_hi:[0,0] neg_lo:[0,1] neg_hi:[1,0]
	s_nop 0
	v_pk_add_f32 v[136:137], v[154:155], v[162:163]
	v_pk_add_f32 v[154:155], v[154:155], v[162:163] neg_lo:[0,1] neg_hi:[0,1]
	s_nop 0
	v_pk_mul_f32 v[162:163], v[154:155], s[8:9]
	s_nop 0
	v_pk_fma_f32 v[154:155], v[154:155], s[8:9], v[162:163] op_sel:[0,0,1] op_sel_hi:[1,0,0]
	v_pk_add_f32 v[162:163], v[150:151], v[158:159]
	v_pk_add_f32 v[150:151], v[150:151], v[158:159] neg_lo:[0,1] neg_hi:[0,1]
	v_pk_add_f32 v[158:159], v[120:121], v[144:145]
	v_pk_add_f32 v[120:121], v[120:121], v[144:145] neg_lo:[0,1] neg_hi:[0,1]
	s_nop 0
	v_pk_mul_f32 v[144:145], v[120:121], s[8:9]
	s_nop 0
	v_pk_fma_f32 v[120:121], v[120:121], s[10:11], v[144:145] op_sel:[0,0,1] op_sel_hi:[1,0,0]
	v_pk_add_f32 v[144:145], v[138:139], v[146:147]
	v_pk_add_f32 v[146:147], v[138:139], v[146:147] op_sel:[1,1] op_sel_hi:[0,0] neg_lo:[0,1] neg_hi:[1,0]
	s_nop 0
	v_pk_add_f32 v[138:139], v[140:141], v[148:149]
	v_pk_add_f32 v[140:141], v[140:141], v[148:149] neg_lo:[0,1] neg_hi:[0,1]
	s_nop 0
	v_pk_mul_f32 v[148:149], v[140:141], s[8:9]
	s_nop 0
	v_pk_fma_f32 v[140:141], v[140:141], s[8:9], v[148:149] op_sel:[0,0,1] op_sel_hi:[1,0,0]
	v_pk_add_f32 v[148:149], v[164:165], v[126:127]
	v_pk_add_f32 v[126:127], v[164:165], v[126:127] neg_lo:[0,1] neg_hi:[0,1]
	v_pk_add_f32 v[164:165], v[152:153], v[80:81]
	v_pk_add_f32 v[80:81], v[152:153], v[80:81] neg_lo:[0,1] neg_hi:[0,1]
	s_nop 0
	v_pk_mul_f32 v[152:153], v[80:81], s[8:9]
	s_nop 0
	v_pk_fma_f32 v[80:81], v[80:81], s[10:11], v[152:153] op_sel:[0,0,1] op_sel_hi:[1,0,0]
	v_pk_add_f32 v[152:153], v[122:123], v[130:131]
	v_pk_add_f32 v[130:131], v[122:123], v[130:131] op_sel:[1,1] op_sel_hi:[0,0] neg_lo:[0,1] neg_hi:[1,0]
	s_nop 0
	v_pk_add_f32 v[122:123], v[124:125], v[132:133]
	v_pk_add_f32 v[124:125], v[124:125], v[132:133] neg_lo:[0,1] neg_hi:[0,1]
	s_nop 0
	v_pk_mul_f32 v[132:133], v[124:125], s[8:9]
	s_nop 0
	v_pk_fma_f32 v[124:125], v[124:125], s[8:9], v[132:133] op_sel:[0,0,1] op_sel_hi:[1,0,0]
	v_pk_add_f32 v[132:133], v[66:67], v[128:129]
	v_pk_add_f32 v[66:67], v[66:67], v[128:129] neg_lo:[0,1] neg_hi:[0,1]
	v_pk_add_f32 v[128:129], v[68:69], v[82:83]
	v_pk_add_f32 v[68:69], v[68:69], v[82:83] neg_lo:[0,1] neg_hi:[0,1]
	s_nop 0
	v_pk_mul_f32 v[82:83], v[68:69], s[8:9]
	s_nop 0
	v_pk_fma_f32 v[68:69], v[68:69], s[10:11], v[82:83] op_sel:[0,0,1] op_sel_hi:[1,0,0]
	v_pk_add_f32 v[82:83], v[72:73], v[116:117]
	v_pk_add_f32 v[116:117], v[72:73], v[116:117] op_sel:[1,1] op_sel_hi:[0,0] neg_lo:[0,1] neg_hi:[1,0]
	s_nop 0
	v_pk_add_f32 v[72:73], v[76:77], v[118:119]
	v_pk_add_f32 v[76:77], v[76:77], v[118:119] neg_lo:[0,1] neg_hi:[0,1]
	v_pk_add_f32 v[174:175], v[66:67], v[116:117]
	v_pk_mul_f32 v[118:119], v[76:77], s[8:9]
	v_pk_add_f32 v[116:117], v[66:67], v[116:117] neg_lo:[0,1] neg_hi:[0,1]
	v_pk_fma_f32 v[76:77], v[76:77], s[8:9], v[118:119] op_sel:[0,0,1] op_sel_hi:[1,0,0]
	v_pk_add_f32 v[118:119], v[134:135], v[168:169]
	v_pk_add_f32 v[134:135], v[134:135], v[168:169] neg_lo:[0,1] neg_hi:[0,1]
	v_pk_add_f32 v[168:169], v[166:167], v[136:137]
	v_pk_add_f32 v[166:167], v[166:167], v[136:137] op_sel:[1,1] op_sel_hi:[0,0] neg_lo:[0,1] neg_hi:[1,0]
	v_pk_add_f32 v[180:181], v[118:119], v[168:169]
	v_pk_add_f32 v[136:137], v[156:157], v[160:161]
	v_pk_add_f32 v[156:157], v[156:157], v[160:161] neg_lo:[0,1] neg_hi:[0,1]
	v_pk_add_f32 v[160:161], v[142:143], v[154:155]
	v_pk_add_f32 v[154:155], v[142:143], v[154:155] op_sel:[1,1] op_sel_hi:[0,0] neg_lo:[0,1] neg_hi:[1,0]
	v_pk_add_f32 v[178:179], v[68:69], v[76:77] op_sel:[1,1] op_sel_hi:[0,0] neg_lo:[0,1] neg_hi:[1,0]
	v_pk_add_f32 v[142:143], v[162:163], v[144:145]
	v_pk_add_f32 v[144:145], v[162:163], v[144:145] neg_lo:[0,1] neg_hi:[0,1]
	v_pk_add_f32 v[162:163], v[158:159], v[138:139]
	v_pk_add_f32 v[158:159], v[158:159], v[138:139] op_sel:[1,1] op_sel_hi:[0,0] neg_lo:[0,1] neg_hi:[1,0]
	ds_write_b64 v74, v[180:181]
	v_pk_add_f32 v[138:139], v[150:151], v[146:147]
	v_pk_add_f32 v[146:147], v[150:151], v[146:147] neg_lo:[0,1] neg_hi:[0,1]
	v_pk_add_f32 v[150:151], v[120:121], v[140:141]
	v_pk_add_f32 v[140:141], v[120:121], v[140:141] op_sel:[1,1] op_sel_hi:[0,0] neg_lo:[0,1] neg_hi:[1,0]
	v_cos_f32_e32 v74, v115
	v_pk_add_f32 v[120:121], v[148:149], v[152:153]
	v_pk_add_f32 v[148:149], v[148:149], v[152:153] neg_lo:[0,1] neg_hi:[0,1]
	v_pk_add_f32 v[152:153], v[164:165], v[122:123]
	v_pk_add_f32 v[164:165], v[164:165], v[122:123] op_sel:[1,1] op_sel_hi:[0,0] neg_lo:[0,1] neg_hi:[1,0]
	v_pk_add_f32 v[122:123], v[126:127], v[130:131]
	v_pk_add_f32 v[126:127], v[126:127], v[130:131] neg_lo:[0,1] neg_hi:[0,1]
	v_pk_add_f32 v[130:131], v[80:81], v[124:125]
	v_pk_add_f32 v[124:125], v[80:81], v[124:125] op_sel:[1,1] op_sel_hi:[0,0] neg_lo:[0,1] neg_hi:[1,0]
	v_pk_add_f32 v[80:81], v[132:133], v[82:83]
	v_pk_add_f32 v[132:133], v[132:133], v[82:83] neg_lo:[0,1] neg_hi:[0,1]
	v_pk_add_f32 v[176:177], v[68:69], v[76:77]
	v_pk_add_f32 v[118:119], v[118:119], v[168:169] neg_lo:[0,1] neg_hi:[0,1]
	v_pk_add_f32 v[168:169], v[134:135], v[166:167]
	v_pk_add_f32 v[82:83], v[134:135], v[166:167] neg_lo:[0,1] neg_hi:[0,1]
	v_pk_add_f32 v[134:135], v[136:137], v[160:161]
	v_pk_add_f32 v[136:137], v[136:137], v[160:161] neg_lo:[0,1] neg_hi:[0,1]
	v_pk_add_f32 v[160:161], v[156:157], v[154:155]
	v_pk_add_f32 v[68:69], v[156:157], v[154:155] neg_lo:[0,1] neg_hi:[0,1]
	v_pk_add_f32 v[154:155], v[142:143], v[162:163]
	v_pk_add_f32 v[142:143], v[142:143], v[162:163] neg_lo:[0,1] neg_hi:[0,1]
	v_pk_add_f32 v[156:157], v[144:145], v[158:159]
	v_pk_add_f32 v[76:77], v[144:145], v[158:159] neg_lo:[0,1] neg_hi:[0,1]
	v_pk_add_f32 v[144:145], v[138:139], v[150:151]
	v_pk_add_f32 v[138:139], v[138:139], v[150:151] neg_lo:[0,1] neg_hi:[0,1]
	v_pk_add_f32 v[150:151], v[146:147], v[140:141]
	v_pk_add_f32 v[66:67], v[146:147], v[140:141] neg_lo:[0,1] neg_hi:[0,1]
	v_pk_add_f32 v[140:141], v[120:121], v[152:153]
	v_pk_add_f32 v[162:163], v[116:117], v[178:179]
	v_pk_add_f32 v[70:71], v[116:117], v[178:179] neg_lo:[0,1] neg_hi:[0,1]
	v_mov_b32_e32 v116, v75
	v_pk_mul_f32 v[116:117], v[116:117], v[140:141] op_sel:[0,1] op_sel_hi:[0,0] neg_hi:[1,0]
	v_pk_fma_f32 v[116:117], v[140:141], v[74:75], v[116:117] op_sel_hi:[1,0,1]
	ds_write_b64 v222, v[116:117] offset:256
	v_pk_mul_f32 v[114:115], v[78:79], v[74:75] op_sel:[0,1] op_sel_hi:[1,0]
	v_pk_add_f32 v[172:173], v[128:129], v[72:73]
	v_pk_fma_f32 v[114:115], v[74:75], v[74:75], v[114:115] op_sel_hi:[1,0,1]
	v_pk_add_f32 v[128:129], v[128:129], v[72:73] op_sel:[1,1] op_sel_hi:[0,0] neg_lo:[0,1] neg_hi:[1,0]
	v_pk_mul_f32 v[116:117], v[154:155], v[114:115] op_sel:[1,1] op_sel_hi:[0,1] neg_hi:[0,1]
	v_pk_fma_f32 v[116:117], v[154:155], v[114:115], v[116:117] op_sel_hi:[1,0,1]
	ds_write_b64 v222, v[116:117] offset:520
	v_pk_mul_f32 v[116:117], v[78:79], v[114:115] op_sel:[0,1] op_sel_hi:[1,0]
	v_pk_add_f32 v[120:121], v[120:121], v[152:153] neg_lo:[0,1] neg_hi:[0,1]
	v_pk_fma_f32 v[114:115], v[114:115], v[74:75], v[116:117] op_sel_hi:[1,0,1]
	v_pk_add_f32 v[152:153], v[122:123], v[130:131]
	v_pk_add_f32 v[122:123], v[122:123], v[130:131] neg_lo:[0,1] neg_hi:[0,1]
	v_pk_add_f32 v[130:131], v[126:127], v[124:125]
	v_pk_add_f32 v[72:73], v[126:127], v[124:125] neg_lo:[0,1] neg_hi:[0,1]
	v_pk_add_f32 v[124:125], v[80:81], v[172:173]
	v_pk_mul_f32 v[116:117], v[124:125], v[114:115] op_sel:[1,1] op_sel_hi:[0,1] neg_hi:[0,1]
	v_pk_add_f32 v[126:127], v[80:81], v[172:173] neg_lo:[0,1] neg_hi:[0,1]
	v_pk_fma_f32 v[116:117], v[124:125], v[114:115], v[116:117] op_sel_hi:[1,0,1]
	ds_write_b64 v222, v[116:117] offset:784
	v_pk_mul_f32 v[112:113], v[78:79], v[114:115] op_sel:[0,1] op_sel_hi:[1,0]
	v_pk_add_f32 v[158:159], v[132:133], v[128:129]
	v_pk_fma_f32 v[112:113], v[114:115], v[74:75], v[112:113] op_sel_hi:[1,0,1]
	v_pk_add_f32 v[80:81], v[132:133], v[128:129] neg_lo:[0,1] neg_hi:[0,1]
	v_pk_add_f32 v[128:129], v[174:175], v[176:177]
	v_pk_mul_f32 v[114:115], v[134:135], v[112:113] op_sel:[1,1] op_sel_hi:[0,1] neg_hi:[0,1]
	v_pk_add_f32 v[146:147], v[148:149], v[164:165]
	v_pk_fma_f32 v[114:115], v[134:135], v[112:113], v[114:115] op_sel_hi:[1,0,1]
	ds_write_b64 v222, v[114:115] offset:1048
	v_pk_mul_f32 v[114:115], v[78:79], v[112:113] op_sel:[0,1] op_sel_hi:[1,0]
	v_pk_add_f32 v[132:133], v[174:175], v[176:177] neg_lo:[0,1] neg_hi:[0,1]
	v_pk_fma_f32 v[112:113], v[112:113], v[74:75], v[114:115] op_sel_hi:[1,0,1]
	v_pk_add_f32 v[148:149], v[148:149], v[164:165] neg_lo:[0,1] neg_hi:[0,1]
	s_nop 0
	v_pk_mul_f32 v[114:115], v[152:153], v[112:113] op_sel:[1,1] op_sel_hi:[0,1] neg_hi:[0,1]
	s_nop 0
	v_pk_fma_f32 v[114:115], v[152:153], v[112:113], v[114:115] op_sel_hi:[1,0,1]
	ds_write_b64 v222, v[114:115] offset:1312
	v_pk_mul_f32 v[110:111], v[78:79], v[112:113] op_sel:[0,1] op_sel_hi:[1,0]
	s_nop 0
	v_pk_fma_f32 v[110:111], v[112:113], v[74:75], v[110:111] op_sel_hi:[1,0,1]
	s_nop 0
	s_nop 0
	v_pk_mul_f32 v[112:113], v[144:145], v[110:111] op_sel:[1,1] op_sel_hi:[0,1] neg_hi:[0,1]
	s_nop 0
	v_pk_fma_f32 v[112:113], v[144:145], v[110:111], v[112:113] op_sel_hi:[1,0,1]
	ds_write_b64 v222, v[112:113] offset:1576
	v_pk_mul_f32 v[112:113], v[78:79], v[110:111] op_sel:[0,1] op_sel_hi:[1,0]
	s_nop 0
	v_pk_fma_f32 v[110:111], v[110:111], v[74:75], v[112:113] op_sel_hi:[1,0,1]
	s_nop 0
	s_nop 0
	v_pk_mul_f32 v[112:113], v[128:129], v[110:111] op_sel:[1,1] op_sel_hi:[0,1] neg_hi:[0,1]
	s_nop 0
	v_pk_fma_f32 v[112:113], v[128:129], v[110:111], v[112:113] op_sel_hi:[1,0,1]
	ds_write_b64 v222, v[112:113] offset:1840
	v_pk_mul_f32 v[108:109], v[78:79], v[110:111] op_sel:[0,1] op_sel_hi:[1,0]
	s_nop 0
	v_pk_fma_f32 v[108:109], v[110:111], v[74:75], v[108:109] op_sel_hi:[1,0,1]
	s_nop 0
	s_nop 0
	v_pk_mul_f32 v[110:111], v[168:169], v[108:109] op_sel:[1,1] op_sel_hi:[0,1] neg_hi:[0,1]
	s_nop 0
	v_pk_fma_f32 v[110:111], v[168:169], v[108:109], v[110:111] op_sel_hi:[1,0,1]
	ds_write_b64 v222, v[110:111] offset:2104
	v_pk_mul_f32 v[110:111], v[78:79], v[108:109] op_sel:[0,1] op_sel_hi:[1,0]
	s_nop 0
	v_pk_fma_f32 v[108:109], v[108:109], v[74:75], v[110:111] op_sel_hi:[1,0,1]
	s_nop 0
	s_nop 0
	v_pk_mul_f32 v[110:111], v[146:147], v[108:109] op_sel:[1,1] op_sel_hi:[0,1] neg_hi:[0,1]
	s_nop 0
	v_pk_fma_f32 v[110:111], v[146:147], v[108:109], v[110:111] op_sel_hi:[1,0,1]
	ds_write_b64 v222, v[110:111] offset:2368
	v_pk_mul_f32 v[106:107], v[78:79], v[108:109] op_sel:[0,1] op_sel_hi:[1,0]
	s_nop 0
	v_pk_fma_f32 v[106:107], v[108:109], v[74:75], v[106:107] op_sel_hi:[1,0,1]
	s_nop 0
	s_nop 0
	v_pk_mul_f32 v[108:109], v[156:157], v[106:107] op_sel:[1,1] op_sel_hi:[0,1] neg_hi:[0,1]
	s_nop 0
	v_pk_fma_f32 v[108:109], v[156:157], v[106:107], v[108:109] op_sel_hi:[1,0,1]
	ds_write_b64 v222, v[108:109] offset:2632
	v_pk_mul_f32 v[108:109], v[78:79], v[106:107] op_sel:[0,1] op_sel_hi:[1,0]
	s_nop 0
	v_pk_fma_f32 v[106:107], v[106:107], v[74:75], v[108:109] op_sel_hi:[1,0,1]
	s_nop 0
	s_nop 0
	v_pk_mul_f32 v[108:109], v[158:159], v[106:107] op_sel:[1,1] op_sel_hi:[0,1] neg_hi:[0,1]
	s_nop 0
	v_pk_fma_f32 v[108:109], v[158:159], v[106:107], v[108:109] op_sel_hi:[1,0,1]
	ds_write_b64 v222, v[108:109] offset:2896
	v_pk_mul_f32 v[108:109], v[78:79], v[106:107] op_sel:[0,1] op_sel_hi:[1,0]
	s_nop 0
	v_pk_fma_f32 v[106:107], v[106:107], v[74:75], v[108:109] op_sel_hi:[1,0,1]
	s_nop 0
	s_nop 0
	v_pk_mul_f32 v[108:109], v[160:161], v[106:107] op_sel:[1,1] op_sel_hi:[0,1] neg_hi:[0,1]
	s_nop 0
	v_pk_fma_f32 v[108:109], v[160:161], v[106:107], v[108:109] op_sel_hi:[1,0,1]
	ds_write_b64 v222, v[108:109] offset:3160
	v_pk_mul_f32 v[102:103], v[78:79], v[106:107] op_sel:[0,1] op_sel_hi:[1,0]
	s_nop 0
	v_pk_fma_f32 v[102:103], v[106:107], v[74:75], v[102:103] op_sel_hi:[1,0,1]
	s_nop 0
	s_nop 0
	v_pk_mul_f32 v[106:107], v[130:131], v[102:103] op_sel:[1,1] op_sel_hi:[0,1] neg_hi:[0,1]
	s_nop 0
	v_pk_fma_f32 v[106:107], v[130:131], v[102:103], v[106:107] op_sel_hi:[1,0,1]
	ds_write_b64 v222, v[106:107] offset:3424
	v_pk_mul_f32 v[106:107], v[78:79], v[102:103] op_sel:[0,1] op_sel_hi:[1,0]
	s_nop 0
	v_pk_fma_f32 v[102:103], v[102:103], v[74:75], v[106:107] op_sel_hi:[1,0,1]
	s_nop 0
	s_nop 0
	v_pk_mul_f32 v[106:107], v[150:151], v[102:103] op_sel:[1,1] op_sel_hi:[0,1] neg_hi:[0,1]
	v_pk_fma_f32 v[106:107], v[150:151], v[102:103], v[106:107] op_sel_hi:[1,0,1]
	ds_write_b64 v222, v[106:107] offset:3688
	v_pk_mul_f32 v[100:101], v[78:79], v[102:103] op_sel:[0,1] op_sel_hi:[1,0]
	s_nop 0
	v_pk_fma_f32 v[100:101], v[102:103], v[74:75], v[100:101] op_sel_hi:[1,0,1]
	s_nop 0
	s_nop 0
	v_pk_mul_f32 v[102:103], v[162:163], v[100:101] op_sel:[1,1] op_sel_hi:[0,1] neg_hi:[0,1]
	v_pk_fma_f32 v[102:103], v[162:163], v[100:101], v[102:103] op_sel_hi:[1,0,1]
	ds_write_b64 v222, v[102:103] offset:3952
	v_pk_mul_f32 v[102:103], v[78:79], v[100:101] op_sel:[0,1] op_sel_hi:[1,0]
	s_nop 0
	v_pk_fma_f32 v[100:101], v[100:101], v[74:75], v[102:103] op_sel_hi:[1,0,1]
	s_nop 0
	s_nop 0
	v_pk_mul_f32 v[102:103], v[118:119], v[100:101] op_sel:[1,1] op_sel_hi:[0,1] neg_hi:[0,1]
	v_pk_fma_f32 v[102:103], v[118:119], v[100:101], v[102:103] op_sel_hi:[1,0,1]
	ds_write_b64 v222, v[102:103] offset:4216
	v_pk_mul_f32 v[98:99], v[78:79], v[100:101] op_sel:[0,1] op_sel_hi:[1,0]
	s_nop 0
	v_pk_fma_f32 v[98:99], v[100:101], v[74:75], v[98:99] op_sel_hi:[1,0,1]
	s_nop 0
	s_nop 0
	v_pk_mul_f32 v[100:101], v[120:121], v[98:99] op_sel:[1,1] op_sel_hi:[0,1] neg_hi:[0,1]
	v_pk_fma_f32 v[100:101], v[120:121], v[98:99], v[100:101] op_sel_hi:[1,0,1]
	ds_write_b64 v222, v[100:101] offset:4480
	v_pk_mul_f32 v[100:101], v[78:79], v[98:99] op_sel:[0,1] op_sel_hi:[1,0]
	s_nop 0
	v_pk_fma_f32 v[98:99], v[98:99], v[74:75], v[100:101] op_sel_hi:[1,0,1]
	s_nop 0
	s_nop 0
	v_pk_mul_f32 v[100:101], v[142:143], v[98:99] op_sel:[1,1] op_sel_hi:[0,1] neg_hi:[0,1]
	v_pk_fma_f32 v[100:101], v[142:143], v[98:99], v[100:101] op_sel_hi:[1,0,1]
	ds_write_b64 v222, v[100:101] offset:4744
	v_pk_mul_f32 v[96:97], v[78:79], v[98:99] op_sel:[0,1] op_sel_hi:[1,0]
	s_nop 0
	v_pk_fma_f32 v[96:97], v[98:99], v[74:75], v[96:97] op_sel_hi:[1,0,1]
	s_nop 0
	s_nop 0
	v_pk_mul_f32 v[98:99], v[126:127], v[96:97] op_sel:[1,1] op_sel_hi:[0,1] neg_hi:[0,1]
	v_pk_fma_f32 v[98:99], v[126:127], v[96:97], v[98:99] op_sel_hi:[1,0,1]
	ds_write_b64 v222, v[98:99] offset:5008
	v_pk_mul_f32 v[98:99], v[78:79], v[96:97] op_sel:[0,1] op_sel_hi:[1,0]
	s_nop 0
	v_pk_fma_f32 v[96:97], v[96:97], v[74:75], v[98:99] op_sel_hi:[1,0,1]
	s_nop 0
	s_nop 0
	v_pk_mul_f32 v[98:99], v[136:137], v[96:97] op_sel:[1,1] op_sel_hi:[0,1] neg_hi:[0,1]
	v_pk_fma_f32 v[98:99], v[136:137], v[96:97], v[98:99] op_sel_hi:[1,0,1]
	ds_write_b64 v222, v[98:99] offset:5272
	v_pk_mul_f32 v[94:95], v[78:79], v[96:97] op_sel:[0,1] op_sel_hi:[1,0]
	s_nop 0
	v_pk_fma_f32 v[94:95], v[96:97], v[74:75], v[94:95] op_sel_hi:[1,0,1]
	s_nop 0
	s_nop 0
	v_pk_mul_f32 v[96:97], v[122:123], v[94:95] op_sel:[1,1] op_sel_hi:[0,1] neg_hi:[0,1]
	v_pk_fma_f32 v[96:97], v[122:123], v[94:95], v[96:97] op_sel_hi:[1,0,1]
	ds_write_b64 v222, v[96:97] offset:5536
	v_pk_mul_f32 v[96:97], v[78:79], v[94:95] op_sel:[0,1] op_sel_hi:[1,0]
	s_nop 0
	v_pk_fma_f32 v[94:95], v[94:95], v[74:75], v[96:97] op_sel_hi:[1,0,1]
	s_nop 0
	s_nop 0
	v_pk_mul_f32 v[96:97], v[138:139], v[94:95] op_sel:[1,1] op_sel_hi:[0,1] neg_hi:[0,1]
	v_pk_fma_f32 v[96:97], v[138:139], v[94:95], v[96:97] op_sel_hi:[1,0,1]
	ds_write_b64 v222, v[96:97] offset:5800
	v_pk_mul_f32 v[92:93], v[78:79], v[94:95] op_sel:[0,1] op_sel_hi:[1,0]
	s_nop 0
	v_pk_fma_f32 v[92:93], v[94:95], v[74:75], v[92:93] op_sel_hi:[1,0,1]
	s_nop 0
	s_nop 0
	v_pk_mul_f32 v[94:95], v[132:133], v[92:93] op_sel:[1,1] op_sel_hi:[0,1] neg_hi:[0,1]
	v_pk_fma_f32 v[94:95], v[132:133], v[92:93], v[94:95] op_sel_hi:[1,0,1]
	ds_write_b64 v222, v[94:95] offset:6064
	v_pk_mul_f32 v[94:95], v[78:79], v[92:93] op_sel:[0,1] op_sel_hi:[1,0]
	s_nop 0
	v_pk_fma_f32 v[92:93], v[92:93], v[74:75], v[94:95] op_sel_hi:[1,0,1]
	s_nop 0
	s_nop 0
	v_pk_mul_f32 v[94:95], v[82:83], v[92:93] op_sel:[1,1] op_sel_hi:[0,1] neg_hi:[0,1]
	v_pk_fma_f32 v[82:83], v[82:83], v[92:93], v[94:95] op_sel_hi:[1,0,1]
	ds_write_b64 v222, v[82:83] offset:6328
	v_pk_mul_f32 v[82:83], v[78:79], v[92:93] op_sel:[0,1] op_sel_hi:[1,0]
	s_nop 0
	v_pk_fma_f32 v[82:83], v[92:93], v[74:75], v[82:83] op_sel_hi:[1,0,1]
	s_nop 0
	s_nop 0
	v_pk_mul_f32 v[90:91], v[148:149], v[82:83] op_sel:[1,1] op_sel_hi:[0,1] neg_hi:[0,1]
	v_pk_fma_f32 v[90:91], v[148:149], v[82:83], v[90:91] op_sel_hi:[1,0,1]
	ds_write_b64 v222, v[90:91] offset:6592
	v_pk_mul_f32 v[90:91], v[78:79], v[82:83] op_sel:[0,1] op_sel_hi:[1,0]
	s_nop 0
	v_pk_fma_f32 v[82:83], v[82:83], v[74:75], v[90:91] op_sel_hi:[1,0,1]
	s_nop 0
	s_nop 0
	v_pk_mul_f32 v[90:91], v[76:77], v[82:83] op_sel:[1,1] op_sel_hi:[0,1] neg_hi:[0,1]
	v_pk_fma_f32 v[76:77], v[76:77], v[82:83], v[90:91] op_sel_hi:[1,0,1]
	ds_write_b64 v222, v[76:77] offset:6856
	v_pk_mul_f32 v[76:77], v[78:79], v[82:83] op_sel:[0,1] op_sel_hi:[1,0]
	s_nop 0
	v_pk_fma_f32 v[76:77], v[82:83], v[74:75], v[76:77] op_sel_hi:[1,0,1]
	s_nop 0
	s_nop 0
	v_pk_mul_f32 v[82:83], v[80:81], v[76:77] op_sel:[1,1] op_sel_hi:[0,1] neg_hi:[0,1]
	v_pk_fma_f32 v[80:81], v[80:81], v[76:77], v[82:83] op_sel_hi:[1,0,1]
	ds_write_b64 v222, v[80:81] offset:7120
	v_pk_mul_f32 v[80:81], v[78:79], v[76:77] op_sel:[0,1] op_sel_hi:[1,0]
	s_nop 0
	v_pk_fma_f32 v[76:77], v[76:77], v[74:75], v[80:81] op_sel_hi:[1,0,1]
	s_nop 0
	s_nop 0
	v_pk_mul_f32 v[80:81], v[68:69], v[76:77] op_sel:[1,1] op_sel_hi:[0,1] neg_hi:[0,1]
	v_pk_fma_f32 v[68:69], v[68:69], v[76:77], v[80:81] op_sel_hi:[1,0,1]
	ds_write_b64 v222, v[68:69] offset:7384
	v_pk_mul_f32 v[68:69], v[78:79], v[76:77] op_sel:[0,1] op_sel_hi:[1,0]
	s_nop 0
	v_pk_fma_f32 v[68:69], v[76:77], v[74:75], v[68:69] op_sel_hi:[1,0,1]
	s_nop 0
	s_nop 0
	v_pk_mul_f32 v[76:77], v[72:73], v[68:69] op_sel:[1,1] op_sel_hi:[0,1] neg_hi:[0,1]
	v_pk_fma_f32 v[72:73], v[72:73], v[68:69], v[76:77] op_sel_hi:[1,0,1]
	ds_write_b64 v222, v[72:73] offset:7648
	v_pk_mul_f32 v[72:73], v[78:79], v[68:69] op_sel:[0,1] op_sel_hi:[1,0]
	s_nop 0
	v_pk_fma_f32 v[68:69], v[68:69], v[74:75], v[72:73] op_sel_hi:[1,0,1]
	s_nop 0
	s_nop 0
	v_pk_mul_f32 v[72:73], v[66:67], v[68:69] op_sel:[1,1] op_sel_hi:[0,1] neg_hi:[0,1]
	v_pk_fma_f32 v[66:67], v[66:67], v[68:69], v[72:73] op_sel_hi:[1,0,1]
	ds_write_b64 v222, v[66:67] offset:7912
	v_pk_mul_f32 v[66:67], v[78:79], v[68:69] op_sel:[0,1] op_sel_hi:[1,0]
	s_nop 0
	v_pk_fma_f32 v[66:67], v[68:69], v[74:75], v[66:67] op_sel_hi:[1,0,1]
	s_nop 0
	s_nop 0
	v_pk_mul_f32 v[68:69], v[70:71], v[66:67] op_sel:[1,1] op_sel_hi:[0,1] neg_hi:[0,1]
	v_pk_fma_f32 v[66:67], v[70:71], v[66:67], v[68:69] op_sel_hi:[1,0,1]
	ds_write_b64 v222, v[66:67] offset:8176
	s_waitcnt lgkmcnt(0)
	s_barrier
	ds_read2_b64 v[66:69], v104 offset1:1
	ds_read2_b64 v[70:73], v104 offset0:2 offset1:3
	ds_read2_b64 v[74:77], v104 offset0:4 offset1:5
	ds_read2_b64 v[78:81], v104 offset0:6 offset1:7
	ds_read2_b64 v[82:85], v104 offset0:8 offset1:9
	ds_read2_b64 v[86:89], v104 offset0:10 offset1:11
	ds_read2_b64 v[90:93], v104 offset0:12 offset1:13
	ds_read2_b64 v[94:97], v104 offset0:14 offset1:15
	ds_read2_b64 v[98:101], v104 offset0:16 offset1:17
	ds_read2_b64 v[106:109], v104 offset0:18 offset1:19
	ds_read2_b64 v[110:113], v104 offset0:20 offset1:21
	ds_read2_b64 v[114:117], v104 offset0:22 offset1:23
	ds_read2_b64 v[118:121], v104 offset0:24 offset1:25
	ds_read2_b64 v[122:125], v104 offset0:26 offset1:27
	ds_read2_b64 v[126:129], v104 offset0:28 offset1:29
	ds_read2_b64 v[130:133], v104 offset0:30 offset1:31
	s_waitcnt lgkmcnt(7)
	v_pk_add_f32 v[102:103], v[66:67], v[98:99]
	v_pk_add_f32 v[66:67], v[66:67], v[98:99] neg_lo:[0,1] neg_hi:[0,1]
	v_pk_add_f32 v[98:99], v[68:69], v[100:101]
	v_pk_add_f32 v[68:69], v[68:69], v[100:101] neg_lo:[0,1] neg_hi:[0,1]
	global_load_dwordx2 v[134:135], v[2:3], off
	global_load_dwordx2 v[136:137], v[4:5], off
	global_load_dwordx2 v[138:139], v[6:7], off
	v_pk_mul_f32 v[100:101], v[68:69], s[18:19]
	global_load_dwordx2 v[148:149], v[14:15], off
	global_load_dwordx2 v[154:155], v[16:17], off
	v_pk_fma_f32 v[68:69], v[68:69], s[20:21], v[100:101] op_sel:[0,0,1] op_sel_hi:[1,0,0]
	s_waitcnt lgkmcnt(6)
	v_pk_add_f32 v[100:101], v[70:71], v[106:107]
	v_pk_add_f32 v[70:71], v[70:71], v[106:107] neg_lo:[0,1] neg_hi:[0,1]
	global_load_dwordx2 v[158:159], v[18:19], off
	v_pk_mul_f32 v[106:107], v[70:71], s[4:5]
	global_load_dwordx2 v[160:161], v[28:29], off
	global_load_dwordx2 v[164:165], v[32:33], off
	v_pk_fma_f32 v[70:71], v[70:71], s[6:7], v[106:107] op_sel:[0,0,1] op_sel_hi:[1,0,0]
	v_pk_add_f32 v[106:107], v[72:73], v[108:109]
	v_pk_add_f32 v[72:73], v[72:73], v[108:109] neg_lo:[0,1] neg_hi:[0,1]
	global_load_dwordx2 v[168:169], v[36:37], off
	v_pk_mul_f32 v[108:109], v[72:73], s[22:23]
	global_load_dwordx2 v[172:173], v[44:45], off
	v_pk_fma_f32 v[72:73], v[72:73], s[24:25], v[108:109] op_sel:[0,0,1] op_sel_hi:[1,0,0]
	s_waitcnt lgkmcnt(5)
	v_pk_add_f32 v[108:109], v[74:75], v[110:111]
	v_pk_add_f32 v[74:75], v[74:75], v[110:111] neg_lo:[0,1] neg_hi:[0,1]
	global_load_dwordx2 v[174:175], v[52:53], off
	v_pk_mul_f32 v[110:111], v[74:75], s[8:9]
	global_load_dwordx2 v[176:177], v[60:61], off
	v_pk_fma_f32 v[74:75], v[74:75], s[10:11], v[110:111] op_sel:[0,0,1] op_sel_hi:[1,0,0]
	v_pk_add_f32 v[110:111], v[76:77], v[112:113]
	v_pk_add_f32 v[76:77], v[76:77], v[112:113] neg_lo:[0,1] neg_hi:[0,1]
	s_nop 0
	v_pk_mul_f32 v[112:113], v[76:77], s[26:27]
	s_nop 0
	v_pk_fma_f32 v[76:77], v[76:77], s[0:1], v[112:113] op_sel:[0,0,1] op_sel_hi:[1,0,0]
	s_waitcnt lgkmcnt(4)
	v_pk_add_f32 v[112:113], v[78:79], v[114:115]
	v_pk_add_f32 v[78:79], v[78:79], v[114:115] neg_lo:[0,1] neg_hi:[0,1]
	s_nop 0
	v_pk_mul_f32 v[114:115], v[78:79], s[12:13]
	s_nop 0
	v_pk_fma_f32 v[78:79], v[78:79], s[14:15], v[114:115] op_sel:[0,0,1] op_sel_hi:[1,0,0]
	v_pk_add_f32 v[114:115], v[80:81], v[116:117]
	v_pk_add_f32 v[80:81], v[80:81], v[116:117] neg_lo:[0,1] neg_hi:[0,1]
	s_nop 0
	v_pk_mul_f32 v[116:117], v[80:81], s[34:35]
	s_nop 0
	v_pk_fma_f32 v[80:81], v[80:81], s[48:49], v[116:117] op_sel:[0,0,1] op_sel_hi:[1,0,0]
	s_waitcnt lgkmcnt(3)
	v_pk_add_f32 v[116:117], v[82:83], v[118:119]
	v_pk_add_f32 v[118:119], v[82:83], v[118:119] op_sel:[1,1] op_sel_hi:[0,0] neg_lo:[0,1] neg_hi:[1,0]
	s_nop 0
	v_pk_add_f32 v[82:83], v[84:85], v[120:121]
	v_pk_add_f32 v[84:85], v[84:85], v[120:121] neg_lo:[0,1] neg_hi:[0,1]
	s_nop 0
	v_pk_mul_f32 v[120:121], v[84:85], s[34:35]
	s_nop 0
	v_pk_fma_f32 v[84:85], v[84:85], s[18:19], v[120:121] op_sel:[0,0,1] op_sel_hi:[1,0,0]
	s_waitcnt lgkmcnt(2)
	v_pk_add_f32 v[120:121], v[86:87], v[122:123]
	v_pk_add_f32 v[86:87], v[86:87], v[122:123] neg_lo:[0,1] neg_hi:[0,1]
	s_nop 0
	v_pk_mul_f32 v[122:123], v[86:87], s[12:13]
	s_nop 0
	v_pk_fma_f32 v[86:87], v[86:87], s[4:5], v[122:123] op_sel:[0,0,1] op_sel_hi:[1,0,0]
	v_pk_add_f32 v[122:123], v[88:89], v[124:125]
	v_pk_add_f32 v[88:89], v[88:89], v[124:125] neg_lo:[0,1] neg_hi:[0,1]
	s_nop 0
	v_pk_mul_f32 v[124:125], v[88:89], s[26:27]
	s_nop 0
	v_pk_fma_f32 v[88:89], v[88:89], s[22:23], v[124:125] op_sel:[0,0,1] op_sel_hi:[1,0,0]
	s_waitcnt lgkmcnt(1)
	v_pk_add_f32 v[124:125], v[90:91], v[126:127]
	v_pk_add_f32 v[90:91], v[90:91], v[126:127] neg_lo:[0,1] neg_hi:[0,1]
	s_nop 0
	v_pk_mul_f32 v[126:127], v[90:91], s[8:9]
	s_nop 0
	v_pk_fma_f32 v[90:91], v[90:91], s[8:9], v[126:127] op_sel:[0,0,1] op_sel_hi:[1,0,0]
	v_pk_add_f32 v[126:127], v[92:93], v[128:129]
	v_pk_add_f32 v[92:93], v[92:93], v[128:129] neg_lo:[0,1] neg_hi:[0,1]
	s_nop 0
	v_pk_mul_f32 v[128:129], v[92:93], s[22:23]
	s_nop 0
	v_pk_fma_f32 v[92:93], v[92:93], s[26:27], v[128:129] op_sel:[0,0,1] op_sel_hi:[1,0,0]
	s_waitcnt lgkmcnt(0)
	v_pk_add_f32 v[128:129], v[94:95], v[130:131]
	v_pk_add_f32 v[94:95], v[94:95], v[130:131] neg_lo:[0,1] neg_hi:[0,1]
	s_nop 0
	v_pk_mul_f32 v[130:131], v[94:95], s[4:5]
	s_nop 0
	v_pk_fma_f32 v[94:95], v[94:95], s[12:13], v[130:131] op_sel:[0,0,1] op_sel_hi:[1,0,0]
	v_pk_add_f32 v[130:131], v[96:97], v[132:133]
	v_pk_add_f32 v[96:97], v[96:97], v[132:133] neg_lo:[0,1] neg_hi:[0,1]
	s_nop 0
	v_pk_mul_f32 v[132:133], v[96:97], s[18:19]
	s_nop 0
	v_pk_fma_f32 v[96:97], v[96:97], s[34:35], v[132:133] op_sel:[0,0,1] op_sel_hi:[1,0,0]
	v_pk_add_f32 v[132:133], v[102:103], v[116:117]
	v_pk_add_f32 v[102:103], v[102:103], v[116:117] neg_lo:[0,1] neg_hi:[0,1]
	v_pk_add_f32 v[116:117], v[98:99], v[82:83]
	v_pk_add_f32 v[82:83], v[98:99], v[82:83] neg_lo:[0,1] neg_hi:[0,1]
	s_nop 0
	v_pk_mul_f32 v[98:99], v[82:83], s[4:5]
	s_nop 0
	v_pk_fma_f32 v[82:83], v[82:83], s[6:7], v[98:99] op_sel:[0,0,1] op_sel_hi:[1,0,0]
	v_pk_add_f32 v[98:99], v[100:101], v[120:121]
	v_pk_add_f32 v[100:101], v[100:101], v[120:121] neg_lo:[0,1] neg_hi:[0,1]
	s_nop 0
	v_pk_mul_f32 v[120:121], v[100:101], s[8:9]
	s_nop 0
	v_pk_fma_f32 v[100:101], v[100:101], s[10:11], v[120:121] op_sel:[0,0,1] op_sel_hi:[1,0,0]
	v_pk_add_f32 v[120:121], v[106:107], v[122:123]
	v_pk_add_f32 v[106:107], v[106:107], v[122:123] neg_lo:[0,1] neg_hi:[0,1]
	s_nop 0
	v_pk_mul_f32 v[122:123], v[106:107], s[12:13]
	s_nop 0
	v_pk_fma_f32 v[106:107], v[106:107], s[14:15], v[122:123] op_sel:[0,0,1] op_sel_hi:[1,0,0]
	v_pk_add_f32 v[122:123], v[108:109], v[124:125]
	v_pk_add_f32 v[124:125], v[108:109], v[124:125] op_sel:[1,1] op_sel_hi:[0,0] neg_lo:[0,1] neg_hi:[1,0]
	s_nop 0
	v_pk_add_f32 v[108:109], v[110:111], v[126:127]
	v_pk_add_f32 v[110:111], v[110:111], v[126:127] neg_lo:[0,1] neg_hi:[0,1]
	s_nop 0
	v_pk_mul_f32 v[126:127], v[110:111], s[12:13]
	s_nop 0
	v_pk_fma_f32 v[110:111], v[110:111], s[4:5], v[126:127] op_sel:[0,0,1] op_sel_hi:[1,0,0]
	v_pk_add_f32 v[126:127], v[112:113], v[128:129]
	v_pk_add_f32 v[112:113], v[112:113], v[128:129] neg_lo:[0,1] neg_hi:[0,1]
	s_nop 0
	v_pk_mul_f32 v[128:129], v[112:113], s[8:9]
	s_nop 0
	v_pk_fma_f32 v[112:113], v[112:113], s[8:9], v[128:129] op_sel:[0,0,1] op_sel_hi:[1,0,0]
	v_pk_add_f32 v[128:129], v[114:115], v[130:131]
	v_pk_add_f32 v[114:115], v[114:115], v[130:131] neg_lo:[0,1] neg_hi:[0,1]
	s_nop 0
	v_pk_mul_f32 v[130:131], v[114:115], s[4:5]
	s_nop 0
	v_pk_fma_f32 v[114:115], v[114:115], s[12:13], v[130:131] op_sel:[0,0,1] op_sel_hi:[1,0,0]
	v_pk_add_f32 v[130:131], v[66:67], v[118:119]
	v_pk_add_f32 v[66:67], v[66:67], v[118:119] neg_lo:[0,1] neg_hi:[0,1]
	v_pk_add_f32 v[118:119], v[68:69], v[84:85]
	v_pk_add_f32 v[68:69], v[68:69], v[84:85] neg_lo:[0,1] neg_hi:[0,1]
	s_nop 0
	v_pk_mul_f32 v[84:85], v[68:69], s[4:5]
	s_nop 0
	v_pk_fma_f32 v[68:69], v[68:69], s[6:7], v[84:85] op_sel:[0,0,1] op_sel_hi:[1,0,0]
	v_pk_add_f32 v[84:85], v[70:71], v[86:87]
	v_pk_add_f32 v[70:71], v[70:71], v[86:87] neg_lo:[0,1] neg_hi:[0,1]
	s_nop 0
	v_pk_mul_f32 v[86:87], v[70:71], s[8:9]
	s_nop 0
	v_pk_fma_f32 v[70:71], v[70:71], s[10:11], v[86:87] op_sel:[0,0,1] op_sel_hi:[1,0,0]
	v_pk_add_f32 v[86:87], v[72:73], v[88:89]
	v_pk_add_f32 v[72:73], v[72:73], v[88:89] neg_lo:[0,1] neg_hi:[0,1]
	s_nop 0
	v_pk_mul_f32 v[88:89], v[72:73], s[12:13]
	s_nop 0
	v_pk_fma_f32 v[72:73], v[72:73], s[14:15], v[88:89] op_sel:[0,0,1] op_sel_hi:[1,0,0]
	v_pk_add_f32 v[88:89], v[74:75], v[90:91]
	v_pk_add_f32 v[90:91], v[74:75], v[90:91] op_sel:[1,1] op_sel_hi:[0,0] neg_lo:[0,1] neg_hi:[1,0]
	s_mov_b32 s15, s4
	v_pk_add_f32 v[74:75], v[76:77], v[92:93]
	v_pk_add_f32 v[76:77], v[76:77], v[92:93] neg_lo:[0,1] neg_hi:[0,1]
	s_nop 0
	v_pk_mul_f32 v[92:93], v[76:77], s[12:13]
	s_nop 0
	v_pk_fma_f32 v[76:77], v[76:77], s[4:5], v[92:93] op_sel:[0,0,1] op_sel_hi:[1,0,0]
	v_pk_add_f32 v[92:93], v[78:79], v[94:95]
	v_pk_add_f32 v[78:79], v[78:79], v[94:95] neg_lo:[0,1] neg_hi:[0,1]
	s_nop 0
	v_pk_mul_f32 v[94:95], v[78:79], s[8:9]
	s_nop 0
	v_pk_fma_f32 v[78:79], v[78:79], s[8:9], v[94:95] op_sel:[0,0,1] op_sel_hi:[1,0,0]
	v_pk_add_f32 v[94:95], v[80:81], v[96:97]
	v_pk_add_f32 v[80:81], v[80:81], v[96:97] neg_lo:[0,1] neg_hi:[0,1]
	s_nop 0
	v_pk_mul_f32 v[96:97], v[80:81], s[4:5]
	s_nop 0
	v_pk_fma_f32 v[80:81], v[80:81], s[12:13], v[96:97] op_sel:[0,0,1] op_sel_hi:[1,0,0]
	v_pk_add_f32 v[96:97], v[132:133], v[122:123]
	v_pk_add_f32 v[122:123], v[132:133], v[122:123] neg_lo:[0,1] neg_hi:[0,1]
	v_pk_add_f32 v[132:133], v[116:117], v[108:109]
	v_pk_add_f32 v[108:109], v[116:117], v[108:109] neg_lo:[0,1] neg_hi:[0,1]
	s_nop 0
	v_pk_mul_f32 v[116:117], v[108:109], s[8:9]
	s_nop 0
	v_pk_fma_f32 v[108:109], v[108:109], s[10:11], v[116:117] op_sel:[0,0,1] op_sel_hi:[1,0,0]
	v_pk_add_f32 v[116:117], v[98:99], v[126:127]
	v_pk_add_f32 v[126:127], v[98:99], v[126:127] op_sel:[1,1] op_sel_hi:[0,0] neg_lo:[0,1] neg_hi:[1,0]
	s_nop 0
	v_pk_add_f32 v[98:99], v[120:121], v[128:129]
	v_pk_add_f32 v[120:121], v[120:121], v[128:129] neg_lo:[0,1] neg_hi:[0,1]
	s_nop 0
	v_pk_mul_f32 v[128:129], v[120:121], s[8:9]
	s_nop 0
	v_pk_fma_f32 v[120:121], v[120:121], s[8:9], v[128:129] op_sel:[0,0,1] op_sel_hi:[1,0,0]
	v_pk_add_f32 v[128:129], v[102:103], v[124:125]
	v_pk_add_f32 v[102:103], v[102:103], v[124:125] neg_lo:[0,1] neg_hi:[0,1]
	v_pk_add_f32 v[124:125], v[82:83], v[110:111]
	v_pk_add_f32 v[82:83], v[82:83], v[110:111] neg_lo:[0,1] neg_hi:[0,1]
	s_nop 0
	v_pk_mul_f32 v[110:111], v[82:83], s[8:9]
	s_nop 0
	v_pk_fma_f32 v[82:83], v[82:83], s[10:11], v[110:111] op_sel:[0,0,1] op_sel_hi:[1,0,0]
	v_pk_add_f32 v[110:111], v[100:101], v[112:113]
	v_pk_add_f32 v[112:113], v[100:101], v[112:113] op_sel:[1,1] op_sel_hi:[0,0] neg_lo:[0,1] neg_hi:[1,0]
	s_nop 0
	v_pk_add_f32 v[100:101], v[106:107], v[114:115]
	v_pk_add_f32 v[106:107], v[106:107], v[114:115] neg_lo:[0,1] neg_hi:[0,1]
	s_nop 0
	v_pk_mul_f32 v[114:115], v[106:107], s[8:9]
	s_nop 0
	v_pk_fma_f32 v[106:107], v[106:107], s[8:9], v[114:115] op_sel:[0,0,1] op_sel_hi:[1,0,0]
	v_pk_add_f32 v[114:115], v[130:131], v[88:89]
	v_pk_add_f32 v[88:89], v[130:131], v[88:89] neg_lo:[0,1] neg_hi:[0,1]
	v_pk_add_f32 v[130:131], v[118:119], v[74:75]
	v_pk_add_f32 v[74:75], v[118:119], v[74:75] neg_lo:[0,1] neg_hi:[0,1]
	s_nop 0
	v_pk_mul_f32 v[118:119], v[74:75], s[8:9]
	s_nop 0
	v_pk_fma_f32 v[74:75], v[74:75], s[10:11], v[118:119] op_sel:[0,0,1] op_sel_hi:[1,0,0]
	v_pk_add_f32 v[118:119], v[84:85], v[92:93]
	v_pk_add_f32 v[92:93], v[84:85], v[92:93] op_sel:[1,1] op_sel_hi:[0,0] neg_lo:[0,1] neg_hi:[1,0]
	s_nop 0
	v_pk_add_f32 v[84:85], v[86:87], v[94:95]
	v_pk_add_f32 v[86:87], v[86:87], v[94:95] neg_lo:[0,1] neg_hi:[0,1]
	v_pk_add_f32 v[140:141], v[88:89], v[92:93]
	v_pk_mul_f32 v[94:95], v[86:87], s[8:9]
	v_pk_add_f32 v[88:89], v[88:89], v[92:93] neg_lo:[0,1] neg_hi:[0,1]
	v_pk_fma_f32 v[86:87], v[86:87], s[8:9], v[94:95] op_sel:[0,0,1] op_sel_hi:[1,0,0]
	v_pk_add_f32 v[94:95], v[66:67], v[90:91]
	v_pk_add_f32 v[66:67], v[66:67], v[90:91] neg_lo:[0,1] neg_hi:[0,1]
	v_pk_add_f32 v[90:91], v[68:69], v[76:77]
	v_pk_add_f32 v[68:69], v[68:69], v[76:77] neg_lo:[0,1] neg_hi:[0,1]
	v_pk_add_f32 v[92:93], v[74:75], v[86:87]
	v_pk_mul_f32 v[76:77], v[68:69], s[8:9]
	v_pk_add_f32 v[142:143], v[74:75], v[86:87] op_sel:[1,1] op_sel_hi:[0,0] neg_lo:[0,1] neg_hi:[1,0]
	v_pk_fma_f32 v[68:69], v[68:69], s[10:11], v[76:77] op_sel:[0,0,1] op_sel_hi:[1,0,0]
	v_pk_add_f32 v[76:77], v[70:71], v[78:79]
	v_pk_add_f32 v[78:79], v[70:71], v[78:79] op_sel:[1,1] op_sel_hi:[0,0] neg_lo:[0,1] neg_hi:[1,0]
	global_load_dwordx2 v[86:87], v[10:11], off
	v_pk_add_f32 v[70:71], v[72:73], v[80:81]
	v_pk_add_f32 v[72:73], v[72:73], v[80:81] neg_lo:[0,1] neg_hi:[0,1]
	v_pk_mul_f32 v[80:81], v[72:73], s[8:9]
	v_pk_fma_f32 v[72:73], v[72:73], s[8:9], v[80:81] op_sel:[0,0,1] op_sel_hi:[1,0,0]
	v_pk_add_f32 v[80:81], v[96:97], v[116:117]
	v_pk_add_f32 v[96:97], v[96:97], v[116:117] neg_lo:[0,1] neg_hi:[0,1]
	v_pk_add_f32 v[116:117], v[132:133], v[98:99]
	v_pk_add_f32 v[132:133], v[132:133], v[98:99] op_sel:[1,1] op_sel_hi:[0,0] neg_lo:[0,1] neg_hi:[1,0]
	v_pk_add_f32 v[74:75], v[94:95], v[76:77]
	v_pk_add_f32 v[98:99], v[122:123], v[126:127]
	v_pk_add_f32 v[122:123], v[122:123], v[126:127] neg_lo:[0,1] neg_hi:[0,1]
	v_pk_add_f32 v[126:127], v[108:109], v[120:121]
	v_pk_add_f32 v[120:121], v[108:109], v[120:121] op_sel:[1,1] op_sel_hi:[0,0] neg_lo:[0,1] neg_hi:[1,0]
	v_pk_add_f32 v[76:77], v[94:95], v[76:77] neg_lo:[0,1] neg_hi:[0,1]
	v_pk_add_f32 v[108:109], v[128:129], v[110:111]
	v_pk_add_f32 v[110:111], v[128:129], v[110:111] neg_lo:[0,1] neg_hi:[0,1]
	v_pk_add_f32 v[128:129], v[124:125], v[100:101]
	v_pk_add_f32 v[124:125], v[124:125], v[100:101] op_sel:[1,1] op_sel_hi:[0,0] neg_lo:[0,1] neg_hi:[1,0]
	global_load_dwordx2 v[94:95], v[12:13], off
	v_pk_add_f32 v[100:101], v[102:103], v[112:113]
	v_pk_add_f32 v[102:103], v[102:103], v[112:113] neg_lo:[0,1] neg_hi:[0,1]
	v_pk_add_f32 v[112:113], v[82:83], v[106:107]
	v_pk_add_f32 v[106:107], v[82:83], v[106:107] op_sel:[1,1] op_sel_hi:[0,0] neg_lo:[0,1] neg_hi:[1,0]
	v_pk_add_f32 v[146:147], v[66:67], v[78:79]
	v_pk_add_f32 v[82:83], v[114:115], v[118:119]
	v_pk_add_f32 v[114:115], v[114:115], v[118:119] neg_lo:[0,1] neg_hi:[0,1]
	v_pk_add_f32 v[118:119], v[130:131], v[84:85]
	v_pk_add_f32 v[130:131], v[130:131], v[84:85] op_sel:[1,1] op_sel_hi:[0,0] neg_lo:[0,1] neg_hi:[1,0]
	v_pk_add_f32 v[78:79], v[66:67], v[78:79] neg_lo:[0,1] neg_hi:[0,1]
	global_load_dwordx2 v[84:85], v[8:9], off
	v_pk_add_f32 v[152:153], v[68:69], v[72:73] op_sel:[1,1] op_sel_hi:[0,0] neg_lo:[0,1] neg_hi:[1,0]
	v_pk_add_f32 v[150:151], v[68:69], v[72:73]
	v_pk_add_f32 v[156:157], v[80:81], v[116:117]
	v_pk_add_f32 v[80:81], v[80:81], v[116:117] neg_lo:[0,1] neg_hi:[0,1]
	v_pk_add_f32 v[116:117], v[96:97], v[132:133]
	v_pk_add_f32 v[68:69], v[96:97], v[132:133] neg_lo:[0,1] neg_hi:[0,1]
	v_pk_add_f32 v[96:97], v[98:99], v[126:127]
	v_pk_add_f32 v[98:99], v[98:99], v[126:127] neg_lo:[0,1] neg_hi:[0,1]
	v_pk_add_f32 v[126:127], v[122:123], v[120:121]
	v_pk_add_f32 v[66:67], v[122:123], v[120:121] neg_lo:[0,1] neg_hi:[0,1]
	global_load_dwordx2 v[120:121], v[20:21], off
	v_pk_add_f32 v[122:123], v[108:109], v[128:129]
	v_pk_add_f32 v[108:109], v[108:109], v[128:129] neg_lo:[0,1] neg_hi:[0,1]
	v_pk_add_f32 v[128:129], v[110:111], v[124:125]
	v_pk_add_f32 v[72:73], v[110:111], v[124:125] neg_lo:[0,1] neg_hi:[0,1]
	global_load_dwordx2 v[110:111], v[22:23], off
	v_pk_add_f32 v[144:145], v[90:91], v[70:71]
	v_pk_add_f32 v[90:91], v[90:91], v[70:71] op_sel:[1,1] op_sel_hi:[0,0] neg_lo:[0,1] neg_hi:[1,0]
	v_pk_add_f32 v[124:125], v[100:101], v[112:113]
	v_pk_add_f32 v[100:101], v[100:101], v[112:113] neg_lo:[0,1] neg_hi:[0,1]
	v_pk_add_f32 v[112:113], v[102:103], v[106:107]
	v_pk_add_f32 v[70:71], v[102:103], v[106:107] neg_lo:[0,1] neg_hi:[0,1]
	global_load_dwordx2 v[102:103], v[24:25], off
	v_pk_add_f32 v[106:107], v[82:83], v[118:119]
	v_pk_add_f32 v[82:83], v[82:83], v[118:119] neg_lo:[0,1] neg_hi:[0,1]
	v_pk_add_f32 v[118:119], v[114:115], v[130:131]
	v_pk_add_f32 v[114:115], v[114:115], v[130:131] neg_lo:[0,1] neg_hi:[0,1]
	global_load_dwordx2 v[130:131], v[26:27], off
	v_pk_add_f32 v[162:163], v[76:77], v[90:91]
	v_pk_add_f32 v[76:77], v[76:77], v[90:91] neg_lo:[0,1] neg_hi:[0,1]
	v_pk_add_f32 v[90:91], v[146:147], v[150:151]
	v_pk_add_f32 v[146:147], v[146:147], v[150:151] neg_lo:[0,1] neg_hi:[0,1]
	v_pk_add_f32 v[150:151], v[78:79], v[152:153]
	v_pk_add_f32 v[78:79], v[78:79], v[152:153] neg_lo:[0,1] neg_hi:[0,1]
	global_load_dwordx2 v[152:153], v[34:35], off
	s_waitcnt vmcnt(19)
	v_pk_mul_f32 v[166:167], v[156:157], v[134:135] op_sel:[1,1] op_sel_hi:[0,1] neg_lo:[0,1]
	v_pk_add_f32 v[132:133], v[140:141], v[92:93]
	v_pk_fma_f32 v[134:135], v[156:157], v[134:135], v[166:167] op_sel_hi:[1,0,1]
	s_waitcnt vmcnt(18)
	global_load_dwordx2 v[166:167], v[38:39], off
	v_pk_mul_f32 v[156:157], v[106:107], v[136:137] op_sel:[1,1] op_sel_hi:[0,1] neg_lo:[0,1]
	v_pk_add_f32 v[92:93], v[140:141], v[92:93] neg_lo:[0,1] neg_hi:[0,1]
	v_pk_fma_f32 v[106:107], v[106:107], v[136:137], v[156:157] op_sel_hi:[1,0,1]
	s_waitcnt vmcnt(18)
	global_load_dwordx2 v[156:157], v[40:41], off
	v_pk_mul_f32 v[136:137], v[122:123], v[138:139] op_sel:[1,1] op_sel_hi:[0,1] neg_lo:[0,1]
	v_pk_add_f32 v[140:141], v[88:89], v[142:143]
	v_pk_fma_f32 v[122:123], v[122:123], v[138:139], v[136:137] op_sel_hi:[1,0,1]
	global_load_dwordx2 v[136:137], v[42:43], off
	v_pk_add_f32 v[88:89], v[88:89], v[142:143] neg_lo:[0,1] neg_hi:[0,1]
	v_pk_add_f32 v[142:143], v[74:75], v[144:145]
	v_pk_add_f32 v[74:75], v[74:75], v[144:145] neg_lo:[0,1] neg_hi:[0,1]
	global_load_dwordx2 v[144:145], v[30:31], off
	s_mov_b32 s11, s8
	s_waitcnt vmcnt(9)
	v_pk_mul_f32 v[138:139], v[142:143], v[84:85] op_sel:[1,1] op_sel_hi:[0,1] neg_lo:[0,1]
	s_nop 0
	v_pk_fma_f32 v[84:85], v[142:143], v[84:85], v[138:139] op_sel_hi:[1,0,1]
	global_load_dwordx2 v[142:143], v[46:47], off
	v_pk_mul_f32 v[138:139], v[96:97], v[86:87] op_sel:[1,1] op_sel_hi:[0,1] neg_lo:[0,1]
	s_nop 0
	v_pk_fma_f32 v[86:87], v[96:97], v[86:87], v[138:139] op_sel_hi:[1,0,1]
	global_load_dwordx2 v[138:139], v[48:49], off
	v_pk_mul_f32 v[96:97], v[132:133], v[94:95] op_sel:[1,1] op_sel_hi:[0,1] neg_lo:[0,1]
	s_nop 0
	v_pk_fma_f32 v[94:95], v[132:133], v[94:95], v[96:97] op_sel_hi:[1,0,1]
	global_load_dwordx2 v[96:97], v[50:51], off
	v_pk_mul_f32 v[132:133], v[124:125], v[148:149] op_sel:[1,1] op_sel_hi:[0,1] neg_lo:[0,1]
	s_nop 0
	v_pk_fma_f32 v[124:125], v[124:125], v[148:149], v[132:133] op_sel_hi:[1,0,1]
	global_load_dwordx2 v[148:149], v[54:55], off
	v_pk_mul_f32 v[132:133], v[90:91], v[154:155] op_sel:[1,1] op_sel_hi:[0,1] neg_lo:[0,1]
	s_nop 0
	v_pk_fma_f32 v[90:91], v[90:91], v[154:155], v[132:133] op_sel_hi:[1,0,1]
	global_load_dwordx2 v[154:155], v[56:57], off
	v_pk_mul_f32 v[132:133], v[116:117], v[158:159] op_sel:[1,1] op_sel_hi:[0,1] neg_lo:[0,1]
	v_pk_fma_f32 v[116:117], v[116:117], v[158:159], v[132:133] op_sel_hi:[1,0,1]
	global_load_dwordx2 v[132:133], v[58:59], off
	s_waitcnt vmcnt(14)
	v_pk_mul_f32 v[158:159], v[118:119], v[120:121] op_sel:[1,1] op_sel_hi:[0,1] neg_lo:[0,1]
	v_pk_fma_f32 v[118:119], v[118:119], v[120:121], v[158:159] op_sel_hi:[1,0,1]
	s_waitcnt vmcnt(13)
	global_load_dwordx2 v[158:159], v[62:63], off
	v_pk_mul_f32 v[120:121], v[128:129], v[110:111] op_sel:[1,1] op_sel_hi:[0,1] neg_lo:[0,1]
	v_pk_fma_f32 v[110:111], v[128:129], v[110:111], v[120:121] op_sel_hi:[1,0,1]
	global_load_dwordx2 v[128:129], v[64:65], off
	s_waitcnt vmcnt(14)
	v_pk_mul_f32 v[120:121], v[162:163], v[102:103] op_sel:[1,1] op_sel_hi:[0,1] neg_lo:[0,1]
	v_mov_b32 v0, 0
	s_nop 0
	v_pk_fma_f32 v[102:103], v[162:163], v[102:103], v[120:121] op_sel_hi:[1,0,1]
	s_waitcnt vmcnt(13)
	v_pk_mul_f32 v[120:121], v[126:127], v[130:131] op_sel:[1,1] op_sel_hi:[0,1] neg_lo:[0,1]
	v_pk_fma_f32 v[120:121], v[126:127], v[130:131], v[120:121] op_sel_hi:[1,0,1]
	v_pk_mul_f32 v[126:127], v[140:141], v[160:161] op_sel:[1,1] op_sel_hi:[0,1] neg_lo:[0,1]
	v_pk_fma_f32 v[126:127], v[140:141], v[160:161], v[126:127] op_sel_hi:[1,0,1]
	s_waitcnt vmcnt(12)
	v_pk_mul_f32 v[140:141], v[80:81], v[152:153] op_sel:[1,1] op_sel_hi:[0,1] neg_lo:[0,1]
	v_pk_fma_f32 v[80:81], v[80:81], v[152:153], v[140:141] op_sel_hi:[1,0,1]
	v_pk_mul_f32 v[140:141], v[82:83], v[168:169] op_sel:[1,1] op_sel_hi:[0,1] neg_lo:[0,1]
	v_pk_fma_f32 v[82:83], v[82:83], v[168:169], v[140:141] op_sel_hi:[1,0,1]
	s_waitcnt vmcnt(11)
	v_pk_mul_f32 v[140:141], v[108:109], v[166:167] op_sel:[1,1] op_sel_hi:[0,1] neg_lo:[0,1]
	v_pk_fma_f32 v[108:109], v[108:109], v[166:167], v[140:141] op_sel_hi:[1,0,1]
	s_waitcnt vmcnt(10)
	v_pk_mul_f32 v[140:141], v[74:75], v[156:157] op_sel:[1,1] op_sel_hi:[0,1] neg_lo:[0,1]
	v_pk_fma_f32 v[74:75], v[74:75], v[156:157], v[140:141] op_sel_hi:[1,0,1]
	s_waitcnt vmcnt(9)
	v_pk_mul_f32 v[140:141], v[98:99], v[136:137] op_sel:[1,1] op_sel_hi:[0,1] neg_lo:[0,1]
	v_pk_fma_f32 v[98:99], v[98:99], v[136:137], v[140:141] op_sel_hi:[1,0,1]
	v_pk_mul_f32 v[136:137], v[92:93], v[172:173] op_sel:[1,1] op_sel_hi:[0,1] neg_lo:[0,1]
	v_pk_fma_f32 v[92:93], v[92:93], v[172:173], v[136:137] op_sel_hi:[1,0,1]
	s_waitcnt vmcnt(8)
	v_pk_mul_f32 v[130:131], v[112:113], v[144:145] op_sel:[1,1] op_sel_hi:[0,1] neg_lo:[0,1]
	v_pk_fma_f32 v[112:113], v[112:113], v[144:145], v[130:131] op_sel_hi:[1,0,1]
	s_waitcnt vmcnt(7)
	v_pk_mul_f32 v[136:137], v[100:101], v[142:143] op_sel:[1,1] op_sel_hi:[0,1] neg_lo:[0,1]
	v_pk_fma_f32 v[100:101], v[100:101], v[142:143], v[136:137] op_sel_hi:[1,0,1]
	s_waitcnt vmcnt(6)
	v_pk_mul_f32 v[136:137], v[146:147], v[138:139] op_sel:[1,1] op_sel_hi:[0,1] neg_lo:[0,1]
	v_pk_fma_f32 v[136:137], v[146:147], v[138:139], v[136:137] op_sel_hi:[1,0,1]
	s_waitcnt vmcnt(5)
	v_pk_mul_f32 v[138:139], v[68:69], v[96:97] op_sel:[1,1] op_sel_hi:[0,1] neg_lo:[0,1]
	v_pk_fma_f32 v[68:69], v[68:69], v[96:97], v[138:139] op_sel_hi:[1,0,1]
	v_pk_mul_f32 v[96:97], v[114:115], v[174:175] op_sel:[1,1] op_sel_hi:[0,1] neg_lo:[0,1]
	v_pk_fma_f32 v[96:97], v[114:115], v[174:175], v[96:97] op_sel_hi:[1,0,1]
	s_waitcnt vmcnt(4)
	v_pk_mul_f32 v[114:115], v[72:73], v[148:149] op_sel:[1,1] op_sel_hi:[0,1] neg_lo:[0,1]
	v_pk_fma_f32 v[72:73], v[72:73], v[148:149], v[114:115] op_sel_hi:[1,0,1]
	v_pk_mul_f32 v[130:131], v[150:151], v[164:165] op_sel:[1,1] op_sel_hi:[0,1] neg_lo:[0,1]
	s_waitcnt vmcnt(3)
	v_pk_mul_f32 v[114:115], v[76:77], v[154:155] op_sel:[1,1] op_sel_hi:[0,1] neg_lo:[0,1]
	v_pk_fma_f32 v[76:77], v[76:77], v[154:155], v[114:115] op_sel_hi:[1,0,1]
	s_waitcnt vmcnt(2)
	v_pk_mul_f32 v[114:115], v[66:67], v[132:133] op_sel:[1,1] op_sel_hi:[0,1] neg_lo:[0,1]
	v_pk_fma_f32 v[66:67], v[66:67], v[132:133], v[114:115] op_sel_hi:[1,0,1]
	v_pk_mul_f32 v[114:115], v[88:89], v[176:177] op_sel:[1,1] op_sel_hi:[0,1] neg_lo:[0,1]
	v_pk_fma_f32 v[88:89], v[88:89], v[176:177], v[114:115] op_sel_hi:[1,0,1]
	s_waitcnt vmcnt(1)
	v_pk_mul_f32 v[114:115], v[70:71], v[158:159] op_sel:[1,1] op_sel_hi:[0,1] neg_lo:[0,1]
	v_pk_fma_f32 v[70:71], v[70:71], v[158:159], v[114:115] op_sel_hi:[1,0,1]
	s_waitcnt vmcnt(0)
	v_pk_mul_f32 v[114:115], v[78:79], v[128:129] op_sel:[1,1] op_sel_hi:[0,1] neg_lo:[0,1]
	v_pk_fma_f32 v[78:79], v[78:79], v[128:129], v[114:115] op_sel_hi:[1,0,1]
	v_pk_add_f32 v[128:129], v[106:107], v[82:83]
	v_pk_add_f32 v[82:83], v[106:107], v[82:83] neg_lo:[0,1] neg_hi:[0,1]
	v_pk_fma_f32 v[130:131], v[150:151], v[164:165], v[130:131] op_sel_hi:[1,0,1]
	v_pk_mul_f32 v[106:107], v[82:83], s[50:51]
	v_pk_add_f32 v[114:115], v[134:135], v[80:81]
	v_pk_fma_f32 v[82:83], v[82:83], s[20:21], v[106:107] op_sel:[0,0,1] op_sel_hi:[1,0,0]
	v_pk_add_f32 v[106:107], v[122:123], v[108:109]
	v_pk_add_f32 v[108:109], v[122:123], v[108:109] neg_lo:[0,1] neg_hi:[0,1]
	s_mov_b32 s21, s34
	v_pk_mul_f32 v[122:123], v[108:109], s[14:15]
	v_pk_add_f32 v[80:81], v[134:135], v[80:81] neg_lo:[0,1] neg_hi:[0,1]
	v_pk_fma_f32 v[108:109], v[108:109], s[6:7], v[122:123] op_sel:[0,0,1] op_sel_hi:[1,0,0]
	v_pk_add_f32 v[122:123], v[84:85], v[74:75]
	v_pk_add_f32 v[74:75], v[84:85], v[74:75] neg_lo:[0,1] neg_hi:[0,1]
	s_mov_b32 s7, s12
	v_pk_mul_f32 v[84:85], v[74:75], s[52:53]
	v_add_u32_e32 v0, v0, v170
	v_pk_fma_f32 v[74:75], v[74:75], s[24:25], v[84:85] op_sel:[0,0,1] op_sel_hi:[1,0,0]
	v_pk_add_f32 v[84:85], v[86:87], v[98:99]
	v_pk_add_f32 v[86:87], v[86:87], v[98:99] neg_lo:[0,1] neg_hi:[0,1]
	s_mov_b32 s25, s26
	v_pk_mul_f32 v[98:99], v[86:87], s[10:11]
	v_lshlrev_b32_e32 v105, 5, v0
	v_pk_fma_f32 v[86:87], v[86:87], s[10:11], v[98:99] op_sel:[0,0,1] op_sel_hi:[1,0,0]
	v_pk_add_f32 v[98:99], v[94:95], v[92:93]
	v_pk_add_f32 v[92:93], v[94:95], v[92:93] neg_lo:[0,1] neg_hi:[0,1]
	s_nop 0
	v_pk_mul_f32 v[94:95], v[92:93], s[24:25]
	s_nop 0
	v_pk_fma_f32 v[92:93], v[92:93], s[0:1], v[94:95] op_sel:[0,0,1] op_sel_hi:[1,0,0]
	v_pk_add_f32 v[94:95], v[124:125], v[100:101]
	v_pk_add_f32 v[100:101], v[124:125], v[100:101] neg_lo:[0,1] neg_hi:[0,1]
	s_nop 0
	v_pk_mul_f32 v[124:125], v[100:101], s[6:7]
	s_nop 0
	v_pk_fma_f32 v[100:101], v[100:101], s[14:15], v[124:125] op_sel:[0,0,1] op_sel_hi:[1,0,0]
	v_pk_add_f32 v[124:125], v[90:91], v[136:137]
	v_pk_add_f32 v[90:91], v[90:91], v[136:137] neg_lo:[0,1] neg_hi:[0,1]
	s_nop 0
	v_pk_mul_f32 v[132:133], v[90:91], s[20:21]
	s_nop 0
	v_pk_fma_f32 v[90:91], v[90:91], s[48:49], v[132:133] op_sel:[0,0,1] op_sel_hi:[1,0,0]
	v_pk_add_f32 v[132:133], v[116:117], v[68:69]
	v_pk_add_f32 v[116:117], v[116:117], v[68:69] op_sel:[1,1] op_sel_hi:[0,0] neg_lo:[1,0] neg_hi:[0,1]
	s_nop 0
	v_pk_add_f32 v[68:69], v[118:119], v[96:97]
	v_pk_add_f32 v[96:97], v[118:119], v[96:97] neg_lo:[0,1] neg_hi:[0,1]
	s_nop 0
	v_pk_mul_f32 v[118:119], v[96:97], s[20:21]
	s_nop 0
	v_pk_fma_f32 v[96:97], v[96:97], s[18:19], v[118:119] op_sel:[0,0,1] op_sel_hi:[1,0,0]
	v_pk_add_f32 v[118:119], v[110:111], v[72:73]
	v_pk_add_f32 v[72:73], v[110:111], v[72:73] neg_lo:[0,1] neg_hi:[0,1]
	s_nop 0
	v_pk_mul_f32 v[110:111], v[72:73], s[6:7]
	s_nop 0
	v_pk_fma_f32 v[72:73], v[72:73], s[4:5], v[110:111] op_sel:[0,0,1] op_sel_hi:[1,0,0]
	v_pk_add_f32 v[110:111], v[102:103], v[76:77]
	v_pk_add_f32 v[76:77], v[102:103], v[76:77] neg_lo:[0,1] neg_hi:[0,1]
	s_nop 0
	v_pk_mul_f32 v[102:103], v[76:77], s[24:25]
	s_nop 0
	v_pk_fma_f32 v[76:77], v[76:77], s[22:23], v[102:103] op_sel:[0,0,1] op_sel_hi:[1,0,0]
	v_pk_add_f32 v[102:103], v[120:121], v[66:67]
	v_pk_add_f32 v[66:67], v[120:121], v[66:67] neg_lo:[0,1] neg_hi:[0,1]
	s_nop 0
	v_pk_mul_f32 v[120:121], v[66:67], s[10:11]
	s_nop 0
	v_pk_fma_f32 v[66:67], v[66:67], s[8:9], v[120:121] op_sel:[0,0,1] op_sel_hi:[1,0,0]
	v_pk_add_f32 v[120:121], v[126:127], v[88:89]
	v_pk_add_f32 v[88:89], v[126:127], v[88:89] neg_lo:[0,1] neg_hi:[0,1]
	s_nop 0
	v_pk_mul_f32 v[126:127], v[88:89], s[52:53]
	s_nop 0
	v_pk_fma_f32 v[88:89], v[88:89], s[26:27], v[126:127] op_sel:[0,0,1] op_sel_hi:[1,0,0]
	v_pk_add_f32 v[126:127], v[112:113], v[70:71]
	v_pk_add_f32 v[70:71], v[112:113], v[70:71] neg_lo:[0,1] neg_hi:[0,1]
	s_nop 0
	v_pk_mul_f32 v[112:113], v[70:71], s[14:15]
	s_nop 0
	v_pk_fma_f32 v[70:71], v[70:71], s[12:13], v[112:113] op_sel:[0,0,1] op_sel_hi:[1,0,0]
	v_pk_add_f32 v[112:113], v[130:131], v[78:79]
	v_pk_add_f32 v[78:79], v[130:131], v[78:79] neg_lo:[0,1] neg_hi:[0,1]
	s_nop 0
	v_pk_mul_f32 v[130:131], v[78:79], s[50:51]
	s_nop 0
	v_pk_fma_f32 v[78:79], v[78:79], s[34:35], v[130:131] op_sel:[0,0,1] op_sel_hi:[1,0,0]
	v_pk_add_f32 v[130:131], v[114:115], v[132:133]
	v_pk_add_f32 v[114:115], v[114:115], v[132:133] neg_lo:[0,1] neg_hi:[0,1]
	v_pk_add_f32 v[132:133], v[128:129], v[68:69]
	v_pk_add_f32 v[68:69], v[128:129], v[68:69] neg_lo:[0,1] neg_hi:[0,1]
	s_nop 0
	v_pk_mul_f32 v[128:129], v[68:69], s[14:15]
	s_nop 0
	v_pk_fma_f32 v[68:69], v[68:69], s[6:7], v[128:129] op_sel:[0,0,1] op_sel_hi:[1,0,0]
	v_pk_add_f32 v[128:129], v[106:107], v[118:119]
	v_pk_add_f32 v[106:107], v[106:107], v[118:119] neg_lo:[0,1] neg_hi:[0,1]
	s_nop 0
	v_pk_mul_f32 v[118:119], v[106:107], s[10:11]
	s_nop 0
	v_pk_fma_f32 v[106:107], v[106:107], s[10:11], v[118:119] op_sel:[0,0,1] op_sel_hi:[1,0,0]
	v_pk_add_f32 v[118:119], v[122:123], v[110:111]
	v_pk_add_f32 v[110:111], v[122:123], v[110:111] neg_lo:[0,1] neg_hi:[0,1]
	s_nop 0
	v_pk_mul_f32 v[122:123], v[110:111], s[6:7]
	s_nop 0
	v_pk_fma_f32 v[110:111], v[110:111], s[14:15], v[122:123] op_sel:[0,0,1] op_sel_hi:[1,0,0]
	v_pk_add_f32 v[122:123], v[84:85], v[102:103]
	v_pk_add_f32 v[102:103], v[84:85], v[102:103] op_sel:[1,1] op_sel_hi:[0,0] neg_lo:[1,0] neg_hi:[0,1]
	s_nop 0
	v_pk_add_f32 v[84:85], v[98:99], v[120:121]
	v_pk_add_f32 v[98:99], v[98:99], v[120:121] neg_lo:[0,1] neg_hi:[0,1]
	s_nop 0
	v_pk_mul_f32 v[120:121], v[98:99], s[6:7]
	s_nop 0
	v_pk_fma_f32 v[98:99], v[98:99], s[4:5], v[120:121] op_sel:[0,0,1] op_sel_hi:[1,0,0]
	v_pk_add_f32 v[120:121], v[94:95], v[126:127]
	v_pk_add_f32 v[94:95], v[94:95], v[126:127] neg_lo:[0,1] neg_hi:[0,1]
	s_nop 0
	v_pk_mul_f32 v[126:127], v[94:95], s[10:11]
	s_nop 0
	v_pk_fma_f32 v[94:95], v[94:95], s[8:9], v[126:127] op_sel:[0,0,1] op_sel_hi:[1,0,0]
	v_pk_add_f32 v[126:127], v[124:125], v[112:113]
	v_pk_add_f32 v[112:113], v[124:125], v[112:113] neg_lo:[0,1] neg_hi:[0,1]
	s_nop 0
	v_pk_mul_f32 v[124:125], v[112:113], s[14:15]
	s_nop 0
	v_pk_fma_f32 v[112:113], v[112:113], s[12:13], v[124:125] op_sel:[0,0,1] op_sel_hi:[1,0,0]
	v_pk_add_f32 v[124:125], v[80:81], v[116:117]
	v_pk_add_f32 v[80:81], v[80:81], v[116:117] neg_lo:[0,1] neg_hi:[0,1]
	v_pk_add_f32 v[116:117], v[82:83], v[96:97]
	v_pk_add_f32 v[82:83], v[82:83], v[96:97] neg_lo:[0,1] neg_hi:[0,1]
	s_nop 0
	v_pk_mul_f32 v[96:97], v[82:83], s[14:15]
	s_nop 0
	v_pk_fma_f32 v[82:83], v[82:83], s[6:7], v[96:97] op_sel:[0,0,1] op_sel_hi:[1,0,0]
	v_pk_add_f32 v[96:97], v[108:109], v[72:73]
	v_pk_add_f32 v[72:73], v[108:109], v[72:73] neg_lo:[0,1] neg_hi:[0,1]
	s_nop 0
	v_pk_mul_f32 v[108:109], v[72:73], s[10:11]
	s_nop 0
	v_pk_fma_f32 v[72:73], v[72:73], s[10:11], v[108:109] op_sel:[0,0,1] op_sel_hi:[1,0,0]
	v_pk_add_f32 v[108:109], v[74:75], v[76:77]
	v_pk_add_f32 v[74:75], v[74:75], v[76:77] neg_lo:[0,1] neg_hi:[0,1]
	s_nop 0
	v_pk_mul_f32 v[76:77], v[74:75], s[6:7]
	s_nop 0
	v_pk_fma_f32 v[74:75], v[74:75], s[14:15], v[76:77] op_sel:[0,0,1] op_sel_hi:[1,0,0]
	v_pk_add_f32 v[76:77], v[86:87], v[66:67]
	v_pk_add_f32 v[86:87], v[86:87], v[66:67] op_sel:[1,1] op_sel_hi:[0,0] neg_lo:[1,0] neg_hi:[0,1]
	s_nop 0
	v_pk_add_f32 v[66:67], v[92:93], v[88:89]
	v_pk_add_f32 v[88:89], v[92:93], v[88:89] neg_lo:[0,1] neg_hi:[0,1]
	s_nop 0
	v_pk_mul_f32 v[92:93], v[88:89], s[6:7]
	s_nop 0
	v_pk_fma_f32 v[88:89], v[88:89], s[4:5], v[92:93] op_sel:[0,0,1] op_sel_hi:[1,0,0]
	v_pk_add_f32 v[92:93], v[100:101], v[70:71]
	v_pk_add_f32 v[70:71], v[100:101], v[70:71] neg_lo:[0,1] neg_hi:[0,1]
	s_nop 0
	v_pk_mul_f32 v[100:101], v[70:71], s[10:11]
	s_nop 0
	v_pk_fma_f32 v[70:71], v[70:71], s[8:9], v[100:101] op_sel:[0,0,1] op_sel_hi:[1,0,0]
	v_pk_add_f32 v[100:101], v[90:91], v[78:79]
	v_pk_add_f32 v[78:79], v[90:91], v[78:79] neg_lo:[0,1] neg_hi:[0,1]
	s_nop 0
	v_pk_mul_f32 v[90:91], v[78:79], s[14:15]
	s_nop 0
	v_pk_fma_f32 v[78:79], v[78:79], s[12:13], v[90:91] op_sel:[0,0,1] op_sel_hi:[1,0,0]
	v_pk_add_f32 v[90:91], v[130:131], v[122:123]
	v_pk_add_f32 v[122:123], v[130:131], v[122:123] neg_lo:[0,1] neg_hi:[0,1]
	v_pk_add_f32 v[130:131], v[132:133], v[84:85]
	v_pk_add_f32 v[84:85], v[132:133], v[84:85] neg_lo:[0,1] neg_hi:[0,1]
	s_nop 0
	v_pk_mul_f32 v[132:133], v[84:85], s[10:11]
	s_nop 0
	v_pk_fma_f32 v[84:85], v[84:85], s[10:11], v[132:133] op_sel:[0,0,1] op_sel_hi:[1,0,0]
	v_pk_add_f32 v[132:133], v[128:129], v[120:121]
	v_pk_add_f32 v[128:129], v[128:129], v[120:121] op_sel:[1,1] op_sel_hi:[0,0] neg_lo:[1,0] neg_hi:[0,1]
	s_nop 0
	v_pk_add_f32 v[120:121], v[118:119], v[126:127]
	v_pk_add_f32 v[118:119], v[118:119], v[126:127] neg_lo:[0,1] neg_hi:[0,1]
	s_nop 0
	v_pk_mul_f32 v[126:127], v[118:119], s[10:11]
	s_nop 0
	v_pk_fma_f32 v[118:119], v[118:119], s[8:9], v[126:127] op_sel:[0,0,1] op_sel_hi:[1,0,0]
	v_pk_add_f32 v[126:127], v[114:115], v[102:103]
	v_pk_add_f32 v[102:103], v[114:115], v[102:103] neg_lo:[0,1] neg_hi:[0,1]
	v_pk_add_f32 v[114:115], v[68:69], v[98:99]
	v_pk_add_f32 v[68:69], v[68:69], v[98:99] neg_lo:[0,1] neg_hi:[0,1]
	s_nop 0
	v_pk_mul_f32 v[98:99], v[68:69], s[10:11]
	s_nop 0
	v_pk_fma_f32 v[68:69], v[68:69], s[10:11], v[98:99] op_sel:[0,0,1] op_sel_hi:[1,0,0]
	v_pk_add_f32 v[98:99], v[106:107], v[94:95]
	v_pk_add_f32 v[106:107], v[106:107], v[94:95] op_sel:[1,1] op_sel_hi:[0,0] neg_lo:[1,0] neg_hi:[0,1]
	s_nop 0
	v_pk_add_f32 v[94:95], v[110:111], v[112:113]
	v_pk_add_f32 v[110:111], v[110:111], v[112:113] neg_lo:[0,1] neg_hi:[0,1]
	s_nop 0
	v_pk_mul_f32 v[112:113], v[110:111], s[10:11]
	s_nop 0
	v_pk_fma_f32 v[110:111], v[110:111], s[8:9], v[112:113] op_sel:[0,0,1] op_sel_hi:[1,0,0]
	v_pk_add_f32 v[112:113], v[124:125], v[76:77]
	v_pk_add_f32 v[76:77], v[124:125], v[76:77] neg_lo:[0,1] neg_hi:[0,1]
	v_pk_add_f32 v[124:125], v[116:117], v[66:67]
	v_pk_add_f32 v[66:67], v[116:117], v[66:67] neg_lo:[0,1] neg_hi:[0,1]
	s_nop 0
	v_pk_mul_f32 v[116:117], v[66:67], s[10:11]
	s_nop 0
	v_pk_fma_f32 v[66:67], v[66:67], s[10:11], v[116:117] op_sel:[0,0,1] op_sel_hi:[1,0,0]
	v_pk_add_f32 v[116:117], v[96:97], v[92:93]
	v_pk_add_f32 v[96:97], v[96:97], v[92:93] op_sel:[1,1] op_sel_hi:[0,0] neg_lo:[1,0] neg_hi:[0,1]
	v_pk_add_f32 v[134:135], v[112:113], v[116:117]
	v_pk_add_f32 v[92:93], v[108:109], v[100:101]
	v_pk_add_f32 v[100:101], v[108:109], v[100:101] neg_lo:[0,1] neg_hi:[0,1]
	v_pk_add_f32 v[112:113], v[112:113], v[116:117] neg_lo:[0,1] neg_hi:[0,1]
	v_pk_mul_f32 v[108:109], v[100:101], s[10:11]
	v_pk_add_f32 v[116:117], v[124:125], v[92:93]
	v_pk_fma_f32 v[100:101], v[100:101], s[8:9], v[108:109] op_sel:[0,0,1] op_sel_hi:[1,0,0]
	v_pk_add_f32 v[108:109], v[80:81], v[86:87]
	v_pk_add_f32 v[80:81], v[80:81], v[86:87] neg_lo:[0,1] neg_hi:[0,1]
	v_pk_add_f32 v[86:87], v[82:83], v[88:89]
	v_pk_add_f32 v[82:83], v[82:83], v[88:89] neg_lo:[0,1] neg_hi:[0,1]
	s_nop 0
	v_pk_mul_f32 v[88:89], v[82:83], s[10:11]
	s_nop 0
	v_pk_fma_f32 v[82:83], v[82:83], s[10:11], v[88:89] op_sel:[0,0,1] op_sel_hi:[1,0,0]
	v_pk_add_f32 v[88:89], v[72:73], v[70:71]
	v_pk_add_f32 v[72:73], v[72:73], v[70:71] op_sel:[1,1] op_sel_hi:[0,0] neg_lo:[1,0] neg_hi:[0,1]
	v_pk_add_f32 v[136:137], v[108:109], v[88:89]
	v_pk_add_f32 v[70:71], v[74:75], v[78:79]
	v_pk_add_f32 v[74:75], v[74:75], v[78:79] neg_lo:[0,1] neg_hi:[0,1]
	v_pk_add_f32 v[88:89], v[108:109], v[88:89] neg_lo:[0,1] neg_hi:[0,1]
	v_pk_mul_f32 v[78:79], v[74:75], s[10:11]
	v_pk_add_f32 v[108:109], v[86:87], v[70:71]
	v_pk_fma_f32 v[74:75], v[74:75], s[8:9], v[78:79] op_sel:[0,0,1] op_sel_hi:[1,0,0]
	v_pk_add_f32 v[78:79], v[90:91], v[132:133]
	v_pk_add_f32 v[90:91], v[90:91], v[132:133] neg_lo:[0,1] neg_hi:[0,1]
	v_pk_add_f32 v[132:133], v[130:131], v[120:121]
	v_pk_add_f32 v[130:131], v[130:131], v[120:121] op_sel:[1,1] op_sel_hi:[0,0] neg_lo:[1,0] neg_hi:[0,1]
	v_pk_add_f32 v[138:139], v[80:81], v[72:73] neg_lo:[0,1] neg_hi:[0,1]
	v_pk_add_f32 v[120:121], v[122:123], v[128:129]
	v_pk_add_f32 v[122:123], v[122:123], v[128:129] neg_lo:[0,1] neg_hi:[0,1]
	v_pk_add_f32 v[128:129], v[84:85], v[118:119]
	v_pk_add_f32 v[118:119], v[84:85], v[118:119] op_sel:[1,1] op_sel_hi:[0,0] neg_lo:[1,0] neg_hi:[0,1]
	v_pk_add_f32 v[140:141], v[82:83], v[74:75]
	v_pk_add_f32 v[84:85], v[126:127], v[98:99]
	v_pk_add_f32 v[98:99], v[126:127], v[98:99] neg_lo:[0,1] neg_hi:[0,1]
	v_pk_add_f32 v[126:127], v[114:115], v[94:95]
	v_pk_add_f32 v[114:115], v[114:115], v[94:95] op_sel:[1,1] op_sel_hi:[0,0] neg_lo:[1,0] neg_hi:[0,1]
	v_pk_add_f32 v[142:143], v[78:79], v[132:133]
	v_pk_add_f32 v[94:95], v[102:103], v[106:107]
	v_pk_add_f32 v[102:103], v[102:103], v[106:107] neg_lo:[0,1] neg_hi:[0,1]
	v_pk_add_f32 v[106:107], v[68:69], v[110:111]
	v_pk_add_f32 v[110:111], v[68:69], v[110:111] op_sel:[1,1] op_sel_hi:[0,0] neg_lo:[1,0] neg_hi:[0,1]
	v_pk_add_f32 v[132:133], v[78:79], v[132:133] neg_lo:[0,1] neg_hi:[0,1]
	v_pk_add_f32 v[92:93], v[124:125], v[92:93] op_sel:[1,1] op_sel_hi:[0,0] neg_lo:[1,0] neg_hi:[0,1]
	v_pk_add_f32 v[124:125], v[76:77], v[96:97]
	v_pk_add_f32 v[76:77], v[76:77], v[96:97] neg_lo:[0,1] neg_hi:[0,1]
	v_pk_add_f32 v[96:97], v[66:67], v[100:101]
	v_pk_add_f32 v[100:101], v[66:67], v[100:101] op_sel:[1,1] op_sel_hi:[0,0] neg_lo:[1,0] neg_hi:[0,1]
	v_pk_add_f32 v[70:71], v[86:87], v[70:71] op_sel:[1,1] op_sel_hi:[0,0] neg_lo:[1,0] neg_hi:[0,1]
	v_pk_add_f32 v[74:75], v[82:83], v[74:75] op_sel:[1,1] op_sel_hi:[0,0] neg_lo:[1,0] neg_hi:[0,1]
	v_pk_add_f32 v[86:87], v[80:81], v[72:73]
	v_pk_add_f32 v[144:145], v[90:91], v[130:131]
	v_pk_add_f32 v[82:83], v[90:91], v[130:131] neg_lo:[0,1] neg_hi:[0,1]
	v_pk_add_f32 v[90:91], v[120:121], v[128:129]
	v_pk_add_f32 v[120:121], v[120:121], v[128:129] neg_lo:[0,1] neg_hi:[0,1]
	v_pk_add_f32 v[128:129], v[122:123], v[118:119]
	v_pk_add_f32 v[68:69], v[122:123], v[118:119] neg_lo:[0,1] neg_hi:[0,1]
	v_pk_add_f32 v[118:119], v[84:85], v[126:127]
	v_pk_add_f32 v[122:123], v[84:85], v[126:127] neg_lo:[0,1] neg_hi:[0,1]
	v_pk_add_f32 v[126:127], v[98:99], v[114:115]
	v_pk_add_f32 v[78:79], v[98:99], v[114:115] neg_lo:[0,1] neg_hi:[0,1]
	v_pk_add_f32 v[98:99], v[94:95], v[106:107]
	v_pk_add_f32 v[94:95], v[94:95], v[106:107] neg_lo:[0,1] neg_hi:[0,1]
	v_pk_add_f32 v[106:107], v[102:103], v[110:111]
	v_pk_add_f32 v[66:67], v[102:103], v[110:111] neg_lo:[0,1] neg_hi:[0,1]
	v_pk_add_f32 v[102:103], v[134:135], v[116:117]
	v_pk_add_f32 v[110:111], v[134:135], v[116:117] neg_lo:[0,1] neg_hi:[0,1]
	v_pk_add_f32 v[116:117], v[88:89], v[70:71]
	v_pk_add_f32 v[80:81], v[88:89], v[70:71] neg_lo:[0,1] neg_hi:[0,1]
	v_lshlrev_b32_e32 v70, 4, v0
	v_and_b32_e32 v70, 0x1f0, v70
	v_pk_add_f32 v[114:115], v[112:113], v[92:93]
	v_pk_add_f32 v[84:85], v[112:113], v[92:93] neg_lo:[0,1] neg_hi:[0,1]
	v_pk_add_f32 v[112:113], v[76:77], v[100:101]
	v_pk_add_f32 v[72:73], v[76:77], v[100:101] neg_lo:[0,1] neg_hi:[0,1]
	v_cvt_f32_u32_e32 v76, v70
	v_pk_add_f32 v[92:93], v[124:125], v[96:97]
	v_pk_add_f32 v[96:97], v[124:125], v[96:97] neg_lo:[0,1] neg_hi:[0,1]
	v_pk_add_f32 v[124:125], v[138:139], v[74:75]
	v_mul_f32_e32 v76, 0x38800000, v76
	v_pk_add_f32 v[70:71], v[138:139], v[74:75] neg_lo:[0,1] neg_hi:[0,1]
	v_sin_f32_e32 v75, v76
	v_ashrrev_i32_e32 v74, 2, v105
	v_lshlrev_b32_e32 v0, 8, v0
	v_add3_u32 v0, 0, v74, v0
	v_cos_f32_e32 v74, v76
	v_xor_b32_e32 v76, 0x80000000, v75
	v_mov_b32_e32 v77, v75
	v_pk_mul_f32 v[130:131], v[76:77], v[102:103] op_sel:[0,1] op_sel_hi:[1,0]
	v_pk_add_f32 v[100:101], v[136:137], v[108:109]
	v_pk_fma_f32 v[102:103], v[102:103], v[74:75], v[130:131] op_sel_hi:[1,0,1]
	ds_write2_b64 v0, v[142:143], v[102:103] offset1:1
	v_pk_mul_f32 v[102:103], v[76:77], v[74:75] op_sel:[0,1] op_sel_hi:[1,0]
	v_pk_add_f32 v[88:89], v[86:87], v[140:141]
	v_pk_fma_f32 v[102:103], v[74:75], v[74:75], v[102:103] op_sel_hi:[1,0,1]
	v_pk_add_f32 v[108:109], v[136:137], v[108:109] neg_lo:[0,1] neg_hi:[0,1]
	v_pk_mul_f32 v[130:131], v[118:119], v[102:103] op_sel:[1,1] op_sel_hi:[0,1] neg_lo:[0,1]
	v_pk_fma_f32 v[118:119], v[118:119], v[102:103], v[130:131] op_sel_hi:[1,0,1]
	v_pk_mul_f32 v[130:131], v[76:77], v[102:103] op_sel:[0,1] op_sel_hi:[1,0]
	v_pk_add_f32 v[86:87], v[86:87], v[140:141] neg_lo:[0,1] neg_hi:[0,1]
	v_pk_fma_f32 v[102:103], v[102:103], v[74:75], v[130:131] op_sel_hi:[1,0,1]
	s_nop 0
	v_pk_mul_f32 v[130:131], v[100:101], v[102:103] op_sel:[1,1] op_sel_hi:[0,1] neg_lo:[0,1]
	v_pk_fma_f32 v[100:101], v[100:101], v[102:103], v[130:131] op_sel_hi:[1,0,1]
	ds_write2_b64 v0, v[118:119], v[100:101] offset0:2 offset1:3
	v_pk_mul_f32 v[100:101], v[76:77], v[102:103] op_sel:[0,1] op_sel_hi:[1,0]
	s_nop 0
	v_pk_fma_f32 v[100:101], v[102:103], v[74:75], v[100:101] op_sel_hi:[1,0,1]
	s_nop 0
	v_pk_mul_f32 v[102:103], v[90:91], v[100:101] op_sel:[1,1] op_sel_hi:[0,1] neg_lo:[0,1]
	v_pk_fma_f32 v[90:91], v[90:91], v[100:101], v[102:103] op_sel_hi:[1,0,1]
	v_pk_mul_f32 v[102:103], v[76:77], v[100:101] op_sel:[0,1] op_sel_hi:[1,0]
	s_nop 0
	v_pk_fma_f32 v[100:101], v[100:101], v[74:75], v[102:103] op_sel_hi:[1,0,1]
	s_nop 0
	v_pk_mul_f32 v[102:103], v[92:93], v[100:101] op_sel:[1,1] op_sel_hi:[0,1] neg_lo:[0,1]
	v_pk_fma_f32 v[92:93], v[92:93], v[100:101], v[102:103] op_sel_hi:[1,0,1]
	ds_write2_b64 v0, v[90:91], v[92:93] offset0:4 offset1:5
	v_pk_mul_f32 v[90:91], v[76:77], v[100:101] op_sel:[0,1] op_sel_hi:[1,0]
	s_nop 0
	v_pk_fma_f32 v[90:91], v[100:101], v[74:75], v[90:91] op_sel_hi:[1,0,1]
	s_nop 0
	v_pk_mul_f32 v[92:93], v[98:99], v[90:91] op_sel:[1,1] op_sel_hi:[0,1] neg_lo:[0,1]
	v_pk_fma_f32 v[92:93], v[98:99], v[90:91], v[92:93] op_sel_hi:[1,0,1]
	v_pk_mul_f32 v[98:99], v[76:77], v[90:91] op_sel:[0,1] op_sel_hi:[1,0]
	s_nop 0
	v_pk_fma_f32 v[90:91], v[90:91], v[74:75], v[98:99] op_sel_hi:[1,0,1]
	s_nop 0
	v_pk_mul_f32 v[98:99], v[88:89], v[90:91] op_sel:[1,1] op_sel_hi:[0,1] neg_lo:[0,1]
	v_pk_fma_f32 v[88:89], v[88:89], v[90:91], v[98:99] op_sel_hi:[1,0,1]
	ds_write2_b64 v0, v[92:93], v[88:89] offset0:6 offset1:7
	v_pk_mul_f32 v[88:89], v[76:77], v[90:91] op_sel:[0,1] op_sel_hi:[1,0]
	s_nop 0
	v_pk_fma_f32 v[88:89], v[90:91], v[74:75], v[88:89] op_sel_hi:[1,0,1]
	s_nop 0
	v_pk_mul_f32 v[90:91], v[144:145], v[88:89] op_sel:[1,1] op_sel_hi:[0,1] neg_lo:[0,1]
	v_pk_mul_f32 v[92:93], v[76:77], v[88:89] op_sel:[0,1] op_sel_hi:[1,0]
	v_pk_fma_f32 v[90:91], v[144:145], v[88:89], v[90:91] op_sel_hi:[1,0,1]
	v_pk_fma_f32 v[88:89], v[88:89], v[74:75], v[92:93] op_sel_hi:[1,0,1]
	s_nop 0
	v_pk_mul_f32 v[92:93], v[114:115], v[88:89] op_sel:[1,1] op_sel_hi:[0,1] neg_lo:[0,1]
	v_pk_fma_f32 v[92:93], v[114:115], v[88:89], v[92:93] op_sel_hi:[1,0,1]
	ds_write2_b64 v0, v[90:91], v[92:93] offset0:8 offset1:9
	v_pk_mul_f32 v[90:91], v[76:77], v[88:89] op_sel:[0,1] op_sel_hi:[1,0]
	s_nop 0
	v_pk_fma_f32 v[88:89], v[88:89], v[74:75], v[90:91] op_sel_hi:[1,0,1]
	s_nop 0
	v_pk_mul_f32 v[90:91], v[126:127], v[88:89] op_sel:[1,1] op_sel_hi:[0,1] neg_lo:[0,1]
	v_pk_mul_f32 v[92:93], v[76:77], v[88:89] op_sel:[0,1] op_sel_hi:[1,0]
	v_pk_fma_f32 v[90:91], v[126:127], v[88:89], v[90:91] op_sel_hi:[1,0,1]
	v_pk_fma_f32 v[88:89], v[88:89], v[74:75], v[92:93] op_sel_hi:[1,0,1]
	s_nop 0
	v_pk_mul_f32 v[92:93], v[116:117], v[88:89] op_sel:[1,1] op_sel_hi:[0,1] neg_lo:[0,1]
	v_pk_fma_f32 v[92:93], v[116:117], v[88:89], v[92:93] op_sel_hi:[1,0,1]
	ds_write2_b64 v0, v[90:91], v[92:93] offset0:10 offset1:11
	v_pk_mul_f32 v[90:91], v[76:77], v[88:89] op_sel:[0,1] op_sel_hi:[1,0]
	s_nop 0
	v_pk_fma_f32 v[88:89], v[88:89], v[74:75], v[90:91] op_sel_hi:[1,0,1]
	s_nop 0
	v_pk_mul_f32 v[90:91], v[128:129], v[88:89] op_sel:[1,1] op_sel_hi:[0,1] neg_lo:[0,1]
	v_pk_mul_f32 v[92:93], v[76:77], v[88:89] op_sel:[0,1] op_sel_hi:[1,0]
	v_pk_fma_f32 v[90:91], v[128:129], v[88:89], v[90:91] op_sel_hi:[1,0,1]
	v_pk_fma_f32 v[88:89], v[88:89], v[74:75], v[92:93] op_sel_hi:[1,0,1]
	s_nop 0
	v_pk_mul_f32 v[92:93], v[112:113], v[88:89] op_sel:[1,1] op_sel_hi:[0,1] neg_lo:[0,1]
	v_pk_fma_f32 v[92:93], v[112:113], v[88:89], v[92:93] op_sel_hi:[1,0,1]
	ds_write2_b64 v0, v[90:91], v[92:93] offset0:12 offset1:13
	v_pk_mul_f32 v[90:91], v[76:77], v[88:89] op_sel:[0,1] op_sel_hi:[1,0]
	s_nop 0
	v_pk_fma_f32 v[88:89], v[88:89], v[74:75], v[90:91] op_sel_hi:[1,0,1]
	s_nop 0
	v_pk_mul_f32 v[90:91], v[106:107], v[88:89] op_sel:[1,1] op_sel_hi:[0,1] neg_lo:[0,1]
	v_pk_mul_f32 v[92:93], v[76:77], v[88:89] op_sel:[0,1] op_sel_hi:[1,0]
	v_pk_fma_f32 v[90:91], v[106:107], v[88:89], v[90:91] op_sel_hi:[1,0,1]
	v_pk_fma_f32 v[88:89], v[88:89], v[74:75], v[92:93] op_sel_hi:[1,0,1]
	s_nop 0
	v_pk_mul_f32 v[92:93], v[124:125], v[88:89] op_sel:[1,1] op_sel_hi:[0,1] neg_lo:[0,1]
	v_pk_fma_f32 v[92:93], v[124:125], v[88:89], v[92:93] op_sel_hi:[1,0,1]
	ds_write2_b64 v0, v[90:91], v[92:93] offset0:14 offset1:15
	v_pk_mul_f32 v[90:91], v[76:77], v[88:89] op_sel:[0,1] op_sel_hi:[1,0]
	s_nop 0
	v_pk_fma_f32 v[88:89], v[88:89], v[74:75], v[90:91] op_sel_hi:[1,0,1]
	s_nop 0
	v_pk_mul_f32 v[90:91], v[132:133], v[88:89] op_sel:[1,1] op_sel_hi:[0,1] neg_lo:[0,1]
	v_pk_mul_f32 v[92:93], v[76:77], v[88:89] op_sel:[0,1] op_sel_hi:[1,0]
	v_pk_fma_f32 v[90:91], v[132:133], v[88:89], v[90:91] op_sel_hi:[1,0,1]
	v_pk_fma_f32 v[88:89], v[88:89], v[74:75], v[92:93] op_sel_hi:[1,0,1]
	s_nop 0
	v_pk_mul_f32 v[92:93], v[110:111], v[88:89] op_sel:[1,1] op_sel_hi:[0,1] neg_lo:[0,1]
	v_pk_fma_f32 v[92:93], v[110:111], v[88:89], v[92:93] op_sel_hi:[1,0,1]
	ds_write2_b64 v0, v[90:91], v[92:93] offset0:16 offset1:17
	v_pk_mul_f32 v[90:91], v[76:77], v[88:89] op_sel:[0,1] op_sel_hi:[1,0]
	s_nop 0
	v_pk_fma_f32 v[88:89], v[88:89], v[74:75], v[90:91] op_sel_hi:[1,0,1]
	s_nop 0
	v_pk_mul_f32 v[90:91], v[122:123], v[88:89] op_sel:[1,1] op_sel_hi:[0,1] neg_lo:[0,1]
	v_pk_mul_f32 v[92:93], v[76:77], v[88:89] op_sel:[0,1] op_sel_hi:[1,0]
	v_pk_fma_f32 v[90:91], v[122:123], v[88:89], v[90:91] op_sel_hi:[1,0,1]
	v_pk_fma_f32 v[88:89], v[88:89], v[74:75], v[92:93] op_sel_hi:[1,0,1]
	s_nop 0
	v_pk_mul_f32 v[92:93], v[108:109], v[88:89] op_sel:[1,1] op_sel_hi:[0,1] neg_lo:[0,1]
	v_pk_fma_f32 v[92:93], v[108:109], v[88:89], v[92:93] op_sel_hi:[1,0,1]
	ds_write2_b64 v0, v[90:91], v[92:93] offset0:18 offset1:19
	v_pk_mul_f32 v[90:91], v[76:77], v[88:89] op_sel:[0,1] op_sel_hi:[1,0]
	s_nop 0
	v_pk_fma_f32 v[88:89], v[88:89], v[74:75], v[90:91] op_sel_hi:[1,0,1]
	s_nop 0
	v_pk_mul_f32 v[90:91], v[120:121], v[88:89] op_sel:[1,1] op_sel_hi:[0,1] neg_lo:[0,1]
	v_pk_mul_f32 v[92:93], v[76:77], v[88:89] op_sel:[0,1] op_sel_hi:[1,0]
	v_pk_fma_f32 v[90:91], v[120:121], v[88:89], v[90:91] op_sel_hi:[1,0,1]
	v_pk_fma_f32 v[88:89], v[88:89], v[74:75], v[92:93] op_sel_hi:[1,0,1]
	s_nop 0
	v_pk_mul_f32 v[92:93], v[96:97], v[88:89] op_sel:[1,1] op_sel_hi:[0,1] neg_lo:[0,1]
	v_pk_fma_f32 v[92:93], v[96:97], v[88:89], v[92:93] op_sel_hi:[1,0,1]
	ds_write2_b64 v0, v[90:91], v[92:93] offset0:20 offset1:21
	v_pk_mul_f32 v[90:91], v[76:77], v[88:89] op_sel:[0,1] op_sel_hi:[1,0]
	s_nop 0
	v_pk_fma_f32 v[88:89], v[88:89], v[74:75], v[90:91] op_sel_hi:[1,0,1]
	s_nop 0
	v_pk_mul_f32 v[90:91], v[94:95], v[88:89] op_sel:[1,1] op_sel_hi:[0,1] neg_lo:[0,1]
	v_pk_mul_f32 v[92:93], v[76:77], v[88:89] op_sel:[0,1] op_sel_hi:[1,0]
	v_pk_fma_f32 v[90:91], v[94:95], v[88:89], v[90:91] op_sel_hi:[1,0,1]
	v_pk_fma_f32 v[88:89], v[88:89], v[74:75], v[92:93] op_sel_hi:[1,0,1]
	s_nop 0
	v_pk_mul_f32 v[92:93], v[86:87], v[88:89] op_sel:[1,1] op_sel_hi:[0,1] neg_lo:[0,1]
	v_pk_fma_f32 v[86:87], v[86:87], v[88:89], v[92:93] op_sel_hi:[1,0,1]
	ds_write2_b64 v0, v[90:91], v[86:87] offset0:22 offset1:23
	v_pk_mul_f32 v[86:87], v[76:77], v[88:89] op_sel:[0,1] op_sel_hi:[1,0]
	s_nop 0
	v_pk_fma_f32 v[86:87], v[88:89], v[74:75], v[86:87] op_sel_hi:[1,0,1]
	s_nop 0
	v_pk_mul_f32 v[88:89], v[82:83], v[86:87] op_sel:[1,1] op_sel_hi:[0,1] neg_lo:[0,1]
	v_pk_fma_f32 v[82:83], v[82:83], v[86:87], v[88:89] op_sel_hi:[1,0,1]
	v_pk_mul_f32 v[88:89], v[76:77], v[86:87] op_sel:[0,1] op_sel_hi:[1,0]
	s_nop 0
	v_pk_fma_f32 v[86:87], v[86:87], v[74:75], v[88:89] op_sel_hi:[1,0,1]
	s_nop 0
	v_pk_mul_f32 v[88:89], v[84:85], v[86:87] op_sel:[1,1] op_sel_hi:[0,1] neg_lo:[0,1]
	v_pk_fma_f32 v[84:85], v[84:85], v[86:87], v[88:89] op_sel_hi:[1,0,1]
	ds_write2_b64 v0, v[82:83], v[84:85] offset0:24 offset1:25
	v_pk_mul_f32 v[82:83], v[76:77], v[86:87] op_sel:[0,1] op_sel_hi:[1,0]
	s_nop 0
	v_pk_fma_f32 v[82:83], v[86:87], v[74:75], v[82:83] op_sel_hi:[1,0,1]
	s_nop 0
	v_pk_mul_f32 v[84:85], v[78:79], v[82:83] op_sel:[1,1] op_sel_hi:[0,1] neg_lo:[0,1]
	v_pk_fma_f32 v[78:79], v[78:79], v[82:83], v[84:85] op_sel_hi:[1,0,1]
	v_pk_mul_f32 v[84:85], v[76:77], v[82:83] op_sel:[0,1] op_sel_hi:[1,0]
	s_nop 0
	v_pk_fma_f32 v[82:83], v[82:83], v[74:75], v[84:85] op_sel_hi:[1,0,1]
	s_nop 0
	v_pk_mul_f32 v[84:85], v[80:81], v[82:83] op_sel:[1,1] op_sel_hi:[0,1] neg_lo:[0,1]
	v_pk_fma_f32 v[80:81], v[80:81], v[82:83], v[84:85] op_sel_hi:[1,0,1]
	ds_write2_b64 v0, v[78:79], v[80:81] offset0:26 offset1:27
	v_pk_mul_f32 v[78:79], v[76:77], v[82:83] op_sel:[0,1] op_sel_hi:[1,0]
	s_nop 0
	v_pk_fma_f32 v[78:79], v[82:83], v[74:75], v[78:79] op_sel_hi:[1,0,1]
	s_nop 0
	v_pk_mul_f32 v[80:81], v[68:69], v[78:79] op_sel:[1,1] op_sel_hi:[0,1] neg_lo:[0,1]
	v_pk_fma_f32 v[68:69], v[68:69], v[78:79], v[80:81] op_sel_hi:[1,0,1]
	v_pk_mul_f32 v[80:81], v[76:77], v[78:79] op_sel:[0,1] op_sel_hi:[1,0]
	s_nop 0
	v_pk_fma_f32 v[78:79], v[78:79], v[74:75], v[80:81] op_sel_hi:[1,0,1]
	s_nop 0
	v_pk_mul_f32 v[80:81], v[72:73], v[78:79] op_sel:[1,1] op_sel_hi:[0,1] neg_lo:[0,1]
	v_pk_fma_f32 v[72:73], v[72:73], v[78:79], v[80:81] op_sel_hi:[1,0,1]
	ds_write2_b64 v0, v[68:69], v[72:73] offset0:28 offset1:29
	v_pk_mul_f32 v[68:69], v[76:77], v[78:79] op_sel:[0,1] op_sel_hi:[1,0]
	s_nop 0
	v_pk_fma_f32 v[68:69], v[78:79], v[74:75], v[68:69] op_sel_hi:[1,0,1]
	s_nop 0
	v_pk_mul_f32 v[72:73], v[66:67], v[68:69] op_sel:[1,1] op_sel_hi:[0,1] neg_lo:[0,1]
	v_pk_fma_f32 v[66:67], v[66:67], v[68:69], v[72:73] op_sel_hi:[1,0,1]
	v_pk_mul_f32 v[72:73], v[76:77], v[68:69] op_sel:[0,1] op_sel_hi:[1,0]
	s_nop 0
	v_pk_fma_f32 v[68:69], v[68:69], v[74:75], v[72:73] op_sel_hi:[1,0,1]
	s_nop 0
	v_pk_mul_f32 v[72:73], v[70:71], v[68:69] op_sel:[1,1] op_sel_hi:[0,1] neg_lo:[0,1]
	v_pk_fma_f32 v[68:69], v[70:71], v[68:69], v[72:73] op_sel_hi:[1,0,1]
	ds_write2_b64 v0, v[66:67], v[68:69] offset0:30 offset1:31
	s_waitcnt lgkmcnt(0)
	s_barrier
	v_mov_b32 v0, 0
	s_nop 0
	v_add_u32_e32 v71, v0, v170
	v_ashrrev_i32_e32 v105, 5, v71
	v_lshlrev_b32_e32 v0, 10, v105
	v_and_b32_e32 v140, 31, v71
	v_ashrrev_i32_e32 v0, 2, v0
	v_lshlrev_b32_e32 v67, 13, v105
	v_lshlrev_b32_e32 v68, 3, v140
	v_add_u32_e32 v0, 0, v0
	v_lshl_add_u32 v66, v105, 8, 0
	v_add3_u32 v0, v0, v67, v68
	v_add3_u32 v142, v66, v67, v68
	v_add_u32_e32 v143, 0x400, v0
	v_add_u32_e32 v144, 0x800, v0
	v_add_u32_e32 v145, 0xc00, v0
	ds_read_b64 v[130:131], v142
	ds_read2_b64 v[66:69], v0 offset0:33 offset1:66
	ds_read2_b64 v[72:75], v0 offset0:99 offset1:132
	ds_read2_b64 v[76:79], v0 offset0:165 offset1:198
	ds_read2_b64 v[80:83], v143 offset0:103 offset1:136
	ds_read2_b64 v[84:87], v144 offset0:41 offset1:74
	ds_read2_b64 v[88:91], v144 offset0:107 offset1:140
	ds_read2_b64 v[92:95], v144 offset0:173 offset1:206
	ds_read2_b64 v[96:99], v145 offset0:111 offset1:144
	v_add_u32_e32 v146, 0x1000, v0
	ds_read2_b64 v[100:103], v146 offset0:49 offset1:82
	ds_read2_b64 v[106:109], v146 offset0:115 offset1:148
	ds_read2_b64 v[110:113], v146 offset0:181 offset1:214
	v_add_u32_e32 v147, 0x1400, v0
	ds_read2_b64 v[114:117], v147 offset0:119 offset1:152
	s_waitcnt lgkmcnt(4)
	v_pk_add_f32 v[134:135], v[130:131], v[98:99]
	v_pk_add_f32 v[98:99], v[130:131], v[98:99] neg_lo:[0,1] neg_hi:[0,1]
	s_waitcnt lgkmcnt(3)
	v_pk_add_f32 v[130:131], v[66:67], v[100:101]
	v_pk_add_f32 v[66:67], v[66:67], v[100:101] neg_lo:[0,1] neg_hi:[0,1]
	v_add_u32_e32 v70, 0x1800, v0
	v_pk_mul_f32 v[100:101], v[66:67], s[50:51]
	ds_read2_b64 v[118:121], v70 offset0:57 offset1:90
	ds_read2_b64 v[122:125], v70 offset0:123 offset1:156
	ds_read2_b64 v[126:129], v70 offset0:189 offset1:222
	ds_read_b64 v[132:133], v0 offset:8184
	v_pk_fma_f32 v[66:67], v[66:67], s[20:21], v[100:101] op_sel:[0,0,1] op_sel_hi:[1,0,0]
	v_pk_add_f32 v[100:101], v[68:69], v[102:103]
	v_pk_add_f32 v[68:69], v[68:69], v[102:103] neg_lo:[0,1] neg_hi:[0,1]
	v_mul_lo_u32 v105, v140, v105
	v_pk_mul_f32 v[102:103], v[68:69], s[14:15]
	v_cvt_f32_i32_e32 v105, v105
	v_pk_fma_f32 v[68:69], v[68:69], s[6:7], v[102:103] op_sel:[0,0,1] op_sel_hi:[1,0,0]
	s_waitcnt lgkmcnt(6)
	v_pk_add_f32 v[102:103], v[72:73], v[106:107]
	v_pk_add_f32 v[72:73], v[72:73], v[106:107] neg_lo:[0,1] neg_hi:[0,1]
	v_and_b32_e32 v71, 0xffffffe0, v71
	v_pk_mul_f32 v[106:107], v[72:73], s[52:53]
	v_cvt_f32_i32_e32 v71, v71
	v_pk_fma_f32 v[72:73], v[72:73], s[24:25], v[106:107] op_sel:[0,0,1] op_sel_hi:[1,0,0]
	v_pk_add_f32 v[106:107], v[74:75], v[108:109]
	v_pk_add_f32 v[74:75], v[74:75], v[108:109] neg_lo:[0,1] neg_hi:[0,1]
	v_mul_f32_e32 v71, 0x38800000, v71
	v_pk_mul_f32 v[108:109], v[74:75], s[10:11]
	s_nop 0
	v_pk_fma_f32 v[74:75], v[74:75], s[10:11], v[108:109] op_sel:[0,0,1] op_sel_hi:[1,0,0]
	s_waitcnt lgkmcnt(5)
	v_pk_add_f32 v[108:109], v[76:77], v[110:111]
	v_pk_add_f32 v[76:77], v[76:77], v[110:111] neg_lo:[0,1] neg_hi:[0,1]
	s_nop 0
	v_pk_mul_f32 v[110:111], v[76:77], s[24:25]
	s_nop 0
	v_pk_fma_f32 v[76:77], v[76:77], s[0:1], v[110:111] op_sel:[0,0,1] op_sel_hi:[1,0,0]
	v_pk_add_f32 v[110:111], v[78:79], v[112:113]
	v_pk_add_f32 v[78:79], v[78:79], v[112:113] neg_lo:[0,1] neg_hi:[0,1]
	s_nop 0
	v_pk_mul_f32 v[112:113], v[78:79], s[6:7]
	s_nop 0
	v_pk_fma_f32 v[78:79], v[78:79], s[14:15], v[112:113] op_sel:[0,0,1] op_sel_hi:[1,0,0]
	s_waitcnt lgkmcnt(4)
	v_pk_add_f32 v[112:113], v[80:81], v[114:115]
	v_pk_add_f32 v[80:81], v[80:81], v[114:115] neg_lo:[0,1] neg_hi:[0,1]
	s_nop 0
	v_pk_mul_f32 v[114:115], v[80:81], s[20:21]
	s_nop 0
	v_pk_fma_f32 v[80:81], v[80:81], s[48:49], v[114:115] op_sel:[0,0,1] op_sel_hi:[1,0,0]
	v_pk_add_f32 v[114:115], v[82:83], v[116:117]
	v_pk_add_f32 v[116:117], v[82:83], v[116:117] op_sel:[1,1] op_sel_hi:[0,0] neg_lo:[1,0] neg_hi:[0,1]
	s_mov_b64 s[48:49], -1
	s_waitcnt lgkmcnt(3)
	v_pk_add_f32 v[82:83], v[84:85], v[118:119]
	v_pk_add_f32 v[84:85], v[84:85], v[118:119] neg_lo:[0,1] neg_hi:[0,1]
	s_nop 0
	v_pk_mul_f32 v[118:119], v[84:85], s[20:21]
	s_nop 0
	v_pk_fma_f32 v[84:85], v[84:85], s[18:19], v[118:119] op_sel:[0,0,1] op_sel_hi:[1,0,0]
	v_pk_add_f32 v[118:119], v[86:87], v[120:121]
	v_pk_add_f32 v[86:87], v[86:87], v[120:121] neg_lo:[0,1] neg_hi:[0,1]
	s_nop 0
	v_pk_mul_f32 v[120:121], v[86:87], s[6:7]
	s_nop 0
	v_pk_fma_f32 v[86:87], v[86:87], s[4:5], v[120:121] op_sel:[0,0,1] op_sel_hi:[1,0,0]
	s_waitcnt lgkmcnt(2)
	v_pk_add_f32 v[120:121], v[88:89], v[122:123]
	v_pk_add_f32 v[88:89], v[88:89], v[122:123] neg_lo:[0,1] neg_hi:[0,1]
	s_nop 0
	v_pk_mul_f32 v[122:123], v[88:89], s[24:25]
	s_nop 0
	v_pk_fma_f32 v[88:89], v[88:89], s[22:23], v[122:123] op_sel:[0,0,1] op_sel_hi:[1,0,0]
	v_pk_add_f32 v[122:123], v[90:91], v[124:125]
	v_pk_add_f32 v[90:91], v[90:91], v[124:125] neg_lo:[0,1] neg_hi:[0,1]
	s_nop 0
	v_pk_mul_f32 v[124:125], v[90:91], s[10:11]
	s_nop 0
	v_pk_fma_f32 v[90:91], v[90:91], s[8:9], v[124:125] op_sel:[0,0,1] op_sel_hi:[1,0,0]
	s_waitcnt lgkmcnt(1)
	v_pk_add_f32 v[124:125], v[92:93], v[126:127]
	v_pk_add_f32 v[92:93], v[92:93], v[126:127] neg_lo:[0,1] neg_hi:[0,1]
	s_nop 0
	v_pk_mul_f32 v[126:127], v[92:93], s[52:53]
	s_nop 0
	v_pk_fma_f32 v[92:93], v[92:93], s[26:27], v[126:127] op_sel:[0,0,1] op_sel_hi:[1,0,0]
	v_pk_add_f32 v[126:127], v[94:95], v[128:129]
	v_pk_add_f32 v[94:95], v[94:95], v[128:129] neg_lo:[0,1] neg_hi:[0,1]
	s_nop 0
	v_pk_mul_f32 v[128:129], v[94:95], s[14:15]
	s_nop 0
	v_pk_fma_f32 v[94:95], v[94:95], s[12:13], v[128:129] op_sel:[0,0,1] op_sel_hi:[1,0,0]
	s_waitcnt lgkmcnt(0)
	v_pk_add_f32 v[128:129], v[96:97], v[132:133]
	v_pk_add_f32 v[96:97], v[96:97], v[132:133] neg_lo:[0,1] neg_hi:[0,1]
	s_nop 0
	v_pk_mul_f32 v[132:133], v[96:97], s[50:51]
	s_nop 0
	v_pk_fma_f32 v[96:97], v[96:97], s[34:35], v[132:133] op_sel:[0,0,1] op_sel_hi:[1,0,0]
	v_pk_add_f32 v[132:133], v[134:135], v[114:115]
	v_pk_add_f32 v[114:115], v[134:135], v[114:115] neg_lo:[0,1] neg_hi:[0,1]
	v_pk_add_f32 v[134:135], v[130:131], v[82:83]
	v_pk_add_f32 v[82:83], v[130:131], v[82:83] neg_lo:[0,1] neg_hi:[0,1]
	s_nop 0
	v_pk_mul_f32 v[130:131], v[82:83], s[14:15]
	s_nop 0
	v_pk_fma_f32 v[82:83], v[82:83], s[6:7], v[130:131] op_sel:[0,0,1] op_sel_hi:[1,0,0]
	v_pk_add_f32 v[130:131], v[100:101], v[118:119]
	v_pk_add_f32 v[100:101], v[100:101], v[118:119] neg_lo:[0,1] neg_hi:[0,1]
	s_nop 0
	v_pk_mul_f32 v[118:119], v[100:101], s[10:11]
	s_nop 0
	v_pk_fma_f32 v[100:101], v[100:101], s[10:11], v[118:119] op_sel:[0,0,1] op_sel_hi:[1,0,0]
	v_pk_add_f32 v[118:119], v[102:103], v[120:121]
	v_pk_add_f32 v[102:103], v[102:103], v[120:121] neg_lo:[0,1] neg_hi:[0,1]
	s_nop 0
	v_pk_mul_f32 v[120:121], v[102:103], s[6:7]
	s_nop 0
	v_pk_fma_f32 v[102:103], v[102:103], s[14:15], v[120:121] op_sel:[0,0,1] op_sel_hi:[1,0,0]
	v_pk_add_f32 v[120:121], v[106:107], v[122:123]
	v_pk_add_f32 v[122:123], v[106:107], v[122:123] op_sel:[1,1] op_sel_hi:[0,0] neg_lo:[1,0] neg_hi:[0,1]
	s_nop 0
	v_pk_add_f32 v[106:107], v[108:109], v[124:125]
	v_pk_add_f32 v[108:109], v[108:109], v[124:125] neg_lo:[0,1] neg_hi:[0,1]
	s_nop 0
	v_pk_mul_f32 v[124:125], v[108:109], s[6:7]
	s_nop 0
	v_pk_fma_f32 v[108:109], v[108:109], s[4:5], v[124:125] op_sel:[0,0,1] op_sel_hi:[1,0,0]
	v_pk_add_f32 v[124:125], v[110:111], v[126:127]
	v_pk_add_f32 v[110:111], v[110:111], v[126:127] neg_lo:[0,1] neg_hi:[0,1]
	s_nop 0
	v_pk_mul_f32 v[126:127], v[110:111], s[10:11]
	s_nop 0
	v_pk_fma_f32 v[110:111], v[110:111], s[8:9], v[126:127] op_sel:[0,0,1] op_sel_hi:[1,0,0]
	v_pk_add_f32 v[126:127], v[112:113], v[128:129]
	v_pk_add_f32 v[112:113], v[112:113], v[128:129] neg_lo:[0,1] neg_hi:[0,1]
	s_nop 0
	v_pk_mul_f32 v[128:129], v[112:113], s[14:15]
	s_nop 0
	v_pk_fma_f32 v[112:113], v[112:113], s[12:13], v[128:129] op_sel:[0,0,1] op_sel_hi:[1,0,0]
	v_pk_add_f32 v[128:129], v[98:99], v[116:117]
	v_pk_add_f32 v[98:99], v[98:99], v[116:117] neg_lo:[0,1] neg_hi:[0,1]
	v_pk_add_f32 v[116:117], v[66:67], v[84:85]
	v_pk_add_f32 v[66:67], v[66:67], v[84:85] neg_lo:[0,1] neg_hi:[0,1]
	s_nop 0
	v_pk_mul_f32 v[84:85], v[66:67], s[14:15]
	s_nop 0
	v_pk_fma_f32 v[66:67], v[66:67], s[6:7], v[84:85] op_sel:[0,0,1] op_sel_hi:[1,0,0]
	v_pk_add_f32 v[84:85], v[68:69], v[86:87]
	v_pk_add_f32 v[68:69], v[68:69], v[86:87] neg_lo:[0,1] neg_hi:[0,1]
	s_nop 0
	v_pk_mul_f32 v[86:87], v[68:69], s[10:11]
	s_nop 0
	v_pk_fma_f32 v[68:69], v[68:69], s[10:11], v[86:87] op_sel:[0,0,1] op_sel_hi:[1,0,0]
	v_pk_add_f32 v[86:87], v[72:73], v[88:89]
	v_pk_add_f32 v[72:73], v[72:73], v[88:89] neg_lo:[0,1] neg_hi:[0,1]
	s_nop 0
	v_pk_mul_f32 v[88:89], v[72:73], s[6:7]
	s_nop 0
	v_pk_fma_f32 v[72:73], v[72:73], s[14:15], v[88:89] op_sel:[0,0,1] op_sel_hi:[1,0,0]
	v_pk_add_f32 v[88:89], v[74:75], v[90:91]
	v_pk_add_f32 v[90:91], v[74:75], v[90:91] op_sel:[1,1] op_sel_hi:[0,0] neg_lo:[1,0] neg_hi:[0,1]
	s_nop 0
	v_pk_add_f32 v[74:75], v[76:77], v[92:93]
	v_pk_add_f32 v[76:77], v[76:77], v[92:93] neg_lo:[0,1] neg_hi:[0,1]
	s_nop 0
	v_pk_mul_f32 v[92:93], v[76:77], s[6:7]
	s_nop 0
	v_pk_fma_f32 v[76:77], v[76:77], s[4:5], v[92:93] op_sel:[0,0,1] op_sel_hi:[1,0,0]
	v_pk_add_f32 v[92:93], v[78:79], v[94:95]
	v_pk_add_f32 v[78:79], v[78:79], v[94:95] neg_lo:[0,1] neg_hi:[0,1]
	s_mov_b32 s5, 0
	v_pk_mul_f32 v[94:95], v[78:79], s[10:11]
	s_nop 0
	v_pk_fma_f32 v[78:79], v[78:79], s[8:9], v[94:95] op_sel:[0,0,1] op_sel_hi:[1,0,0]
	v_pk_add_f32 v[94:95], v[80:81], v[96:97]
	v_pk_add_f32 v[80:81], v[80:81], v[96:97] neg_lo:[0,1] neg_hi:[0,1]
	s_nop 0
	v_pk_mul_f32 v[96:97], v[80:81], s[14:15]
	s_nop 0
	v_pk_fma_f32 v[80:81], v[80:81], s[12:13], v[96:97] op_sel:[0,0,1] op_sel_hi:[1,0,0]
	v_pk_add_f32 v[96:97], v[132:133], v[120:121]
	v_pk_add_f32 v[120:121], v[132:133], v[120:121] neg_lo:[0,1] neg_hi:[0,1]
	v_pk_add_f32 v[132:133], v[134:135], v[106:107]
	v_pk_add_f32 v[106:107], v[134:135], v[106:107] neg_lo:[0,1] neg_hi:[0,1]
	s_nop 0
	v_pk_mul_f32 v[134:135], v[106:107], s[10:11]
	s_nop 0
	v_pk_fma_f32 v[106:107], v[106:107], s[10:11], v[134:135] op_sel:[0,0,1] op_sel_hi:[1,0,0]
	v_pk_add_f32 v[134:135], v[130:131], v[124:125]
	v_pk_add_f32 v[130:131], v[130:131], v[124:125] op_sel:[1,1] op_sel_hi:[0,0] neg_lo:[1,0] neg_hi:[0,1]
	s_nop 0
	v_pk_add_f32 v[124:125], v[118:119], v[126:127]
	v_pk_add_f32 v[118:119], v[118:119], v[126:127] neg_lo:[0,1] neg_hi:[0,1]
	s_nop 0
	v_pk_mul_f32 v[126:127], v[118:119], s[10:11]
	s_nop 0
	v_pk_fma_f32 v[118:119], v[118:119], s[8:9], v[126:127] op_sel:[0,0,1] op_sel_hi:[1,0,0]
	v_pk_add_f32 v[126:127], v[114:115], v[122:123]
	v_pk_add_f32 v[114:115], v[114:115], v[122:123] neg_lo:[0,1] neg_hi:[0,1]
	v_pk_add_f32 v[122:123], v[82:83], v[108:109]
	v_pk_add_f32 v[82:83], v[82:83], v[108:109] neg_lo:[0,1] neg_hi:[0,1]
	s_nop 0
	v_pk_mul_f32 v[108:109], v[82:83], s[10:11]
	s_nop 0
	v_pk_fma_f32 v[82:83], v[82:83], s[10:11], v[108:109] op_sel:[0,0,1] op_sel_hi:[1,0,0]
	v_pk_add_f32 v[108:109], v[100:101], v[110:111]
	v_pk_add_f32 v[110:111], v[100:101], v[110:111] op_sel:[1,1] op_sel_hi:[0,0] neg_lo:[1,0] neg_hi:[0,1]
	s_nop 0
	v_pk_add_f32 v[100:101], v[102:103], v[112:113]
	v_pk_add_f32 v[102:103], v[102:103], v[112:113] neg_lo:[0,1] neg_hi:[0,1]
	s_nop 0
	v_pk_mul_f32 v[112:113], v[102:103], s[10:11]
	s_nop 0
	v_pk_fma_f32 v[102:103], v[102:103], s[8:9], v[112:113] op_sel:[0,0,1] op_sel_hi:[1,0,0]
	v_pk_add_f32 v[112:113], v[128:129], v[88:89]
	v_pk_add_f32 v[88:89], v[128:129], v[88:89] neg_lo:[0,1] neg_hi:[0,1]
	v_pk_add_f32 v[128:129], v[116:117], v[74:75]
	v_pk_add_f32 v[74:75], v[116:117], v[74:75] neg_lo:[0,1] neg_hi:[0,1]
	s_nop 0
	v_pk_mul_f32 v[116:117], v[74:75], s[10:11]
	s_nop 0
	v_pk_fma_f32 v[74:75], v[74:75], s[10:11], v[116:117] op_sel:[0,0,1] op_sel_hi:[1,0,0]
	v_pk_add_f32 v[116:117], v[84:85], v[92:93]
	v_pk_add_f32 v[92:93], v[84:85], v[92:93] op_sel:[1,1] op_sel_hi:[0,0] neg_lo:[1,0] neg_hi:[0,1]
	s_nop 0
	v_pk_add_f32 v[84:85], v[86:87], v[94:95]
	v_pk_add_f32 v[86:87], v[86:87], v[94:95] neg_lo:[0,1] neg_hi:[0,1]
	s_nop 0
	v_pk_mul_f32 v[94:95], v[86:87], s[10:11]
	s_nop 0
	v_pk_fma_f32 v[86:87], v[86:87], s[8:9], v[94:95] op_sel:[0,0,1] op_sel_hi:[1,0,0]
	v_pk_add_f32 v[94:95], v[98:99], v[90:91]
	v_pk_add_f32 v[90:91], v[98:99], v[90:91] neg_lo:[0,1] neg_hi:[0,1]
	v_pk_add_f32 v[98:99], v[66:67], v[76:77]
	v_pk_add_f32 v[66:67], v[66:67], v[76:77] neg_lo:[0,1] neg_hi:[0,1]
	s_nop 0
	v_pk_mul_f32 v[76:77], v[66:67], s[10:11]
	s_nop 0
	v_pk_fma_f32 v[66:67], v[66:67], s[10:11], v[76:77] op_sel:[0,0,1] op_sel_hi:[1,0,0]
	v_pk_add_f32 v[76:77], v[68:69], v[78:79]
	v_pk_add_f32 v[78:79], v[68:69], v[78:79] op_sel:[1,1] op_sel_hi:[0,0] neg_lo:[1,0] neg_hi:[0,1]
	s_nop 0
	v_pk_add_f32 v[68:69], v[72:73], v[80:81]
	v_pk_add_f32 v[72:73], v[72:73], v[80:81] neg_lo:[0,1] neg_hi:[0,1]
	v_pk_add_f32 v[136:137], v[90:91], v[78:79]
	v_pk_mul_f32 v[80:81], v[72:73], s[10:11]
	v_pk_add_f32 v[78:79], v[90:91], v[78:79] neg_lo:[0,1] neg_hi:[0,1]
	v_pk_fma_f32 v[72:73], v[72:73], s[8:9], v[80:81] op_sel:[0,0,1] op_sel_hi:[1,0,0]
	v_pk_add_f32 v[80:81], v[96:97], v[134:135]
	v_pk_add_f32 v[96:97], v[96:97], v[134:135] neg_lo:[0,1] neg_hi:[0,1]
	v_pk_add_f32 v[134:135], v[132:133], v[124:125]
	v_pk_add_f32 v[132:133], v[132:133], v[124:125] op_sel:[1,1] op_sel_hi:[0,0] neg_lo:[1,0] neg_hi:[0,1]
	v_pk_add_f32 v[90:91], v[66:67], v[72:73]
	v_pk_add_f32 v[124:125], v[120:121], v[130:131]
	v_pk_add_f32 v[120:121], v[120:121], v[130:131] neg_lo:[0,1] neg_hi:[0,1]
	v_pk_add_f32 v[130:131], v[106:107], v[118:119]
	v_pk_add_f32 v[118:119], v[106:107], v[118:119] op_sel:[1,1] op_sel_hi:[0,0] neg_lo:[1,0] neg_hi:[0,1]
	v_pk_add_f32 v[72:73], v[66:67], v[72:73] op_sel:[1,1] op_sel_hi:[0,0] neg_lo:[1,0] neg_hi:[0,1]
	v_pk_add_f32 v[106:107], v[126:127], v[108:109]
	v_pk_add_f32 v[108:109], v[126:127], v[108:109] neg_lo:[0,1] neg_hi:[0,1]
	v_pk_add_f32 v[126:127], v[122:123], v[100:101]
	v_pk_add_f32 v[122:123], v[122:123], v[100:101] op_sel:[1,1] op_sel_hi:[0,0] neg_lo:[1,0] neg_hi:[0,1]
	v_pk_add_f32 v[100:101], v[114:115], v[110:111]
	v_pk_add_f32 v[110:111], v[114:115], v[110:111] neg_lo:[0,1] neg_hi:[0,1]
	v_pk_add_f32 v[114:115], v[82:83], v[102:103]
	v_pk_add_f32 v[102:103], v[82:83], v[102:103] op_sel:[1,1] op_sel_hi:[0,0] neg_lo:[1,0] neg_hi:[0,1]
	v_pk_add_f32 v[82:83], v[112:113], v[116:117]
	v_pk_add_f32 v[112:113], v[112:113], v[116:117] neg_lo:[0,1] neg_hi:[0,1]
	v_pk_add_f32 v[116:117], v[128:129], v[84:85]
	v_pk_add_f32 v[128:129], v[128:129], v[84:85] op_sel:[1,1] op_sel_hi:[0,0] neg_lo:[1,0] neg_hi:[0,1]
	v_pk_add_f32 v[138:139], v[80:81], v[134:135]
	v_pk_add_f32 v[84:85], v[88:89], v[92:93]
	v_pk_add_f32 v[88:89], v[88:89], v[92:93] neg_lo:[0,1] neg_hi:[0,1]
	v_pk_add_f32 v[92:93], v[74:75], v[86:87]
	v_pk_add_f32 v[86:87], v[74:75], v[86:87] op_sel:[1,1] op_sel_hi:[0,0] neg_lo:[1,0] neg_hi:[0,1]
	v_pk_add_f32 v[80:81], v[80:81], v[134:135] neg_lo:[0,1] neg_hi:[0,1]
	v_pk_add_f32 v[74:75], v[94:95], v[76:77]
	v_pk_add_f32 v[76:77], v[94:95], v[76:77] neg_lo:[0,1] neg_hi:[0,1]
	v_pk_add_f32 v[94:95], v[98:99], v[68:69]
	v_pk_add_f32 v[98:99], v[98:99], v[68:69] op_sel:[1,1] op_sel_hi:[0,0] neg_lo:[1,0] neg_hi:[0,1]
	v_pk_add_f32 v[134:135], v[96:97], v[132:133]
	v_pk_add_f32 v[96:97], v[96:97], v[132:133] neg_lo:[0,1] neg_hi:[0,1]
	v_pk_add_f32 v[132:133], v[124:125], v[130:131]
	v_pk_add_f32 v[124:125], v[124:125], v[130:131] neg_lo:[0,1] neg_hi:[0,1]
	v_pk_add_f32 v[130:131], v[120:121], v[118:119]
	v_pk_add_f32 v[68:69], v[120:121], v[118:119] neg_lo:[0,1] neg_hi:[0,1]
	v_pk_add_f32 v[118:119], v[106:107], v[126:127]
	v_pk_add_f32 v[106:107], v[106:107], v[126:127] neg_lo:[0,1] neg_hi:[0,1]
	v_pk_add_f32 v[126:127], v[78:79], v[72:73]
	v_pk_add_f32 v[72:73], v[78:79], v[72:73] neg_lo:[0,1] neg_hi:[0,1]
	v_mul_f32_e32 v78, 0x38800000, v105
	v_sin_f32_e32 v79, v78
	v_cos_f32_e32 v78, v78
	v_pk_add_f32 v[120:121], v[108:109], v[122:123]
	v_pk_add_f32 v[108:109], v[108:109], v[122:123] neg_lo:[0,1] neg_hi:[0,1]
	v_pk_add_f32 v[122:123], v[100:101], v[114:115]
	v_pk_add_f32 v[100:101], v[100:101], v[114:115] neg_lo:[0,1] neg_hi:[0,1]
	v_pk_add_f32 v[114:115], v[110:111], v[102:103]
	v_pk_add_f32 v[66:67], v[110:111], v[102:103] neg_lo:[0,1] neg_hi:[0,1]
	v_pk_add_f32 v[102:103], v[82:83], v[116:117]
	v_pk_add_f32 v[82:83], v[82:83], v[116:117] neg_lo:[0,1] neg_hi:[0,1]
	v_pk_add_f32 v[116:117], v[84:85], v[92:93]
	v_pk_add_f32 v[84:85], v[84:85], v[92:93] neg_lo:[0,1] neg_hi:[0,1]
	v_pk_add_f32 v[92:93], v[88:89], v[86:87]
	v_pk_add_f32 v[86:87], v[88:89], v[86:87] neg_lo:[0,1] neg_hi:[0,1]
	v_pk_add_f32 v[88:89], v[74:75], v[94:95]
	v_pk_add_f32 v[74:75], v[74:75], v[94:95] neg_lo:[0,1] neg_hi:[0,1]
	v_pk_add_f32 v[94:95], v[76:77], v[98:99]
	v_pk_add_f32 v[76:77], v[76:77], v[98:99] neg_lo:[0,1] neg_hi:[0,1]
	v_pk_add_f32 v[98:99], v[136:137], v[90:91]
	v_pk_add_f32 v[90:91], v[136:137], v[90:91] neg_lo:[0,1] neg_hi:[0,1]
	v_sin_f32_e32 v136, v71
	v_pk_add_f32 v[110:111], v[112:113], v[128:129]
	v_pk_add_f32 v[112:113], v[112:113], v[128:129] neg_lo:[0,1] neg_hi:[0,1]
	v_cos_f32_e32 v128, v71
	v_pk_mul_f32 v[140:141], v[138:139], v[78:79] op_sel:[1,1] op_sel_hi:[0,1] neg_lo:[0,1]
	s_nop 0
	v_pk_fma_f32 v[138:139], v[138:139], v[78:79], v[140:141] op_sel_hi:[1,0,1]
	ds_write_b64 v142, v[138:139]
	v_pk_mul_f32 v[138:139], v[136:137], v[78:79] op_sel:[0,1] op_sel_hi:[0,0] neg_lo:[1,0]
	v_pk_fma_f32 v[78:79], v[78:79], v[128:129], v[138:139] op_sel_hi:[1,0,1]
	s_nop 0
	v_pk_mul_f32 v[138:139], v[102:103], v[78:79] op_sel:[1,1] op_sel_hi:[0,1] neg_lo:[0,1]
	s_nop 0
	v_pk_fma_f32 v[102:103], v[102:103], v[78:79], v[138:139] op_sel_hi:[1,0,1]
	v_pk_mul_f32 v[138:139], v[136:137], v[78:79] op_sel:[0,1] op_sel_hi:[0,0] neg_lo:[1,0]
	v_pk_fma_f32 v[78:79], v[78:79], v[128:129], v[138:139] op_sel_hi:[1,0,1]
	s_nop 0
	v_pk_mul_f32 v[138:139], v[118:119], v[78:79] op_sel:[1,1] op_sel_hi:[0,1] neg_lo:[0,1]
	s_nop 0
	v_pk_fma_f32 v[118:119], v[118:119], v[78:79], v[138:139] op_sel_hi:[1,0,1]
	ds_write2_b64 v0, v[102:103], v[118:119] offset0:33 offset1:66
	v_pk_mul_f32 v[102:103], v[136:137], v[78:79] op_sel:[0,1] op_sel_hi:[0,0] neg_lo:[1,0]
	v_pk_fma_f32 v[78:79], v[78:79], v[128:129], v[102:103] op_sel_hi:[1,0,1]
	s_nop 0
	v_pk_mul_f32 v[102:103], v[88:89], v[78:79] op_sel:[1,1] op_sel_hi:[0,1] neg_lo:[0,1]
	s_nop 0
	v_pk_fma_f32 v[88:89], v[88:89], v[78:79], v[102:103] op_sel_hi:[1,0,1]
	v_pk_mul_f32 v[102:103], v[136:137], v[78:79] op_sel:[0,1] op_sel_hi:[0,0] neg_lo:[1,0]
	v_pk_fma_f32 v[78:79], v[78:79], v[128:129], v[102:103] op_sel_hi:[1,0,1]
	s_nop 0
	v_pk_mul_f32 v[102:103], v[132:133], v[78:79] op_sel:[1,1] op_sel_hi:[0,1] neg_lo:[0,1]
	s_nop 0
	v_pk_fma_f32 v[102:103], v[132:133], v[78:79], v[102:103] op_sel_hi:[1,0,1]
	ds_write2_b64 v0, v[88:89], v[102:103] offset0:99 offset1:132
	v_pk_mul_f32 v[88:89], v[136:137], v[78:79] op_sel:[0,1] op_sel_hi:[0,0] neg_lo:[1,0]
	v_pk_fma_f32 v[78:79], v[78:79], v[128:129], v[88:89] op_sel_hi:[1,0,1]
	s_nop 0
	v_pk_mul_f32 v[88:89], v[116:117], v[78:79] op_sel:[1,1] op_sel_hi:[0,1] neg_lo:[0,1]
	v_pk_mul_f32 v[102:103], v[136:137], v[78:79] op_sel:[0,1] op_sel_hi:[0,0] neg_lo:[1,0]
	v_pk_fma_f32 v[88:89], v[116:117], v[78:79], v[88:89] op_sel_hi:[1,0,1]
	v_pk_fma_f32 v[78:79], v[78:79], v[128:129], v[102:103] op_sel_hi:[1,0,1]
	s_nop 0
	v_pk_mul_f32 v[102:103], v[122:123], v[78:79] op_sel:[1,1] op_sel_hi:[0,1] neg_lo:[0,1]
	s_nop 0
	v_pk_fma_f32 v[102:103], v[122:123], v[78:79], v[102:103] op_sel_hi:[1,0,1]
	ds_write2_b64 v0, v[88:89], v[102:103] offset0:165 offset1:198
	v_pk_mul_f32 v[88:89], v[136:137], v[78:79] op_sel:[0,1] op_sel_hi:[0,0] neg_lo:[1,0]
	v_pk_fma_f32 v[78:79], v[78:79], v[128:129], v[88:89] op_sel_hi:[1,0,1]
	s_nop 0
	v_pk_mul_f32 v[88:89], v[98:99], v[78:79] op_sel:[1,1] op_sel_hi:[0,1] neg_lo:[0,1]
	s_nop 0
	v_pk_fma_f32 v[88:89], v[98:99], v[78:79], v[88:89] op_sel_hi:[1,0,1]
	v_pk_mul_f32 v[98:99], v[136:137], v[78:79] op_sel:[0,1] op_sel_hi:[0,0] neg_lo:[1,0]
	v_pk_fma_f32 v[78:79], v[78:79], v[128:129], v[98:99] op_sel_hi:[1,0,1]
	s_nop 0
	v_pk_mul_f32 v[98:99], v[134:135], v[78:79] op_sel:[1,1] op_sel_hi:[0,1] neg_lo:[0,1]
	s_nop 0
	v_pk_fma_f32 v[98:99], v[134:135], v[78:79], v[98:99] op_sel_hi:[1,0,1]
	ds_write2_b64 v143, v[88:89], v[98:99] offset0:103 offset1:136
	v_pk_mul_f32 v[88:89], v[136:137], v[78:79] op_sel:[0,1] op_sel_hi:[0,0] neg_lo:[1,0]
	v_pk_fma_f32 v[78:79], v[78:79], v[128:129], v[88:89] op_sel_hi:[1,0,1]
	s_nop 0
	v_pk_mul_f32 v[88:89], v[110:111], v[78:79] op_sel:[1,1] op_sel_hi:[0,1] neg_lo:[0,1]
	v_pk_mul_f32 v[98:99], v[136:137], v[78:79] op_sel:[0,1] op_sel_hi:[0,0] neg_lo:[1,0]
	v_pk_fma_f32 v[88:89], v[110:111], v[78:79], v[88:89] op_sel_hi:[1,0,1]
	v_pk_fma_f32 v[78:79], v[78:79], v[128:129], v[98:99] op_sel_hi:[1,0,1]
	s_nop 0
	v_pk_mul_f32 v[98:99], v[120:121], v[78:79] op_sel:[1,1] op_sel_hi:[0,1] neg_lo:[0,1]
	s_nop 0
	v_pk_fma_f32 v[98:99], v[120:121], v[78:79], v[98:99] op_sel_hi:[1,0,1]
	ds_write2_b64 v144, v[88:89], v[98:99] offset0:41 offset1:74
	v_pk_mul_f32 v[88:89], v[136:137], v[78:79] op_sel:[0,1] op_sel_hi:[0,0] neg_lo:[1,0]
	v_pk_fma_f32 v[78:79], v[78:79], v[128:129], v[88:89] op_sel_hi:[1,0,1]
	s_nop 0
	v_pk_mul_f32 v[88:89], v[94:95], v[78:79] op_sel:[1,1] op_sel_hi:[0,1] neg_lo:[0,1]
	s_nop 0
	v_pk_fma_f32 v[88:89], v[94:95], v[78:79], v[88:89] op_sel_hi:[1,0,1]
	v_pk_mul_f32 v[94:95], v[136:137], v[78:79] op_sel:[0,1] op_sel_hi:[0,0] neg_lo:[1,0]
	v_pk_fma_f32 v[78:79], v[78:79], v[128:129], v[94:95] op_sel_hi:[1,0,1]
	s_nop 0
	v_pk_mul_f32 v[94:95], v[130:131], v[78:79] op_sel:[1,1] op_sel_hi:[0,1] neg_lo:[0,1]
	v_pk_fma_f32 v[94:95], v[130:131], v[78:79], v[94:95] op_sel_hi:[1,0,1]
	ds_write2_b64 v144, v[88:89], v[94:95] offset0:107 offset1:140
	v_pk_mul_f32 v[88:89], v[136:137], v[78:79] op_sel:[0,1] op_sel_hi:[0,0] neg_lo:[1,0]
	v_pk_fma_f32 v[78:79], v[78:79], v[128:129], v[88:89] op_sel_hi:[1,0,1]
	s_nop 0
	v_pk_mul_f32 v[88:89], v[92:93], v[78:79] op_sel:[1,1] op_sel_hi:[0,1] neg_lo:[0,1]
	v_pk_fma_f32 v[88:89], v[92:93], v[78:79], v[88:89] op_sel_hi:[1,0,1]
	v_pk_mul_f32 v[92:93], v[136:137], v[78:79] op_sel:[0,1] op_sel_hi:[0,0] neg_lo:[1,0]
	v_pk_fma_f32 v[78:79], v[78:79], v[128:129], v[92:93] op_sel_hi:[1,0,1]
	s_nop 0
	v_pk_mul_f32 v[92:93], v[114:115], v[78:79] op_sel:[1,1] op_sel_hi:[0,1] neg_lo:[0,1]
	v_pk_fma_f32 v[92:93], v[114:115], v[78:79], v[92:93] op_sel_hi:[1,0,1]
	ds_write2_b64 v144, v[88:89], v[92:93] offset0:173 offset1:206
	v_pk_mul_f32 v[88:89], v[136:137], v[78:79] op_sel:[0,1] op_sel_hi:[0,0] neg_lo:[1,0]
	v_pk_fma_f32 v[78:79], v[78:79], v[128:129], v[88:89] op_sel_hi:[1,0,1]
	s_nop 0
	v_pk_mul_f32 v[88:89], v[126:127], v[78:79] op_sel:[1,1] op_sel_hi:[0,1] neg_lo:[0,1]
	v_pk_mul_f32 v[92:93], v[136:137], v[78:79] op_sel:[0,1] op_sel_hi:[0,0] neg_lo:[1,0]
	v_pk_fma_f32 v[88:89], v[126:127], v[78:79], v[88:89] op_sel_hi:[1,0,1]
	v_pk_fma_f32 v[78:79], v[78:79], v[128:129], v[92:93] op_sel_hi:[1,0,1]
	s_nop 0
	v_pk_mul_f32 v[92:93], v[80:81], v[78:79] op_sel:[1,1] op_sel_hi:[0,1] neg_lo:[0,1]
	v_pk_fma_f32 v[80:81], v[80:81], v[78:79], v[92:93] op_sel_hi:[1,0,1]
	ds_write2_b64 v145, v[88:89], v[80:81] offset0:111 offset1:144
	v_pk_mul_f32 v[80:81], v[136:137], v[78:79] op_sel:[0,1] op_sel_hi:[0,0] neg_lo:[1,0]
	v_pk_fma_f32 v[78:79], v[78:79], v[128:129], v[80:81] op_sel_hi:[1,0,1]
	s_nop 0
	v_pk_mul_f32 v[80:81], v[82:83], v[78:79] op_sel:[1,1] op_sel_hi:[0,1] neg_lo:[0,1]
	v_pk_fma_f32 v[80:81], v[82:83], v[78:79], v[80:81] op_sel_hi:[1,0,1]
	v_pk_mul_f32 v[82:83], v[136:137], v[78:79] op_sel:[0,1] op_sel_hi:[0,0] neg_lo:[1,0]
	v_pk_fma_f32 v[78:79], v[78:79], v[128:129], v[82:83] op_sel_hi:[1,0,1]
	s_nop 0
	v_pk_mul_f32 v[82:83], v[106:107], v[78:79] op_sel:[1,1] op_sel_hi:[0,1] neg_lo:[0,1]
	v_pk_fma_f32 v[82:83], v[106:107], v[78:79], v[82:83] op_sel_hi:[1,0,1]
	ds_write2_b64 v146, v[80:81], v[82:83] offset0:49 offset1:82
	v_pk_mul_f32 v[80:81], v[136:137], v[78:79] op_sel:[0,1] op_sel_hi:[0,0] neg_lo:[1,0]
	v_pk_fma_f32 v[78:79], v[78:79], v[128:129], v[80:81] op_sel_hi:[1,0,1]
	s_nop 0
	v_pk_mul_f32 v[80:81], v[74:75], v[78:79] op_sel:[1,1] op_sel_hi:[0,1] neg_lo:[0,1]
	v_pk_fma_f32 v[74:75], v[74:75], v[78:79], v[80:81] op_sel_hi:[1,0,1]
	v_pk_mul_f32 v[80:81], v[136:137], v[78:79] op_sel:[0,1] op_sel_hi:[0,0] neg_lo:[1,0]
	v_pk_fma_f32 v[78:79], v[78:79], v[128:129], v[80:81] op_sel_hi:[1,0,1]
	s_nop 0
	v_pk_mul_f32 v[80:81], v[124:125], v[78:79] op_sel:[1,1] op_sel_hi:[0,1] neg_lo:[0,1]
	v_pk_fma_f32 v[80:81], v[124:125], v[78:79], v[80:81] op_sel_hi:[1,0,1]
	ds_write2_b64 v146, v[74:75], v[80:81] offset0:115 offset1:148
	v_pk_mul_f32 v[74:75], v[136:137], v[78:79] op_sel:[0,1] op_sel_hi:[0,0] neg_lo:[1,0]
	v_pk_fma_f32 v[74:75], v[78:79], v[128:129], v[74:75] op_sel_hi:[1,0,1]
	s_nop 0
	v_pk_mul_f32 v[78:79], v[84:85], v[74:75] op_sel:[1,1] op_sel_hi:[0,1] neg_lo:[0,1]
	v_pk_mul_f32 v[80:81], v[136:137], v[74:75] op_sel:[0,1] op_sel_hi:[0,0] neg_lo:[1,0]
	v_pk_fma_f32 v[78:79], v[84:85], v[74:75], v[78:79] op_sel_hi:[1,0,1]
	v_pk_fma_f32 v[74:75], v[74:75], v[128:129], v[80:81] op_sel_hi:[1,0,1]
	s_nop 0
	v_pk_mul_f32 v[80:81], v[100:101], v[74:75] op_sel:[1,1] op_sel_hi:[0,1] neg_lo:[0,1]
	v_pk_fma_f32 v[80:81], v[100:101], v[74:75], v[80:81] op_sel_hi:[1,0,1]
	ds_write2_b64 v146, v[78:79], v[80:81] offset0:181 offset1:214
	v_pk_mul_f32 v[78:79], v[136:137], v[74:75] op_sel:[0,1] op_sel_hi:[0,0] neg_lo:[1,0]
	v_pk_fma_f32 v[74:75], v[74:75], v[128:129], v[78:79] op_sel_hi:[1,0,1]
	s_nop 0
	v_pk_mul_f32 v[78:79], v[90:91], v[74:75] op_sel:[1,1] op_sel_hi:[0,1] neg_lo:[0,1]
	v_pk_mul_f32 v[80:81], v[136:137], v[74:75] op_sel:[0,1] op_sel_hi:[0,0] neg_lo:[1,0]
	v_pk_fma_f32 v[78:79], v[90:91], v[74:75], v[78:79] op_sel_hi:[1,0,1]
	v_pk_fma_f32 v[74:75], v[74:75], v[128:129], v[80:81] op_sel_hi:[1,0,1]
	s_nop 0
	v_pk_mul_f32 v[80:81], v[96:97], v[74:75] op_sel:[1,1] op_sel_hi:[0,1] neg_lo:[0,1]
	v_pk_fma_f32 v[80:81], v[96:97], v[74:75], v[80:81] op_sel_hi:[1,0,1]
	ds_write2_b64 v147, v[78:79], v[80:81] offset0:119 offset1:152
	v_pk_mul_f32 v[78:79], v[136:137], v[74:75] op_sel:[0,1] op_sel_hi:[0,0] neg_lo:[1,0]
	v_pk_fma_f32 v[74:75], v[74:75], v[128:129], v[78:79] op_sel_hi:[1,0,1]
	s_nop 0
	v_pk_mul_f32 v[78:79], v[112:113], v[74:75] op_sel:[1,1] op_sel_hi:[0,1] neg_lo:[0,1]
	v_pk_mul_f32 v[80:81], v[136:137], v[74:75] op_sel:[0,1] op_sel_hi:[0,0] neg_lo:[1,0]
	v_pk_fma_f32 v[78:79], v[112:113], v[74:75], v[78:79] op_sel_hi:[1,0,1]
	v_pk_fma_f32 v[74:75], v[74:75], v[128:129], v[80:81] op_sel_hi:[1,0,1]
	s_nop 0
	v_pk_mul_f32 v[80:81], v[108:109], v[74:75] op_sel:[1,1] op_sel_hi:[0,1] neg_lo:[0,1]
	v_pk_fma_f32 v[80:81], v[108:109], v[74:75], v[80:81] op_sel_hi:[1,0,1]
	ds_write2_b64 v70, v[78:79], v[80:81] offset0:57 offset1:90
	v_pk_mul_f32 v[78:79], v[136:137], v[74:75] op_sel:[0,1] op_sel_hi:[0,0] neg_lo:[1,0]
	v_pk_fma_f32 v[74:75], v[74:75], v[128:129], v[78:79] op_sel_hi:[1,0,1]
	s_nop 0
	v_pk_mul_f32 v[78:79], v[76:77], v[74:75] op_sel:[1,1] op_sel_hi:[0,1] neg_lo:[0,1]
	v_pk_fma_f32 v[76:77], v[76:77], v[74:75], v[78:79] op_sel_hi:[1,0,1]
	v_pk_mul_f32 v[78:79], v[136:137], v[74:75] op_sel:[0,1] op_sel_hi:[0,0] neg_lo:[1,0]
	v_pk_fma_f32 v[74:75], v[74:75], v[128:129], v[78:79] op_sel_hi:[1,0,1]
	s_nop 0
	v_pk_mul_f32 v[78:79], v[68:69], v[74:75] op_sel:[1,1] op_sel_hi:[0,1] neg_lo:[0,1]
	v_pk_fma_f32 v[68:69], v[68:69], v[74:75], v[78:79] op_sel_hi:[1,0,1]
	ds_write2_b64 v70, v[76:77], v[68:69] offset0:123 offset1:156
	v_pk_mul_f32 v[68:69], v[136:137], v[74:75] op_sel:[0,1] op_sel_hi:[0,0] neg_lo:[1,0]
	v_pk_fma_f32 v[68:69], v[74:75], v[128:129], v[68:69] op_sel_hi:[1,0,1]
	s_nop 0
	v_pk_mul_f32 v[74:75], v[86:87], v[68:69] op_sel:[1,1] op_sel_hi:[0,1] neg_lo:[0,1]
	v_pk_mul_f32 v[76:77], v[136:137], v[68:69] op_sel:[0,1] op_sel_hi:[0,0] neg_lo:[1,0]
	v_pk_fma_f32 v[74:75], v[86:87], v[68:69], v[74:75] op_sel_hi:[1,0,1]
	v_pk_fma_f32 v[68:69], v[68:69], v[128:129], v[76:77] op_sel_hi:[1,0,1]
	s_nop 0
	v_pk_mul_f32 v[76:77], v[66:67], v[68:69] op_sel:[1,1] op_sel_hi:[0,1] neg_lo:[0,1]
	v_pk_fma_f32 v[66:67], v[66:67], v[68:69], v[76:77] op_sel_hi:[1,0,1]
	ds_write2_b64 v70, v[74:75], v[66:67] offset0:189 offset1:222
	v_pk_mul_f32 v[66:67], v[136:137], v[68:69] op_sel:[0,1] op_sel_hi:[0,0] neg_lo:[1,0]
	v_pk_fma_f32 v[66:67], v[68:69], v[128:129], v[66:67] op_sel_hi:[1,0,1]
	s_nop 0
	v_pk_mul_f32 v[68:69], v[72:73], v[66:67] op_sel:[1,1] op_sel_hi:[0,1] neg_lo:[0,1]
	v_pk_fma_f32 v[66:67], v[72:73], v[66:67], v[68:69] op_sel_hi:[1,0,1]
	ds_write_b64 v0, v[66:67] offset:8184
	s_waitcnt lgkmcnt(0)
	s_barrier
